# v31 + A-operand-stationary MFMA order in all GEMM 16x16x32 groups (A fixed for 4 consecutive MFMAs, B cycling) instead of B-pair order
# baseline (speedup 1.0000x reference)
; #define PG8_WAIT_V(n) asm volatile("s_waitcnt vmcnt(" #n ")" ::: "memory")
; #define PG8_BAR __builtin_amdgcn_s_barrier()
; template <class Epi, bool ALIGN_EPI, bool SPLITA>
; __device__ __forceinline__ void gemm_phase(LAS unsigned char* lds, const Gemm g, const StaticOrder& S, const Epi& E) {
;     ...
;         const bool has_next = S.next(ui + 1, nxt);
;         const char* nA = has_next ? baseA1(nxt) : cA;
;         const char* nB = has_next ? baseB(nxt) : cB;
;         const bool mirN = has_next ? mirrored(nxt) : mirC;
;         for (int t = 0; t < nt; t += 2) {
;             const bool last = (t == nt - 2);
;             if constexpr (Epi::MIDK) { if (t == g.ksplit) E.mid(acc, cur, wr, wc, fr, fq); }
;             const char *a1, *a2;
;             if constexpr (SPLITA) {
;                 a1 = (t + 1 < g.ksplit) ? cA + (size_t)(t + 1) * kstep : cA2 + (size_t)(t + 1 - g.ksplit) * 2048;
;                 a2 = last ? nA : ((t + 2 < g.ksplit) ? cA + (size_t)(t + 2) * kstep : cA2 + (size_t)(t + 2 - g.ksplit) * 2048);
;             } else { a1 = cA + kofs(t + 1); a2 = last ? nA : cA + kofs(t + 2); }
;             const char* b2 = last ? nB : cB + (size_t)(t + 2) * kstepB;
;             const bool s2a = SPLITA && (t + 1 >= g.ksplit), s2b = SPLITA && !last && (t + 2 >= g.ksplit);
;             const char* a3 = a2 + ((Epi::KSUB || s2b) ? (size_t)2048 : kstep); const char* b3 = b2 + kstepB;
;             const bool m1 = SPLITA && mirC && (t + 1 < g.ksplit), m2 = SPLITA && (last ? mirN : (mirC && (t + 2 < g.ksplit)));
;             const unsigned vo1[2] = {s2a ? voffA2[0] : m1 ? voffAm[0] : voffA[0], s2a ? voffA2[1] : m1 ? voffAm[1] : voffA[1]}, vo2[2] = {s2b ? voffA2[0] : m2 ? voffAm[0] : voffA[0], s2b ? voffA2[1] : m2 ? voffAm[1] : voffA[1]};
;             const char* a1h = m1 ? a1 - hstepA : a1 + hstepA; const char* a2h = m2 ? a2 - hstepA : a2 + hstepA;
;             PG8_LDB(B0, 0, 0); PG8_LDB(B1, 0, 1); PG8_SCHED; PG8_LDA(At, 0, 0); PG8_STAGE(PG8_SA(1, 1), a1h, vo1);
;             PG8_WAIT_V(8); PG8_WAIT_L(0); PG8_BAR; PG8_MMA(0, 0, At, B0); PG8_MMA(0, 1, At, B1); PG8_BAR; PG8_SCHED;
;             PG8_LDA(At, 0, 1); PG8_STAGE(PG8_SB(0, 0), b2, voffB); PG8_STAGE(PG8_SB(0, 1), b2 + hstepB, voffB); PG8_STAGE(PG8_SA(0, 0), a2, vo2);
;             PG8_WAIT_V(8); PG8_WAIT_L(0); PG8_BAR; PG8_MMA(1, 0, At, B0); PG8_MMA(1, 1, At, B1); PG8_BAR; PG8_SCHED;
.LBB0_228:
	s_ashr_i32 s27, s26, 31
	s_lshl_b64 s[38:39], s[26:27], 19
	s_add_u32 s38, s34, s38
	s_addc_u32 s39, s35, s39
	s_and_b64 s[40:41], s[2:3], exec
	s_cselect_b32 s27, s39, s43
	s_cselect_b32 s33, s38, s42
	s_ashr_i32 s29, s28, 31
	s_lshl_b64 s[40:41], s[28:29], 19
	s_add_u32 s40, s72, s40
	s_addc_u32 s41, s73, s41
	s_and_b64 s[46:47], s[2:3], exec
	s_cselect_b32 s29, s41, s45
	s_cselect_b32 s60, s40, s44
	s_add_u32 s42, s42, 0x40080
	s_addc_u32 s43, s43, 0
	s_add_u32 s61, s44, 0x100
	s_addc_u32 vcc_lo, s45, 0
	s_mov_b32 vcc_hi, -2
	ds_read_b128 v[130:133], v191
	ds_read_b128 v[134:137], v191 offset:1024
	ds_read_b128 v[138:141], v191 offset:2048
	ds_read_b128 v[142:145], v191 offset:3072
	ds_read_b128 v[146:149], v192
	ds_read_b128 v[150:153], v192 offset:1024
	ds_read_b128 v[154:157], v192 offset:2048
	ds_read_b128 v[158:161], v192 offset:3072
	s_add_u32 s0, s42, 0xfffc0080
	s_addc_u32 s1, s43, -1
	s_cmp_eq_u32 vcc_hi, 12
	s_cselect_b32 s47, s27, s1
	s_cselect_b32 s46, s33, s0
	s_cselect_b32 s45, s29, vcc_lo
	s_cselect_b32 s44, s60, s61
	s_add_i32 m0, s87, 0xc000
	ds_read_b128 v[198:201], v193
	ds_read_b128 v[202:205], v193 offset:1024
	ds_read_b128 v[206:209], v193 offset:2048
	ds_read_b128 v[210:213], v193 offset:3072
	ds_read_b128 v[214:217], v193 offset:4096
	ds_read_b128 v[218:221], v193 offset:5120
	ds_read_b128 v[222:225], v193 offset:6144
	ds_read_b128 v[226:229], v193 offset:7168
	global_load_lds_dwordx4 v182, s[42:43]
	s_add_i32 m0, s87, 0xe000
	s_nop 0
	global_load_lds_dwordx4 v184, s[42:43]
	s_waitcnt vmcnt(8)
	s_waitcnt lgkmcnt(0)
	s_barrier
	s_setprio 1
	s_waitcnt lgkmcnt(0)
	v_mfma_f32_16x16x32_bf16 v[126:129], v[130:133], v[198:201], 0
	v_mfma_f32_16x16x32_bf16 v[110:113], v[130:133], v[206:209], 0
	v_mfma_f32_16x16x32_bf16 v[94:97], v[130:133], v[214:217], 0
	v_mfma_f32_16x16x32_bf16 v[78:81], v[130:133], v[222:225], 0
	v_mfma_f32_16x16x32_bf16 v[122:125], v[138:141], v[198:201], 0
	v_mfma_f32_16x16x32_bf16 v[106:109], v[138:141], v[206:209], 0
	v_mfma_f32_16x16x32_bf16 v[90:93], v[138:141], v[214:217], 0
	v_mfma_f32_16x16x32_bf16 v[74:77], v[138:141], v[222:225], 0
	v_mfma_f32_16x16x32_bf16 v[126:129], v[134:137], v[202:205], v[126:129]
	v_mfma_f32_16x16x32_bf16 v[110:113], v[134:137], v[210:213], v[110:113]
	v_mfma_f32_16x16x32_bf16 v[94:97], v[134:137], v[218:221], v[94:97]
	v_mfma_f32_16x16x32_bf16 v[78:81], v[134:137], v[226:229], v[78:81]
	v_mfma_f32_16x16x32_bf16 v[122:125], v[142:145], v[202:205], v[122:125]
	v_mfma_f32_16x16x32_bf16 v[106:109], v[142:145], v[210:213], v[106:109]
	v_mfma_f32_16x16x32_bf16 v[90:93], v[142:145], v[218:221], v[90:93]
	v_mfma_f32_16x16x32_bf16 v[74:77], v[142:145], v[226:229], v[74:77]
	s_setprio 0
	s_setprio 1
	v_mfma_f32_16x16x32_bf16 v[118:121], v[146:149], v[198:201], 0
	v_mfma_f32_16x16x32_bf16 v[102:105], v[146:149], v[206:209], 0
	v_mfma_f32_16x16x32_bf16 v[86:89], v[146:149], v[214:217], 0
	v_mfma_f32_16x16x32_bf16 v[70:73], v[146:149], v[222:225], 0
	v_mfma_f32_16x16x32_bf16 v[114:117], v[154:157], v[198:201], 0
	v_mfma_f32_16x16x32_bf16 v[98:101], v[154:157], v[206:209], 0
	v_mfma_f32_16x16x32_bf16 v[82:85], v[154:157], v[214:217], 0
	v_mfma_f32_16x16x32_bf16 v[66:69], v[154:157], v[222:225], 0
	v_mfma_f32_16x16x32_bf16 v[118:121], v[150:153], v[202:205], v[118:121]
	v_mfma_f32_16x16x32_bf16 v[102:105], v[150:153], v[210:213], v[102:105]
	v_mfma_f32_16x16x32_bf16 v[86:89], v[150:153], v[218:221], v[86:89]
	v_mfma_f32_16x16x32_bf16 v[70:73], v[150:153], v[226:229], v[70:73]
	v_mfma_f32_16x16x32_bf16 v[114:117], v[158:161], v[202:205], v[114:117]
	v_mfma_f32_16x16x32_bf16 v[98:101], v[158:161], v[210:213], v[98:101]
	v_mfma_f32_16x16x32_bf16 v[82:85], v[158:161], v[218:221], v[82:85]
	v_mfma_f32_16x16x32_bf16 v[66:69], v[158:161], v[226:229], v[66:69]
	s_setprio 0
	s_barrier
	s_add_u32 s98, s44, s8
	s_addc_u32 s99, s45, s9
	s_add_u32 s100, s46, s8
	s_addc_u32 s101, s47, s9
	s_add_i32 s0, s97, s80
	s_mov_b32 m0, s0
	ds_read_b128 v[198:201], v193 offset:16384
	ds_read_b128 v[202:205], v193 offset:17408
	ds_read_b128 v[206:209], v193 offset:18432
	ds_read_b128 v[210:213], v193 offset:19456
	ds_read_b128 v[214:217], v193 offset:20480
	ds_read_b128 v[218:221], v193 offset:21504
	ds_read_b128 v[222:225], v193 offset:22528
	ds_read_b128 v[226:229], v193 offset:23552
	global_load_lds_dwordx4 v168, s[44:45]
	s_add_i32 m0, s0, 0x2000
	s_add_u32 s0, s44, 0x40000
	s_addc_u32 s1, s45, 0
	s_add_i32 s78, s64, s80
	global_load_lds_dwordx4 v164, s[44:45]
	s_mov_b32 m0, s78
	s_nop 0
	global_load_lds_dwordx4 v168, s[0:1]
	s_add_i32 m0, s78, 0x2000
	s_nop 0
	global_load_lds_dwordx4 v164, s[0:1]
	s_mov_b32 m0, s87
	s_nop 0
	global_load_lds_dwordx4 v170, s[46:47]
	s_mov_b32 m0, s88
	s_nop 0
	global_load_lds_dwordx4 v166, s[46:47]
	s_waitcnt vmcnt(8)
	s_waitcnt lgkmcnt(0)
	s_barrier
; #define PG8_STAGE(bufoff, gbase, voff) do { _Pragma("unroll") for (int _i = 0; _i < 2; ++_i) \
;         __builtin_amdgcn_global_load_lds((const unsigned*)((const char*)(gbase) + (voff)[_i]), (LAS unsigned*)(lds + (bufoff) + ldsw + _i * 8192), 16, 0, 0); } while (0)
; #define PG8_LDA(dst, b, h) do { _Pragma("unroll") for (int m = 0; m < 4; ++m) _Pragma("unroll") for (int k = 0; k < 2; ++k) dst[m][k] = *(const LAS bf16x8*)(lds + PG8_SA(b, h) + aoff + m * 2048 + k * 1024); } while (0)
; #define PG8_LDB(dst, b, h) do { _Pragma("unroll") for (int n = 0; n < 2; ++n) _Pragma("unroll") for (int k = 0; k < 2; ++k) dst[n][k] = *(const LAS bf16x8*)(lds + PG8_SB(b, h) + boff + n * 2048 + k * 1024); } while (0)
; #define PG8_MMA(ai, bj, At, Bt) do { __builtin_amdgcn_s_setprio(1); _Pragma("unroll") for (int m = 0; m < 4; ++m) _Pragma("unroll") for (int n = 0; n < 2; ++n) _Pragma("unroll") for (int k = 0; k < 2; ++k) \
;         acc[ai][bj][m][n] = __builtin_amdgcn_mfma_f32_16x16x32_bf16(Bt[n][k], At[m][k], acc[ai][bj][m][n], 0, 0, 0); __builtin_amdgcn_s_setprio(0); } while (0)
; #define PG8_WAIT_V(n) asm volatile("s_waitcnt vmcnt(" #n ")" ::: "memory")
; #define PG8_WAIT_L(n) asm volatile("s_waitcnt lgkmcnt(" #n ")" ::: "memory")
; #define PG8_BAR __builtin_amdgcn_s_barrier()
; #define PG8_SCHED __builtin_amdgcn_sched_barrier(0)
; template <class Epi, bool ALIGN_EPI, bool SPLITA>
; __device__ __forceinline__ void gemm_phase(LAS unsigned char* lds, const Gemm g, const StaticOrder& S, const Epi& E) {
;     ...
;             PG8_LDB(B0, 0, 0); PG8_LDB(B1, 0, 1); PG8_SCHED; PG8_LDA(At, 0, 0); PG8_STAGE(PG8_SA(1, 1), a1h, vo1);
;             PG8_WAIT_V(8); PG8_WAIT_L(0); PG8_BAR; PG8_MMA(0, 0, At, B0); PG8_MMA(0, 1, At, B1); PG8_BAR; PG8_SCHED;
;             PG8_LDA(At, 0, 1); PG8_STAGE(PG8_SB(0, 0), b2, voffB); PG8_STAGE(PG8_SB(0, 1), b2 + hstepB, voffB); PG8_STAGE(PG8_SA(0, 0), a2, vo2);
;             PG8_WAIT_V(8); PG8_WAIT_L(0); PG8_BAR; PG8_MMA(1, 0, At, B0); PG8_MMA(1, 1, At, B1); PG8_BAR; PG8_SCHED;
;             PG8_LDB(B0, 1, 0); PG8_LDB(B1, 1, 1); PG8_SCHED; PG8_LDA(At, 1, 0); PG8_STAGE(PG8_SA(0, 1), a2h, vo2);
;             PG8_WAIT_V(8); PG8_WAIT_L(0); PG8_BAR; PG8_MMA(0, 0, At, B0); PG8_MMA(0, 1, At, B1); PG8_BAR; PG8_SCHED;
	s_setprio 1
	s_waitcnt lgkmcnt(0)
	v_mfma_f32_16x16x32_bf16 v[62:65], v[130:133], v[198:201], 0
	v_mfma_f32_16x16x32_bf16 v[38:41], v[130:133], v[206:209], 0
	v_mfma_f32_16x16x32_bf16 v[22:25], v[130:133], v[214:217], 0
	v_mfma_f32_16x16x32_bf16 v[6:9], v[130:133], v[222:225], 0
	v_mfma_f32_16x16x32_bf16 v[58:61], v[138:141], v[198:201], 0
	v_mfma_f32_16x16x32_bf16 v[34:37], v[138:141], v[206:209], 0
	v_mfma_f32_16x16x32_bf16 v[18:21], v[138:141], v[214:217], 0
	v_mfma_f32_16x16x32_bf16 v[2:5], v[138:141], v[222:225], 0
	v_mfma_f32_16x16x32_bf16 v[62:65], v[134:137], v[202:205], v[62:65]
	v_mfma_f32_16x16x32_bf16 v[38:41], v[134:137], v[210:213], v[38:41]
	v_mfma_f32_16x16x32_bf16 v[22:25], v[134:137], v[218:221], v[22:25]
	v_mfma_f32_16x16x32_bf16 v[6:9], v[134:137], v[226:229], v[6:9]
	v_mfma_f32_16x16x32_bf16 v[58:61], v[142:145], v[202:205], v[58:61]
	v_mfma_f32_16x16x32_bf16 v[34:37], v[142:145], v[210:213], v[34:37]
	v_mfma_f32_16x16x32_bf16 v[18:21], v[142:145], v[218:221], v[18:21]
	v_mfma_f32_16x16x32_bf16 v[2:5], v[142:145], v[226:229], v[2:5]
	s_setprio 0
	s_setprio 1
	v_mfma_f32_16x16x32_bf16 v[54:57], v[146:149], v[198:201], 0
	v_mfma_f32_16x16x32_bf16 v[42:45], v[146:149], v[206:209], 0
	v_mfma_f32_16x16x32_bf16 v[26:29], v[146:149], v[214:217], 0
	v_mfma_f32_16x16x32_bf16 v[10:13], v[146:149], v[222:225], 0
	v_mfma_f32_16x16x32_bf16 v[50:53], v[154:157], v[198:201], 0
	v_mfma_f32_16x16x32_bf16 v[46:49], v[154:157], v[206:209], 0
	v_mfma_f32_16x16x32_bf16 v[30:33], v[154:157], v[214:217], 0
	v_mfma_f32_16x16x32_bf16 v[14:17], v[154:157], v[222:225], 0
	v_mfma_f32_16x16x32_bf16 v[54:57], v[150:153], v[202:205], v[54:57]
	v_mfma_f32_16x16x32_bf16 v[42:45], v[150:153], v[210:213], v[42:45]
	v_mfma_f32_16x16x32_bf16 v[26:29], v[150:153], v[218:221], v[26:29]
	v_mfma_f32_16x16x32_bf16 v[10:13], v[150:153], v[226:229], v[10:13]
	v_mfma_f32_16x16x32_bf16 v[50:53], v[158:161], v[202:205], v[50:53]
	v_mfma_f32_16x16x32_bf16 v[46:49], v[158:161], v[210:213], v[46:49]
	v_mfma_f32_16x16x32_bf16 v[30:33], v[158:161], v[218:221], v[30:33]
	v_mfma_f32_16x16x32_bf16 v[14:17], v[158:161], v[226:229], v[14:17]
	s_setprio 0
	s_barrier
	s_add_i32 s78, 0, 0x18000
	s_add_i32 s89, 0, 0x1c000
	v_add_u32_e32 v142, s78, v163
	v_add_u32_e32 v158, s89, v163
	ds_read_b128 v[130:133], v142
	ds_read_b128 v[134:137], v142 offset:1024
	ds_read_b128 v[138:141], v142 offset:2048
	ds_read_b128 v[142:145], v142 offset:3072
	ds_read_b128 v[146:149], v158
	ds_read_b128 v[150:153], v158 offset:1024
	ds_read_b128 v[154:157], v158 offset:2048
	ds_read_b128 v[158:161], v158 offset:3072
	s_add_u32 s0, s46, 0x40000
	s_addc_u32 s1, s47, 0
	s_mov_b32 m0, s90
	ds_read_b128 v[198:201], v193 offset:32768
	ds_read_b128 v[202:205], v193 offset:33792
	ds_read_b128 v[206:209], v193 offset:34816
	ds_read_b128 v[210:213], v193 offset:35840
	ds_read_b128 v[214:217], v193 offset:36864
	ds_read_b128 v[218:221], v193 offset:37888
	ds_read_b128 v[222:225], v193 offset:38912
	ds_read_b128 v[226:229], v193 offset:39936
	global_load_lds_dwordx4 v170, s[0:1]
	s_mov_b32 m0, s91
	s_nop 0
	global_load_lds_dwordx4 v166, s[0:1]
	s_waitcnt vmcnt(8)
	s_waitcnt lgkmcnt(0)
	s_barrier
	s_setprio 1
	s_waitcnt lgkmcnt(0)
	v_mfma_f32_16x16x32_bf16 v[126:129], v[130:133], v[198:201], v[126:129]
	v_mfma_f32_16x16x32_bf16 v[110:113], v[130:133], v[206:209], v[110:113]
	v_mfma_f32_16x16x32_bf16 v[94:97], v[130:133], v[214:217], v[94:97]
	v_mfma_f32_16x16x32_bf16 v[78:81], v[130:133], v[222:225], v[78:81]
	v_mfma_f32_16x16x32_bf16 v[122:125], v[138:141], v[198:201], v[122:125]
	v_mfma_f32_16x16x32_bf16 v[106:109], v[138:141], v[206:209], v[106:109]
	v_mfma_f32_16x16x32_bf16 v[90:93], v[138:141], v[214:217], v[90:93]
	v_mfma_f32_16x16x32_bf16 v[74:77], v[138:141], v[222:225], v[74:77]
	v_mfma_f32_16x16x32_bf16 v[126:129], v[134:137], v[202:205], v[126:129]
	v_mfma_f32_16x16x32_bf16 v[110:113], v[134:137], v[210:213], v[110:113]
	v_mfma_f32_16x16x32_bf16 v[94:97], v[134:137], v[218:221], v[94:97]
	v_mfma_f32_16x16x32_bf16 v[78:81], v[134:137], v[226:229], v[78:81]
	v_mfma_f32_16x16x32_bf16 v[122:125], v[142:145], v[202:205], v[122:125]
	v_mfma_f32_16x16x32_bf16 v[106:109], v[142:145], v[210:213], v[106:109]
	v_mfma_f32_16x16x32_bf16 v[90:93], v[142:145], v[218:221], v[90:93]
	v_mfma_f32_16x16x32_bf16 v[74:77], v[142:145], v[226:229], v[74:77]
	s_setprio 0
	s_setprio 1
	v_mfma_f32_16x16x32_bf16 v[118:121], v[146:149], v[198:201], v[118:121]
	v_mfma_f32_16x16x32_bf16 v[102:105], v[146:149], v[206:209], v[102:105]
	v_mfma_f32_16x16x32_bf16 v[86:89], v[146:149], v[214:217], v[86:89]
	v_mfma_f32_16x16x32_bf16 v[70:73], v[146:149], v[222:225], v[70:73]
	v_mfma_f32_16x16x32_bf16 v[114:117], v[154:157], v[198:201], v[114:117]
	v_mfma_f32_16x16x32_bf16 v[98:101], v[154:157], v[206:209], v[98:101]
	v_mfma_f32_16x16x32_bf16 v[82:85], v[154:157], v[214:217], v[82:85]
	v_mfma_f32_16x16x32_bf16 v[66:69], v[154:157], v[222:225], v[66:69]
	v_mfma_f32_16x16x32_bf16 v[118:121], v[150:153], v[202:205], v[118:121]
	v_mfma_f32_16x16x32_bf16 v[102:105], v[150:153], v[210:213], v[102:105]
	v_mfma_f32_16x16x32_bf16 v[86:89], v[150:153], v[218:221], v[86:89]
	v_mfma_f32_16x16x32_bf16 v[70:73], v[150:153], v[226:229], v[70:73]
	v_mfma_f32_16x16x32_bf16 v[114:117], v[158:161], v[202:205], v[114:117]
	v_mfma_f32_16x16x32_bf16 v[98:101], v[158:161], v[210:213], v[98:101]
	v_mfma_f32_16x16x32_bf16 v[82:85], v[158:161], v[218:221], v[82:85]
	v_mfma_f32_16x16x32_bf16 v[66:69], v[158:161], v[226:229], v[66:69]
	s_setprio 0
	s_barrier
; #define PG8_STAGE(bufoff, gbase, voff) do { _Pragma("unroll") for (int _i = 0; _i < 2; ++_i) \
;         __builtin_amdgcn_global_load_lds((const unsigned*)((const char*)(gbase) + (voff)[_i]), (LAS unsigned*)(lds + (bufoff) + ldsw + _i * 8192), 16, 0, 0); } while (0)
; #define PG8_LDA(dst, b, h) do { _Pragma("unroll") for (int m = 0; m < 4; ++m) _Pragma("unroll") for (int k = 0; k < 2; ++k) dst[m][k] = *(const LAS bf16x8*)(lds + PG8_SA(b, h) + aoff + m * 2048 + k * 1024); } while (0)
; #define PG8_LDB(dst, b, h) do { _Pragma("unroll") for (int n = 0; n < 2; ++n) _Pragma("unroll") for (int k = 0; k < 2; ++k) dst[n][k] = *(const LAS bf16x8*)(lds + PG8_SB(b, h) + boff + n * 2048 + k * 1024); } while (0)
; #define PG8_MMA(ai, bj, At, Bt) do { __builtin_amdgcn_s_setprio(1); _Pragma("unroll") for (int m = 0; m < 4; ++m) _Pragma("unroll") for (int n = 0; n < 2; ++n) _Pragma("unroll") for (int k = 0; k < 2; ++k) \
;         acc[ai][bj][m][n] = __builtin_amdgcn_mfma_f32_16x16x32_bf16(Bt[n][k], At[m][k], acc[ai][bj][m][n], 0, 0, 0); __builtin_amdgcn_s_setprio(0); } while (0)
; #define PG8_WAIT_V(n) asm volatile("s_waitcnt vmcnt(" #n ")" ::: "memory")
; #define PG8_BAR __builtin_amdgcn_s_barrier()
; template <class Epi, bool ALIGN_EPI, bool SPLITA>
; __device__ __forceinline__ void gemm_phase(LAS unsigned char* lds, const Gemm g, const StaticOrder& S, const Epi& E) {
;     ...
;             PG8_LDB(B0, 0, 0); PG8_LDB(B1, 0, 1); PG8_SCHED; PG8_LDA(At, 0, 0); PG8_STAGE(PG8_SA(1, 1), a1h, vo1);
;             PG8_WAIT_V(8); PG8_WAIT_L(0); PG8_BAR; PG8_MMA(0, 0, At, B0); PG8_MMA(0, 1, At, B1); PG8_BAR; PG8_SCHED;
;             PG8_LDA(At, 0, 1); PG8_STAGE(PG8_SB(0, 0), b2, voffB); PG8_STAGE(PG8_SB(0, 1), b2 + hstepB, voffB); PG8_STAGE(PG8_SA(0, 0), a2, vo2);
;             PG8_WAIT_V(8); PG8_WAIT_L(0); PG8_BAR; PG8_MMA(1, 0, At, B0); PG8_MMA(1, 1, At, B1); PG8_BAR; PG8_SCHED;
;             PG8_LDB(B0, 1, 0); PG8_LDB(B1, 1, 1); PG8_SCHED; PG8_LDA(At, 1, 0); PG8_STAGE(PG8_SA(0, 1), a2h, vo2);
;             PG8_WAIT_V(8); PG8_WAIT_L(0); PG8_BAR; PG8_MMA(0, 0, At, B0); PG8_MMA(0, 1, At, B1); PG8_BAR; PG8_SCHED;
;             PG8_LDA(At, 1, 1); PG8_STAGE(PG8_SB(1, 0), b3, voffB); PG8_STAGE(PG8_SB(1, 1), b3 + hstepB, voffB); PG8_STAGE(PG8_SA(1, 0), a3, vo2);
;             PG8_WAIT_V(8); PG8_WAIT_L(0); PG8_BAR; PG8_MMA(1, 0, At, B0); PG8_MMA(1, 1, At, B1); PG8_BAR; PG8_SCHED;
	s_add_i32 s0, s78, s80
	s_mov_b32 m0, s0
	ds_read_b128 v[198:201], v193 offset:49152
	ds_read_b128 v[202:205], v193 offset:50176
	ds_read_b128 v[206:209], v193 offset:51200
	ds_read_b128 v[210:213], v193 offset:52224
	ds_read_b128 v[214:217], v193 offset:53248
	ds_read_b128 v[218:221], v193 offset:54272
	ds_read_b128 v[222:225], v193 offset:55296
	ds_read_b128 v[226:229], v193 offset:56320
	global_load_lds_dwordx4 v168, s[98:99]
	s_add_i32 m0, s0, 0x2000
	s_add_u32 s0, s44, 0x40080
	s_addc_u32 s1, s45, 0
	s_add_i32 s44, s89, s80
	global_load_lds_dwordx4 v164, s[98:99]
	s_mov_b32 m0, s44
	s_nop 0
	global_load_lds_dwordx4 v168, s[0:1]
	s_add_i32 m0, s44, 0x2000
	s_nop 0
	global_load_lds_dwordx4 v164, s[0:1]
	s_mov_b32 m0, s94
	s_nop 0
	global_load_lds_dwordx4 v170, s[100:101]
	s_mov_b32 m0, s95
	s_nop 0
	global_load_lds_dwordx4 v166, s[100:101]
	s_waitcnt vmcnt(8)
	s_waitcnt lgkmcnt(0)
	s_barrier
	s_setprio 1
	s_waitcnt lgkmcnt(0)
	v_mfma_f32_16x16x32_bf16 v[62:65], v[130:133], v[198:201], v[62:65]
	v_mfma_f32_16x16x32_bf16 v[38:41], v[130:133], v[206:209], v[38:41]
	v_mfma_f32_16x16x32_bf16 v[22:25], v[130:133], v[214:217], v[22:25]
	v_mfma_f32_16x16x32_bf16 v[6:9], v[130:133], v[222:225], v[6:9]
	v_mfma_f32_16x16x32_bf16 v[58:61], v[138:141], v[198:201], v[58:61]
	v_mfma_f32_16x16x32_bf16 v[34:37], v[138:141], v[206:209], v[34:37]
	v_mfma_f32_16x16x32_bf16 v[18:21], v[138:141], v[214:217], v[18:21]
	v_mfma_f32_16x16x32_bf16 v[2:5], v[138:141], v[222:225], v[2:5]
	v_mfma_f32_16x16x32_bf16 v[62:65], v[134:137], v[202:205], v[62:65]
	v_mfma_f32_16x16x32_bf16 v[38:41], v[134:137], v[210:213], v[38:41]
	v_mfma_f32_16x16x32_bf16 v[22:25], v[134:137], v[218:221], v[22:25]
	v_mfma_f32_16x16x32_bf16 v[6:9], v[134:137], v[226:229], v[6:9]
	v_mfma_f32_16x16x32_bf16 v[58:61], v[142:145], v[202:205], v[58:61]
	v_mfma_f32_16x16x32_bf16 v[34:37], v[142:145], v[210:213], v[34:37]
	v_mfma_f32_16x16x32_bf16 v[18:21], v[142:145], v[218:221], v[18:21]
	v_mfma_f32_16x16x32_bf16 v[2:5], v[142:145], v[226:229], v[2:5]
	s_setprio 0
	s_setprio 1
	v_mfma_f32_16x16x32_bf16 v[54:57], v[146:149], v[198:201], v[54:57]
	v_mfma_f32_16x16x32_bf16 v[42:45], v[146:149], v[206:209], v[42:45]
	v_mfma_f32_16x16x32_bf16 v[26:29], v[146:149], v[214:217], v[26:29]
	v_mfma_f32_16x16x32_bf16 v[10:13], v[146:149], v[222:225], v[10:13]
	v_mfma_f32_16x16x32_bf16 v[50:53], v[154:157], v[198:201], v[50:53]
	v_mfma_f32_16x16x32_bf16 v[46:49], v[154:157], v[206:209], v[46:49]
	v_mfma_f32_16x16x32_bf16 v[30:33], v[154:157], v[214:217], v[30:33]
	v_mfma_f32_16x16x32_bf16 v[14:17], v[154:157], v[222:225], v[14:17]
	v_mfma_f32_16x16x32_bf16 v[54:57], v[150:153], v[202:205], v[54:57]
	v_mfma_f32_16x16x32_bf16 v[42:45], v[150:153], v[210:213], v[42:45]
	v_mfma_f32_16x16x32_bf16 v[26:29], v[150:153], v[218:221], v[26:29]
	v_mfma_f32_16x16x32_bf16 v[10:13], v[150:153], v[226:229], v[10:13]
	v_mfma_f32_16x16x32_bf16 v[50:53], v[158:161], v[202:205], v[50:53]
	v_mfma_f32_16x16x32_bf16 v[46:49], v[158:161], v[210:213], v[46:49]
	v_mfma_f32_16x16x32_bf16 v[30:33], v[158:161], v[218:221], v[30:33]
	v_mfma_f32_16x16x32_bf16 v[14:17], v[158:161], v[226:229], v[14:17]
	s_setprio 0
	s_barrier
	s_add_i32 vcc_hi, vcc_hi, 2
	s_add_u32 s42, s42, 0x100
	s_addc_u32 s43, s43, 0
	s_add_u32 s61, s61, 0x100
	s_addc_u32 vcc_lo, vcc_lo, 0
.LBB0_229:
	ds_read_b128 v[130:133], v191
	ds_read_b128 v[134:137], v191 offset:1024
	ds_read_b128 v[138:141], v191 offset:2048
	ds_read_b128 v[142:145], v191 offset:3072
	ds_read_b128 v[146:149], v192
	ds_read_b128 v[150:153], v192 offset:1024
	ds_read_b128 v[154:157], v192 offset:2048
	ds_read_b128 v[158:161], v192 offset:3072
	s_add_u32 s0, s42, 0xfffc0080
	s_addc_u32 s1, s43, -1
	s_cmp_eq_u32 vcc_hi, 12
	s_cselect_b32 s47, s27, s1
	s_cselect_b32 s46, s33, s0
	s_cselect_b32 s45, s29, vcc_lo
	s_cselect_b32 s44, s60, s61
	s_add_i32 m0, s87, 0xc000
	ds_read_b128 v[198:201], v193
	ds_read_b128 v[202:205], v193 offset:1024
	ds_read_b128 v[206:209], v193 offset:2048
	ds_read_b128 v[210:213], v193 offset:3072
	ds_read_b128 v[214:217], v193 offset:4096
	ds_read_b128 v[218:221], v193 offset:5120
	ds_read_b128 v[222:225], v193 offset:6144
	ds_read_b128 v[226:229], v193 offset:7168
	global_load_lds_dwordx4 v182, s[42:43]
	s_add_i32 m0, s87, 0xe000
	s_nop 0
	global_load_lds_dwordx4 v184, s[42:43]
	s_waitcnt vmcnt(8)
	s_waitcnt lgkmcnt(0)
	s_barrier
	s_setprio 1
	s_waitcnt lgkmcnt(0)
	v_mfma_f32_16x16x32_bf16 v[126:129], v[130:133], v[198:201], v[126:129]
	v_mfma_f32_16x16x32_bf16 v[110:113], v[130:133], v[206:209], v[110:113]
	v_mfma_f32_16x16x32_bf16 v[94:97], v[130:133], v[214:217], v[94:97]
	v_mfma_f32_16x16x32_bf16 v[78:81], v[130:133], v[222:225], v[78:81]
	v_mfma_f32_16x16x32_bf16 v[122:125], v[138:141], v[198:201], v[122:125]
	v_mfma_f32_16x16x32_bf16 v[106:109], v[138:141], v[206:209], v[106:109]
	v_mfma_f32_16x16x32_bf16 v[90:93], v[138:141], v[214:217], v[90:93]
	v_mfma_f32_16x16x32_bf16 v[74:77], v[138:141], v[222:225], v[74:77]
	v_mfma_f32_16x16x32_bf16 v[126:129], v[134:137], v[202:205], v[126:129]
	v_mfma_f32_16x16x32_bf16 v[110:113], v[134:137], v[210:213], v[110:113]
	v_mfma_f32_16x16x32_bf16 v[94:97], v[134:137], v[218:221], v[94:97]
	v_mfma_f32_16x16x32_bf16 v[78:81], v[134:137], v[226:229], v[78:81]
	v_mfma_f32_16x16x32_bf16 v[122:125], v[142:145], v[202:205], v[122:125]
	v_mfma_f32_16x16x32_bf16 v[106:109], v[142:145], v[210:213], v[106:109]
	v_mfma_f32_16x16x32_bf16 v[90:93], v[142:145], v[218:221], v[90:93]
	v_mfma_f32_16x16x32_bf16 v[74:77], v[142:145], v[226:229], v[74:77]
	s_setprio 0
	s_setprio 1
	v_mfma_f32_16x16x32_bf16 v[118:121], v[146:149], v[198:201], v[118:121]
	v_mfma_f32_16x16x32_bf16 v[102:105], v[146:149], v[206:209], v[102:105]
	v_mfma_f32_16x16x32_bf16 v[86:89], v[146:149], v[214:217], v[86:89]
	v_mfma_f32_16x16x32_bf16 v[70:73], v[146:149], v[222:225], v[70:73]
	v_mfma_f32_16x16x32_bf16 v[114:117], v[154:157], v[198:201], v[114:117]
	v_mfma_f32_16x16x32_bf16 v[98:101], v[154:157], v[206:209], v[98:101]
	v_mfma_f32_16x16x32_bf16 v[82:85], v[154:157], v[214:217], v[82:85]
	v_mfma_f32_16x16x32_bf16 v[66:69], v[154:157], v[222:225], v[66:69]
	v_mfma_f32_16x16x32_bf16 v[118:121], v[150:153], v[202:205], v[118:121]
	v_mfma_f32_16x16x32_bf16 v[102:105], v[150:153], v[210:213], v[102:105]
	v_mfma_f32_16x16x32_bf16 v[86:89], v[150:153], v[218:221], v[86:89]
	v_mfma_f32_16x16x32_bf16 v[70:73], v[150:153], v[226:229], v[70:73]
	v_mfma_f32_16x16x32_bf16 v[114:117], v[158:161], v[202:205], v[114:117]
	v_mfma_f32_16x16x32_bf16 v[98:101], v[158:161], v[210:213], v[98:101]
	v_mfma_f32_16x16x32_bf16 v[82:85], v[158:161], v[218:221], v[82:85]
	v_mfma_f32_16x16x32_bf16 v[66:69], v[158:161], v[226:229], v[66:69]
	s_setprio 0
	s_barrier
; #define PG8_STAGE(bufoff, gbase, voff) do { _Pragma("unroll") for (int _i = 0; _i < 2; ++_i) \
;         __builtin_amdgcn_global_load_lds((const unsigned*)((const char*)(gbase) + (voff)[_i]), (LAS unsigned*)(lds + (bufoff) + ldsw + _i * 8192), 16, 0, 0); } while (0)
; #define PG8_LDA(dst, b, h) do { _Pragma("unroll") for (int m = 0; m < 4; ++m) _Pragma("unroll") for (int k = 0; k < 2; ++k) dst[m][k] = *(const LAS bf16x8*)(lds + PG8_SA(b, h) + aoff + m * 2048 + k * 1024); } while (0)
; #define PG8_LDB(dst, b, h) do { _Pragma("unroll") for (int n = 0; n < 2; ++n) _Pragma("unroll") for (int k = 0; k < 2; ++k) dst[n][k] = *(const LAS bf16x8*)(lds + PG8_SB(b, h) + boff + n * 2048 + k * 1024); } while (0)
; #define PG8_MMA(ai, bj, At, Bt) do { __builtin_amdgcn_s_setprio(1); _Pragma("unroll") for (int m = 0; m < 4; ++m) _Pragma("unroll") for (int n = 0; n < 2; ++n) _Pragma("unroll") for (int k = 0; k < 2; ++k) \
;         acc[ai][bj][m][n] = __builtin_amdgcn_mfma_f32_16x16x32_bf16(Bt[n][k], At[m][k], acc[ai][bj][m][n], 0, 0, 0); __builtin_amdgcn_s_setprio(0); } while (0)
; #define PG8_WAIT_V(n) asm volatile("s_waitcnt vmcnt(" #n ")" ::: "memory")
; #define PG8_WAIT_L(n) asm volatile("s_waitcnt lgkmcnt(" #n ")" ::: "memory")
; #define PG8_BAR __builtin_amdgcn_s_barrier()
; #define PG8_SCHED __builtin_amdgcn_sched_barrier(0)
; template <class Epi, bool ALIGN_EPI, bool SPLITA>
; __device__ __forceinline__ void gemm_phase(LAS unsigned char* lds, const Gemm g, const StaticOrder& S, const Epi& E) {
;     ...
;             PG8_LDA(At, 0, 1); PG8_STAGE(PG8_SB(0, 0), b2, voffB); PG8_STAGE(PG8_SB(0, 1), b2 + hstepB, voffB); PG8_STAGE(PG8_SA(0, 0), a2, vo2);
;             PG8_WAIT_V(8); PG8_WAIT_L(0); PG8_BAR; PG8_MMA(1, 0, At, B0); PG8_MMA(1, 1, At, B1); PG8_BAR; PG8_SCHED;
;             PG8_LDB(B0, 1, 0); PG8_LDB(B1, 1, 1); PG8_SCHED; PG8_LDA(At, 1, 0); PG8_STAGE(PG8_SA(0, 1), a2h, vo2);
;             PG8_WAIT_V(8); PG8_WAIT_L(0); PG8_BAR; PG8_MMA(0, 0, At, B0); PG8_MMA(0, 1, At, B1); PG8_BAR; PG8_SCHED;
	s_add_u32 s98, s44, s8
	s_addc_u32 s99, s45, s9
	s_add_u32 s100, s46, s8
	s_addc_u32 s101, s47, s9
	s_add_i32 s0, s97, s80
	s_mov_b32 m0, s0
	ds_read_b128 v[198:201], v193 offset:16384
	ds_read_b128 v[202:205], v193 offset:17408
	ds_read_b128 v[206:209], v193 offset:18432
	ds_read_b128 v[210:213], v193 offset:19456
	ds_read_b128 v[214:217], v193 offset:20480
	ds_read_b128 v[218:221], v193 offset:21504
	ds_read_b128 v[222:225], v193 offset:22528
	ds_read_b128 v[226:229], v193 offset:23552
	global_load_lds_dwordx4 v168, s[44:45]
	s_add_i32 m0, s0, 0x2000
	s_add_u32 s0, s44, 0x40000
	s_addc_u32 s1, s45, 0
	s_add_i32 s78, s64, s80
	global_load_lds_dwordx4 v164, s[44:45]
	s_mov_b32 m0, s78
	s_nop 0
	global_load_lds_dwordx4 v168, s[0:1]
	s_add_i32 m0, s78, 0x2000
	s_nop 0
	global_load_lds_dwordx4 v164, s[0:1]
	s_mov_b32 m0, s87
	s_nop 0
	global_load_lds_dwordx4 v170, s[46:47]
	s_mov_b32 m0, s88
	s_nop 0
	global_load_lds_dwordx4 v166, s[46:47]
	s_waitcnt vmcnt(8)
	s_waitcnt lgkmcnt(0)
	s_barrier
	s_setprio 1
	s_waitcnt lgkmcnt(0)
	v_mfma_f32_16x16x32_bf16 v[62:65], v[130:133], v[198:201], v[62:65]
	v_mfma_f32_16x16x32_bf16 v[38:41], v[130:133], v[206:209], v[38:41]
	v_mfma_f32_16x16x32_bf16 v[22:25], v[130:133], v[214:217], v[22:25]
	v_mfma_f32_16x16x32_bf16 v[6:9], v[130:133], v[222:225], v[6:9]
	v_mfma_f32_16x16x32_bf16 v[58:61], v[138:141], v[198:201], v[58:61]
	v_mfma_f32_16x16x32_bf16 v[34:37], v[138:141], v[206:209], v[34:37]
	v_mfma_f32_16x16x32_bf16 v[18:21], v[138:141], v[214:217], v[18:21]
	v_mfma_f32_16x16x32_bf16 v[2:5], v[138:141], v[222:225], v[2:5]
	v_mfma_f32_16x16x32_bf16 v[62:65], v[134:137], v[202:205], v[62:65]
	v_mfma_f32_16x16x32_bf16 v[38:41], v[134:137], v[210:213], v[38:41]
	v_mfma_f32_16x16x32_bf16 v[22:25], v[134:137], v[218:221], v[22:25]
	v_mfma_f32_16x16x32_bf16 v[6:9], v[134:137], v[226:229], v[6:9]
	v_mfma_f32_16x16x32_bf16 v[58:61], v[142:145], v[202:205], v[58:61]
	v_mfma_f32_16x16x32_bf16 v[34:37], v[142:145], v[210:213], v[34:37]
	v_mfma_f32_16x16x32_bf16 v[18:21], v[142:145], v[218:221], v[18:21]
	v_mfma_f32_16x16x32_bf16 v[2:5], v[142:145], v[226:229], v[2:5]
	s_setprio 0
	s_setprio 1
	v_mfma_f32_16x16x32_bf16 v[54:57], v[146:149], v[198:201], v[54:57]
	v_mfma_f32_16x16x32_bf16 v[42:45], v[146:149], v[206:209], v[42:45]
	v_mfma_f32_16x16x32_bf16 v[26:29], v[146:149], v[214:217], v[26:29]
	v_mfma_f32_16x16x32_bf16 v[10:13], v[146:149], v[222:225], v[10:13]
	v_mfma_f32_16x16x32_bf16 v[50:53], v[154:157], v[198:201], v[50:53]
	v_mfma_f32_16x16x32_bf16 v[46:49], v[154:157], v[206:209], v[46:49]
	v_mfma_f32_16x16x32_bf16 v[30:33], v[154:157], v[214:217], v[30:33]
	v_mfma_f32_16x16x32_bf16 v[14:17], v[154:157], v[222:225], v[14:17]
	v_mfma_f32_16x16x32_bf16 v[54:57], v[150:153], v[202:205], v[54:57]
	v_mfma_f32_16x16x32_bf16 v[42:45], v[150:153], v[210:213], v[42:45]
	v_mfma_f32_16x16x32_bf16 v[26:29], v[150:153], v[218:221], v[26:29]
	v_mfma_f32_16x16x32_bf16 v[10:13], v[150:153], v[226:229], v[10:13]
	v_mfma_f32_16x16x32_bf16 v[50:53], v[158:161], v[202:205], v[50:53]
	v_mfma_f32_16x16x32_bf16 v[46:49], v[158:161], v[210:213], v[46:49]
	v_mfma_f32_16x16x32_bf16 v[30:33], v[158:161], v[218:221], v[30:33]
	v_mfma_f32_16x16x32_bf16 v[14:17], v[158:161], v[226:229], v[14:17]
	s_setprio 0
	s_barrier
	s_add_i32 s78, 0, 0x18000
	s_add_i32 s89, 0, 0x1c000
	v_add_u32_e32 v142, s78, v163
	v_add_u32_e32 v158, s89, v163
	ds_read_b128 v[130:133], v142
	ds_read_b128 v[134:137], v142 offset:1024
	ds_read_b128 v[138:141], v142 offset:2048
	ds_read_b128 v[142:145], v142 offset:3072
	ds_read_b128 v[146:149], v158
	ds_read_b128 v[150:153], v158 offset:1024
	ds_read_b128 v[154:157], v158 offset:2048
	ds_read_b128 v[158:161], v158 offset:3072
	s_add_u32 s0, s46, 0x40000
	s_addc_u32 s1, s47, 0
	s_mov_b32 m0, s90
	ds_read_b128 v[198:201], v193 offset:32768
	ds_read_b128 v[202:205], v193 offset:33792
	ds_read_b128 v[206:209], v193 offset:34816
	ds_read_b128 v[210:213], v193 offset:35840
	ds_read_b128 v[214:217], v193 offset:36864
	ds_read_b128 v[218:221], v193 offset:37888
	ds_read_b128 v[222:225], v193 offset:38912
	ds_read_b128 v[226:229], v193 offset:39936
	global_load_lds_dwordx4 v170, s[0:1]
	s_mov_b32 m0, s91
	s_nop 0
	global_load_lds_dwordx4 v166, s[0:1]
	s_waitcnt vmcnt(8)
	s_waitcnt lgkmcnt(0)
	s_barrier
; #define PG8_STAGE(bufoff, gbase, voff) do { _Pragma("unroll") for (int _i = 0; _i < 2; ++_i) \
;         __builtin_amdgcn_global_load_lds((const unsigned*)((const char*)(gbase) + (voff)[_i]), (LAS unsigned*)(lds + (bufoff) + ldsw + _i * 8192), 16, 0, 0); } while (0)
; #define PG8_LDA(dst, b, h) do { _Pragma("unroll") for (int m = 0; m < 4; ++m) _Pragma("unroll") for (int k = 0; k < 2; ++k) dst[m][k] = *(const LAS bf16x8*)(lds + PG8_SA(b, h) + aoff + m * 2048 + k * 1024); } while (0)
; #define PG8_MMA(ai, bj, At, Bt) do { __builtin_amdgcn_s_setprio(1); _Pragma("unroll") for (int m = 0; m < 4; ++m) _Pragma("unroll") for (int n = 0; n < 2; ++n) _Pragma("unroll") for (int k = 0; k < 2; ++k) \
;         acc[ai][bj][m][n] = __builtin_amdgcn_mfma_f32_16x16x32_bf16(Bt[n][k], At[m][k], acc[ai][bj][m][n], 0, 0, 0); __builtin_amdgcn_s_setprio(0); } while (0)
; #define PG8_WAIT_V(n) asm volatile("s_waitcnt vmcnt(" #n ")" ::: "memory")
; #define PG8_WAIT_L(n) asm volatile("s_waitcnt lgkmcnt(" #n ")" ::: "memory")
; #define PG8_BAR __builtin_amdgcn_s_barrier()
; #define PG8_SCHED __builtin_amdgcn_sched_barrier(0)
; template <class Epi, bool ALIGN_EPI, bool SPLITA>
; __device__ __forceinline__ void gemm_phase(LAS unsigned char* lds, const Gemm g, const StaticOrder& S, const Epi& E) {
;     ...
;             PG8_WAIT_V(8); PG8_WAIT_L(0); PG8_BAR; PG8_MMA(0, 0, At, B0); PG8_MMA(0, 1, At, B1); PG8_BAR; PG8_SCHED;
;             PG8_LDA(At, 1, 1); PG8_STAGE(PG8_SB(1, 0), b3, voffB); PG8_STAGE(PG8_SB(1, 1), b3 + hstepB, voffB); PG8_STAGE(PG8_SA(1, 0), a3, vo2);
;             PG8_WAIT_V(8); PG8_WAIT_L(0); PG8_BAR; PG8_MMA(1, 0, At, B0); PG8_MMA(1, 1, At, B1); PG8_BAR; PG8_SCHED;
;         }
;         if constexpr (ALIGN_EPI) { if (wr == 0) PG8_BAR; }
	s_setprio 1
	s_waitcnt lgkmcnt(0)
	v_mfma_f32_16x16x32_bf16 v[126:129], v[130:133], v[198:201], v[126:129]
	v_mfma_f32_16x16x32_bf16 v[110:113], v[130:133], v[206:209], v[110:113]
	v_mfma_f32_16x16x32_bf16 v[94:97], v[130:133], v[214:217], v[94:97]
	v_mfma_f32_16x16x32_bf16 v[78:81], v[130:133], v[222:225], v[78:81]
	v_mfma_f32_16x16x32_bf16 v[122:125], v[138:141], v[198:201], v[122:125]
	v_mfma_f32_16x16x32_bf16 v[106:109], v[138:141], v[206:209], v[106:109]
	v_mfma_f32_16x16x32_bf16 v[90:93], v[138:141], v[214:217], v[90:93]
	v_mfma_f32_16x16x32_bf16 v[74:77], v[138:141], v[222:225], v[74:77]
	v_mfma_f32_16x16x32_bf16 v[126:129], v[134:137], v[202:205], v[126:129]
	v_mfma_f32_16x16x32_bf16 v[110:113], v[134:137], v[210:213], v[110:113]
	v_mfma_f32_16x16x32_bf16 v[94:97], v[134:137], v[218:221], v[94:97]
	v_mfma_f32_16x16x32_bf16 v[78:81], v[134:137], v[226:229], v[78:81]
	v_mfma_f32_16x16x32_bf16 v[122:125], v[142:145], v[202:205], v[122:125]
	v_mfma_f32_16x16x32_bf16 v[106:109], v[142:145], v[210:213], v[106:109]
	v_mfma_f32_16x16x32_bf16 v[90:93], v[142:145], v[218:221], v[90:93]
	v_mfma_f32_16x16x32_bf16 v[74:77], v[142:145], v[226:229], v[74:77]
	s_setprio 0
	s_setprio 1
	v_mfma_f32_16x16x32_bf16 v[118:121], v[146:149], v[198:201], v[118:121]
	v_mfma_f32_16x16x32_bf16 v[102:105], v[146:149], v[206:209], v[102:105]
	v_mfma_f32_16x16x32_bf16 v[86:89], v[146:149], v[214:217], v[86:89]
	v_mfma_f32_16x16x32_bf16 v[70:73], v[146:149], v[222:225], v[70:73]
	v_mfma_f32_16x16x32_bf16 v[114:117], v[154:157], v[198:201], v[114:117]
	v_mfma_f32_16x16x32_bf16 v[98:101], v[154:157], v[206:209], v[98:101]
	v_mfma_f32_16x16x32_bf16 v[82:85], v[154:157], v[214:217], v[82:85]
	v_mfma_f32_16x16x32_bf16 v[66:69], v[154:157], v[222:225], v[66:69]
	v_mfma_f32_16x16x32_bf16 v[118:121], v[150:153], v[202:205], v[118:121]
	v_mfma_f32_16x16x32_bf16 v[102:105], v[150:153], v[210:213], v[102:105]
	v_mfma_f32_16x16x32_bf16 v[86:89], v[150:153], v[218:221], v[86:89]
	v_mfma_f32_16x16x32_bf16 v[70:73], v[150:153], v[226:229], v[70:73]
	v_mfma_f32_16x16x32_bf16 v[114:117], v[158:161], v[202:205], v[114:117]
	v_mfma_f32_16x16x32_bf16 v[98:101], v[158:161], v[210:213], v[98:101]
	v_mfma_f32_16x16x32_bf16 v[82:85], v[158:161], v[218:221], v[82:85]
	v_mfma_f32_16x16x32_bf16 v[66:69], v[158:161], v[226:229], v[66:69]
	s_setprio 0
	s_barrier
	s_add_i32 s0, s78, s80
	s_mov_b32 m0, s0
	ds_read_b128 v[198:201], v193 offset:49152
	ds_read_b128 v[202:205], v193 offset:50176
	ds_read_b128 v[206:209], v193 offset:51200
	ds_read_b128 v[210:213], v193 offset:52224
	ds_read_b128 v[214:217], v193 offset:53248
	ds_read_b128 v[218:221], v193 offset:54272
	ds_read_b128 v[222:225], v193 offset:55296
	ds_read_b128 v[226:229], v193 offset:56320
	global_load_lds_dwordx4 v168, s[98:99]
	s_add_i32 m0, s0, 0x2000
	s_add_u32 s0, s44, 0x40080
	s_addc_u32 s1, s45, 0
	s_add_i32 s44, s89, s80
	global_load_lds_dwordx4 v164, s[98:99]
	s_mov_b32 m0, s44
	s_nop 0
	global_load_lds_dwordx4 v168, s[0:1]
	s_add_i32 m0, s44, 0x2000
	s_nop 0
	global_load_lds_dwordx4 v164, s[0:1]
	s_mov_b32 m0, s94
	s_nop 0
	global_load_lds_dwordx4 v170, s[100:101]
	s_mov_b32 m0, s95
	s_nop 0
	global_load_lds_dwordx4 v166, s[100:101]
	s_waitcnt vmcnt(8)
	s_waitcnt lgkmcnt(0)
	s_barrier
	s_setprio 1
	s_waitcnt lgkmcnt(0)
	v_mfma_f32_16x16x32_bf16 v[62:65], v[130:133], v[198:201], v[62:65]
	v_mfma_f32_16x16x32_bf16 v[38:41], v[130:133], v[206:209], v[38:41]
	v_mfma_f32_16x16x32_bf16 v[22:25], v[130:133], v[214:217], v[22:25]
	v_mfma_f32_16x16x32_bf16 v[6:9], v[130:133], v[222:225], v[6:9]
	v_mfma_f32_16x16x32_bf16 v[58:61], v[138:141], v[198:201], v[58:61]
	v_mfma_f32_16x16x32_bf16 v[34:37], v[138:141], v[206:209], v[34:37]
	v_mfma_f32_16x16x32_bf16 v[18:21], v[138:141], v[214:217], v[18:21]
	v_mfma_f32_16x16x32_bf16 v[2:5], v[138:141], v[222:225], v[2:5]
	v_mfma_f32_16x16x32_bf16 v[62:65], v[134:137], v[202:205], v[62:65]
	v_mfma_f32_16x16x32_bf16 v[38:41], v[134:137], v[210:213], v[38:41]
	v_mfma_f32_16x16x32_bf16 v[22:25], v[134:137], v[218:221], v[22:25]
	v_mfma_f32_16x16x32_bf16 v[6:9], v[134:137], v[226:229], v[6:9]
	v_mfma_f32_16x16x32_bf16 v[58:61], v[142:145], v[202:205], v[58:61]
	v_mfma_f32_16x16x32_bf16 v[34:37], v[142:145], v[210:213], v[34:37]
	v_mfma_f32_16x16x32_bf16 v[18:21], v[142:145], v[218:221], v[18:21]
	v_mfma_f32_16x16x32_bf16 v[2:5], v[142:145], v[226:229], v[2:5]
	s_setprio 0
	s_setprio 1
	v_mfma_f32_16x16x32_bf16 v[54:57], v[146:149], v[198:201], v[54:57]
	v_mfma_f32_16x16x32_bf16 v[42:45], v[146:149], v[206:209], v[42:45]
	v_mfma_f32_16x16x32_bf16 v[26:29], v[146:149], v[214:217], v[26:29]
	v_mfma_f32_16x16x32_bf16 v[10:13], v[146:149], v[222:225], v[10:13]
	v_mfma_f32_16x16x32_bf16 v[50:53], v[154:157], v[198:201], v[50:53]
	v_mfma_f32_16x16x32_bf16 v[46:49], v[154:157], v[206:209], v[46:49]
	v_mfma_f32_16x16x32_bf16 v[30:33], v[154:157], v[214:217], v[30:33]
	v_mfma_f32_16x16x32_bf16 v[14:17], v[154:157], v[222:225], v[14:17]
	v_mfma_f32_16x16x32_bf16 v[54:57], v[150:153], v[202:205], v[54:57]
	v_mfma_f32_16x16x32_bf16 v[42:45], v[150:153], v[210:213], v[42:45]
	v_mfma_f32_16x16x32_bf16 v[26:29], v[150:153], v[218:221], v[26:29]
	v_mfma_f32_16x16x32_bf16 v[10:13], v[150:153], v[226:229], v[10:13]
	v_mfma_f32_16x16x32_bf16 v[50:53], v[158:161], v[202:205], v[50:53]
	v_mfma_f32_16x16x32_bf16 v[46:49], v[158:161], v[210:213], v[46:49]
	v_mfma_f32_16x16x32_bf16 v[30:33], v[158:161], v[218:221], v[30:33]
	v_mfma_f32_16x16x32_bf16 v[14:17], v[158:161], v[226:229], v[14:17]
	s_setprio 0
	s_barrier
	s_add_i32 vcc_hi, vcc_hi, 2
	s_add_u32 s42, s42, 0x100
	s_addc_u32 s43, s43, 0
	s_add_u32 s61, s61, 0x100
	s_addc_u32 vcc_lo, vcc_lo, 0
	s_cmp_gt_u32 vcc_hi, 13
	s_cbranch_scc0 .LBB0_229
	s_and_b64 vcc, exec, s[12:13]
	s_cbranch_vccz .LBB0_232
	s_barrier

; #define PG8_WAIT_V(n) asm volatile("s_waitcnt vmcnt(" #n ")" ::: "memory")
; #define PG8_BAR __builtin_amdgcn_s_barrier()
; template <class Epi, bool ALIGN_EPI, bool SPLITA>
; __device__ __forceinline__ void gemm_phase(LAS unsigned char* lds, const Gemm g, const StaticOrder& S, const Epi& E) {
;     ...
;         const bool has_next = S.next(ui + 1, nxt);
;         const char* nA = has_next ? baseA1(nxt) : cA;
;         const char* nB = has_next ? baseB(nxt) : cB;
;         const bool mirN = has_next ? mirrored(nxt) : mirC;
;         for (int t = 0; t < nt; t += 2) {
;             const bool last = (t == nt - 2);
;             if constexpr (Epi::MIDK) { if (t == g.ksplit) E.mid(acc, cur, wr, wc, fr, fq); }
;             const char *a1, *a2;
;             if constexpr (SPLITA) {
;                 a1 = (t + 1 < g.ksplit) ? cA + (size_t)(t + 1) * kstep : cA2 + (size_t)(t + 1 - g.ksplit) * 2048;
;                 a2 = last ? nA : ((t + 2 < g.ksplit) ? cA + (size_t)(t + 2) * kstep : cA2 + (size_t)(t + 2 - g.ksplit) * 2048);
;             } else { a1 = cA + kofs(t + 1); a2 = last ? nA : cA + kofs(t + 2); }
;             const char* b2 = last ? nB : cB + (size_t)(t + 2) * kstepB;
;             const bool s2a = SPLITA && (t + 1 >= g.ksplit), s2b = SPLITA && !last && (t + 2 >= g.ksplit);
;             const char* a3 = a2 + ((Epi::KSUB || s2b) ? (size_t)2048 : kstep); const char* b3 = b2 + kstepB;
;             const bool m1 = SPLITA && mirC && (t + 1 < g.ksplit), m2 = SPLITA && (last ? mirN : (mirC && (t + 2 < g.ksplit)));
;             const unsigned vo1[2] = {s2a ? voffA2[0] : m1 ? voffAm[0] : voffA[0], s2a ? voffA2[1] : m1 ? voffAm[1] : voffA[1]}, vo2[2] = {s2b ? voffA2[0] : m2 ? voffAm[0] : voffA[0], s2b ? voffA2[1] : m2 ? voffAm[1] : voffA[1]};
;             const char* a1h = m1 ? a1 - hstepA : a1 + hstepA; const char* a2h = m2 ? a2 - hstepA : a2 + hstepA;
;             PG8_LDB(B0, 0, 0); PG8_LDB(B1, 0, 1); PG8_SCHED; PG8_LDA(At, 0, 0); PG8_STAGE(PG8_SA(1, 1), a1h, vo1);
;             PG8_WAIT_V(8); PG8_WAIT_L(0); PG8_BAR; PG8_MMA(0, 0, At, B0); PG8_MMA(0, 1, At, B1); PG8_BAR; PG8_SCHED;
;             PG8_LDA(At, 0, 1); PG8_STAGE(PG8_SB(0, 0), b2, voffB); PG8_STAGE(PG8_SB(0, 1), b2 + hstepB, voffB); PG8_STAGE(PG8_SA(0, 0), a2, vo2);
;             PG8_WAIT_V(8); PG8_WAIT_L(0); PG8_BAR; PG8_MMA(1, 0, At, B0); PG8_MMA(1, 1, At, B1); PG8_BAR; PG8_SCHED;
.LBB0_264:
	s_ashr_i32 s29, s28, 31
	s_lshl_b64 s[40:41], s[28:29], 19
	s_add_u32 s40, s6, s40
	s_addc_u32 s41, s7, s41
	s_and_b64 s[0:1], s[0:1], exec
	s_cselect_b32 s13, s41, s47
	s_cselect_b32 s27, s40, s46
	s_add_u32 s0, s46, 0x40080
	s_addc_u32 s1, s47, 0
	s_add_u32 s29, s44, 0x100
	s_addc_u32 s90, s45, 0
	s_mov_b32 s91, -2
	ds_read_b128 v[146:149], v152
	ds_read_b128 v[156:159], v152 offset:1024
	ds_read_b128 v[164:167], v152 offset:2048
	ds_read_b128 v[168:171], v152 offset:3072
	ds_read_b128 v[172:175], v153
	ds_read_b128 v[176:179], v153 offset:1024
	ds_read_b128 v[180:183], v153 offset:2048
	ds_read_b128 v[184:187], v153 offset:3072
	s_add_u32 s44, s0, 0xfffc0080
	s_addc_u32 s45, s1, -1
	s_cmp_eq_u32 s91, 12
	s_cselect_b32 s47, s13, s45
	s_cselect_b32 s46, s27, s44
	s_cselect_b32 s45, s39, s90
	s_cselect_b32 s44, s38, s29
	s_add_i32 m0, s43, 0xc000
	ds_read_b128 v[188:191], v154
	ds_read_b128 v[192:195], v154 offset:1024
	ds_read_b128 v[196:199], v154 offset:2048
	ds_read_b128 v[200:203], v154 offset:3072
	ds_read_b128 v[204:207], v154 offset:4096
	ds_read_b128 v[208:211], v154 offset:5120
	ds_read_b128 v[212:215], v154 offset:6144
	ds_read_b128 v[216:219], v154 offset:7168
	global_load_lds_dwordx4 v138, s[0:1]
	s_add_i32 m0, s43, 0xe000
	s_nop 0
	global_load_lds_dwordx4 v140, s[0:1]
	s_waitcnt vmcnt(8)
	s_waitcnt lgkmcnt(0)
	s_barrier
	s_setprio 1
	s_waitcnt lgkmcnt(0)
	v_mfma_f32_16x16x32_bf16 v[126:129], v[146:149], v[188:191], 0
	v_mfma_f32_16x16x32_bf16 v[110:113], v[146:149], v[196:199], 0
	v_mfma_f32_16x16x32_bf16 v[94:97], v[146:149], v[204:207], 0
	v_mfma_f32_16x16x32_bf16 v[78:81], v[146:149], v[212:215], 0
	v_mfma_f32_16x16x32_bf16 v[122:125], v[164:167], v[188:191], 0
	v_mfma_f32_16x16x32_bf16 v[106:109], v[164:167], v[196:199], 0
	v_mfma_f32_16x16x32_bf16 v[90:93], v[164:167], v[204:207], 0
	v_mfma_f32_16x16x32_bf16 v[74:77], v[164:167], v[212:215], 0
	v_mfma_f32_16x16x32_bf16 v[126:129], v[156:159], v[192:195], v[126:129]
	v_mfma_f32_16x16x32_bf16 v[110:113], v[156:159], v[200:203], v[110:113]
	v_mfma_f32_16x16x32_bf16 v[94:97], v[156:159], v[208:211], v[94:97]
	v_mfma_f32_16x16x32_bf16 v[78:81], v[156:159], v[216:219], v[78:81]
	v_mfma_f32_16x16x32_bf16 v[122:125], v[168:171], v[192:195], v[122:125]
	v_mfma_f32_16x16x32_bf16 v[106:109], v[168:171], v[200:203], v[106:109]
	v_mfma_f32_16x16x32_bf16 v[90:93], v[168:171], v[208:211], v[90:93]
	v_mfma_f32_16x16x32_bf16 v[74:77], v[168:171], v[216:219], v[74:77]
	s_setprio 0
	s_setprio 1
	v_mfma_f32_16x16x32_bf16 v[118:121], v[172:175], v[188:191], 0
	v_mfma_f32_16x16x32_bf16 v[102:105], v[172:175], v[196:199], 0
	v_mfma_f32_16x16x32_bf16 v[86:89], v[172:175], v[204:207], 0
	v_mfma_f32_16x16x32_bf16 v[70:73], v[172:175], v[212:215], 0
	v_mfma_f32_16x16x32_bf16 v[114:117], v[180:183], v[188:191], 0
	v_mfma_f32_16x16x32_bf16 v[98:101], v[180:183], v[196:199], 0
	v_mfma_f32_16x16x32_bf16 v[82:85], v[180:183], v[204:207], 0
	v_mfma_f32_16x16x32_bf16 v[66:69], v[180:183], v[212:215], 0
	v_mfma_f32_16x16x32_bf16 v[118:121], v[176:179], v[192:195], v[118:121]
	v_mfma_f32_16x16x32_bf16 v[102:105], v[176:179], v[200:203], v[102:105]
	v_mfma_f32_16x16x32_bf16 v[86:89], v[176:179], v[208:211], v[86:89]
	v_mfma_f32_16x16x32_bf16 v[70:73], v[176:179], v[216:219], v[70:73]
	v_mfma_f32_16x16x32_bf16 v[114:117], v[184:187], v[192:195], v[114:117]
	v_mfma_f32_16x16x32_bf16 v[98:101], v[184:187], v[200:203], v[98:101]
	v_mfma_f32_16x16x32_bf16 v[82:85], v[184:187], v[208:211], v[82:85]
	v_mfma_f32_16x16x32_bf16 v[66:69], v[184:187], v[216:219], v[66:69]
	s_setprio 0
	s_barrier
	s_add_u32 s98, s44, s8
	s_addc_u32 s99, s45, s9
	s_add_u32 s100, s46, s8
	s_addc_u32 s101, s47, s9
	s_add_i32 s89, s79, s33
	s_mov_b32 m0, s89
	ds_read_b128 v[188:191], v154 offset:16384
	ds_read_b128 v[192:195], v154 offset:17408
	ds_read_b128 v[196:199], v154 offset:18432
	ds_read_b128 v[200:203], v154 offset:19456
	ds_read_b128 v[204:207], v154 offset:20480
	ds_read_b128 v[208:211], v154 offset:21504
	ds_read_b128 v[212:215], v154 offset:22528
	ds_read_b128 v[216:219], v154 offset:23552
	global_load_lds_dwordx4 v134, s[44:45]
	s_add_i32 m0, s89, 0x2000
	s_add_u32 s92, s44, 0x200000
	s_addc_u32 s93, s45, 0
	s_add_i32 s89, s80, s33
	global_load_lds_dwordx4 v130, s[44:45]
	s_mov_b32 m0, s89
	s_nop 0
	global_load_lds_dwordx4 v134, s[92:93]
	s_add_i32 m0, s89, 0x2000
	s_nop 0
	global_load_lds_dwordx4 v130, s[92:93]
	s_mov_b32 m0, s43
	s_nop 0
	global_load_lds_dwordx4 v136, s[46:47]
	s_mov_b32 m0, s60
	s_nop 0
	global_load_lds_dwordx4 v132, s[46:47]
	s_waitcnt vmcnt(8)
	s_waitcnt lgkmcnt(0)
	s_barrier
; #define PG8_STAGE(bufoff, gbase, voff) do { _Pragma("unroll") for (int _i = 0; _i < 2; ++_i) \
;         __builtin_amdgcn_global_load_lds((const unsigned*)((const char*)(gbase) + (voff)[_i]), (LAS unsigned*)(lds + (bufoff) + ldsw + _i * 8192), 16, 0, 0); } while (0)
; #define PG8_LDA(dst, b, h) do { _Pragma("unroll") for (int m = 0; m < 4; ++m) _Pragma("unroll") for (int k = 0; k < 2; ++k) dst[m][k] = *(const LAS bf16x8*)(lds + PG8_SA(b, h) + aoff + m * 2048 + k * 1024); } while (0)
; #define PG8_LDB(dst, b, h) do { _Pragma("unroll") for (int n = 0; n < 2; ++n) _Pragma("unroll") for (int k = 0; k < 2; ++k) dst[n][k] = *(const LAS bf16x8*)(lds + PG8_SB(b, h) + boff + n * 2048 + k * 1024); } while (0)
; #define PG8_MMA(ai, bj, At, Bt) do { __builtin_amdgcn_s_setprio(1); _Pragma("unroll") for (int m = 0; m < 4; ++m) _Pragma("unroll") for (int n = 0; n < 2; ++n) _Pragma("unroll") for (int k = 0; k < 2; ++k) \
;         acc[ai][bj][m][n] = __builtin_amdgcn_mfma_f32_16x16x32_bf16(Bt[n][k], At[m][k], acc[ai][bj][m][n], 0, 0, 0); __builtin_amdgcn_s_setprio(0); } while (0)
; #define PG8_WAIT_V(n) asm volatile("s_waitcnt vmcnt(" #n ")" ::: "memory")
; #define PG8_WAIT_L(n) asm volatile("s_waitcnt lgkmcnt(" #n ")" ::: "memory")
; #define PG8_BAR __builtin_amdgcn_s_barrier()
; #define PG8_SCHED __builtin_amdgcn_sched_barrier(0)
; template <class Epi, bool ALIGN_EPI, bool SPLITA>
; __device__ __forceinline__ void gemm_phase(LAS unsigned char* lds, const Gemm g, const StaticOrder& S, const Epi& E) {
;     ...
;             PG8_WAIT_V(8); PG8_WAIT_L(0); PG8_BAR; PG8_MMA(1, 0, At, B0); PG8_MMA(1, 1, At, B1); PG8_BAR; PG8_SCHED;
;             PG8_LDB(B0, 1, 0); PG8_LDB(B1, 1, 1); PG8_SCHED; PG8_LDA(At, 1, 0); PG8_STAGE(PG8_SA(0, 1), a2h, vo2);
;             PG8_WAIT_V(8); PG8_WAIT_L(0); PG8_BAR; PG8_MMA(0, 0, At, B0); PG8_MMA(0, 1, At, B1); PG8_BAR; PG8_SCHED;
	s_setprio 1
	s_waitcnt lgkmcnt(0)
	v_mfma_f32_16x16x32_bf16 v[54:57], v[146:149], v[188:191], 0
	v_mfma_f32_16x16x32_bf16 v[22:25], v[146:149], v[196:199], 0
	v_mfma_f32_16x16x32_bf16 v[14:17], v[146:149], v[204:207], 0
	v_mfma_f32_16x16x32_bf16 v[6:9], v[146:149], v[212:215], 0
	v_mfma_f32_16x16x32_bf16 v[50:53], v[164:167], v[188:191], 0
	v_mfma_f32_16x16x32_bf16 v[18:21], v[164:167], v[196:199], 0
	v_mfma_f32_16x16x32_bf16 v[10:13], v[164:167], v[204:207], 0
	v_mfma_f32_16x16x32_bf16 v[2:5], v[164:167], v[212:215], 0
	v_mfma_f32_16x16x32_bf16 v[54:57], v[156:159], v[192:195], v[54:57]
	v_mfma_f32_16x16x32_bf16 v[22:25], v[156:159], v[200:203], v[22:25]
	v_mfma_f32_16x16x32_bf16 v[14:17], v[156:159], v[208:211], v[14:17]
	v_mfma_f32_16x16x32_bf16 v[6:9], v[156:159], v[216:219], v[6:9]
	v_mfma_f32_16x16x32_bf16 v[50:53], v[168:171], v[192:195], v[50:53]
	v_mfma_f32_16x16x32_bf16 v[18:21], v[168:171], v[200:203], v[18:21]
	v_mfma_f32_16x16x32_bf16 v[10:13], v[168:171], v[208:211], v[10:13]
	v_mfma_f32_16x16x32_bf16 v[2:5], v[168:171], v[216:219], v[2:5]
	s_setprio 0
	s_setprio 1
	v_mfma_f32_16x16x32_bf16 v[38:41], v[172:175], v[188:191], 0
	v_mfma_f32_16x16x32_bf16 v[58:61], v[172:175], v[196:199], 0
	v_mfma_f32_16x16x32_bf16 v[42:45], v[172:175], v[204:207], 0
	v_mfma_f32_16x16x32_bf16 v[26:29], v[172:175], v[212:215], 0
	v_mfma_f32_16x16x32_bf16 v[34:37], v[180:183], v[188:191], 0
	v_mfma_f32_16x16x32_bf16 v[62:65], v[180:183], v[196:199], 0
	v_mfma_f32_16x16x32_bf16 v[46:49], v[180:183], v[204:207], 0
	v_mfma_f32_16x16x32_bf16 v[30:33], v[180:183], v[212:215], 0
	v_mfma_f32_16x16x32_bf16 v[38:41], v[176:179], v[192:195], v[38:41]
	v_mfma_f32_16x16x32_bf16 v[58:61], v[176:179], v[200:203], v[58:61]
	v_mfma_f32_16x16x32_bf16 v[42:45], v[176:179], v[208:211], v[42:45]
	v_mfma_f32_16x16x32_bf16 v[26:29], v[176:179], v[216:219], v[26:29]
	v_mfma_f32_16x16x32_bf16 v[34:37], v[184:187], v[192:195], v[34:37]
	v_mfma_f32_16x16x32_bf16 v[62:65], v[184:187], v[200:203], v[62:65]
	v_mfma_f32_16x16x32_bf16 v[46:49], v[184:187], v[208:211], v[46:49]
	v_mfma_f32_16x16x32_bf16 v[30:33], v[184:187], v[216:219], v[30:33]
	s_setprio 0
	s_barrier
	s_add_i32 s89, 0, 0x18000
	v_add_u32_e32 v155, s89, v150
	s_add_i32 s92, 0, 0x1c000
	ds_read_b128 v[146:149], v155
	ds_read_b128 v[156:159], v155 offset:1024
	ds_read_b128 v[164:167], v155 offset:2048
	ds_read_b128 v[168:171], v155 offset:3072
	v_add_u32_e32 v155, s92, v150
	ds_read_b128 v[172:175], v155
	ds_read_b128 v[176:179], v155 offset:1024
	ds_read_b128 v[180:183], v155 offset:2048
	ds_read_b128 v[184:187], v155 offset:3072
	s_add_u32 s46, s46, 0x40000
	s_addc_u32 s47, s47, 0
	s_mov_b32 m0, s61
	ds_read_b128 v[188:191], v154 offset:32768
	ds_read_b128 v[192:195], v154 offset:33792
	ds_read_b128 v[196:199], v154 offset:34816
	ds_read_b128 v[200:203], v154 offset:35840
	ds_read_b128 v[204:207], v154 offset:36864
	ds_read_b128 v[208:211], v154 offset:37888
	ds_read_b128 v[212:215], v154 offset:38912
	ds_read_b128 v[216:219], v154 offset:39936
	global_load_lds_dwordx4 v136, s[46:47]
	s_mov_b32 m0, s64
	s_nop 0
	global_load_lds_dwordx4 v132, s[46:47]
	s_waitcnt vmcnt(8)
	s_waitcnt lgkmcnt(0)
	s_barrier
	s_setprio 1
	s_waitcnt lgkmcnt(0)
	v_mfma_f32_16x16x32_bf16 v[126:129], v[146:149], v[188:191], v[126:129]
	v_mfma_f32_16x16x32_bf16 v[110:113], v[146:149], v[196:199], v[110:113]
	v_mfma_f32_16x16x32_bf16 v[94:97], v[146:149], v[204:207], v[94:97]
	v_mfma_f32_16x16x32_bf16 v[78:81], v[146:149], v[212:215], v[78:81]
	v_mfma_f32_16x16x32_bf16 v[122:125], v[164:167], v[188:191], v[122:125]
	v_mfma_f32_16x16x32_bf16 v[106:109], v[164:167], v[196:199], v[106:109]
	v_mfma_f32_16x16x32_bf16 v[90:93], v[164:167], v[204:207], v[90:93]
	v_mfma_f32_16x16x32_bf16 v[74:77], v[164:167], v[212:215], v[74:77]
	v_mfma_f32_16x16x32_bf16 v[126:129], v[156:159], v[192:195], v[126:129]
	v_mfma_f32_16x16x32_bf16 v[110:113], v[156:159], v[200:203], v[110:113]
	v_mfma_f32_16x16x32_bf16 v[94:97], v[156:159], v[208:211], v[94:97]
	v_mfma_f32_16x16x32_bf16 v[78:81], v[156:159], v[216:219], v[78:81]
	v_mfma_f32_16x16x32_bf16 v[122:125], v[168:171], v[192:195], v[122:125]
	v_mfma_f32_16x16x32_bf16 v[106:109], v[168:171], v[200:203], v[106:109]
	v_mfma_f32_16x16x32_bf16 v[90:93], v[168:171], v[208:211], v[90:93]
	v_mfma_f32_16x16x32_bf16 v[74:77], v[168:171], v[216:219], v[74:77]
	s_setprio 0
	s_setprio 1
	v_mfma_f32_16x16x32_bf16 v[118:121], v[172:175], v[188:191], v[118:121]
	v_mfma_f32_16x16x32_bf16 v[102:105], v[172:175], v[196:199], v[102:105]
	v_mfma_f32_16x16x32_bf16 v[86:89], v[172:175], v[204:207], v[86:89]
	v_mfma_f32_16x16x32_bf16 v[70:73], v[172:175], v[212:215], v[70:73]
	v_mfma_f32_16x16x32_bf16 v[114:117], v[180:183], v[188:191], v[114:117]
	v_mfma_f32_16x16x32_bf16 v[98:101], v[180:183], v[196:199], v[98:101]
	v_mfma_f32_16x16x32_bf16 v[82:85], v[180:183], v[204:207], v[82:85]
	v_mfma_f32_16x16x32_bf16 v[66:69], v[180:183], v[212:215], v[66:69]
	v_mfma_f32_16x16x32_bf16 v[118:121], v[176:179], v[192:195], v[118:121]
	v_mfma_f32_16x16x32_bf16 v[102:105], v[176:179], v[200:203], v[102:105]
	v_mfma_f32_16x16x32_bf16 v[86:89], v[176:179], v[208:211], v[86:89]
	v_mfma_f32_16x16x32_bf16 v[70:73], v[176:179], v[216:219], v[70:73]
	v_mfma_f32_16x16x32_bf16 v[114:117], v[184:187], v[192:195], v[114:117]
	v_mfma_f32_16x16x32_bf16 v[98:101], v[184:187], v[200:203], v[98:101]
	v_mfma_f32_16x16x32_bf16 v[82:85], v[184:187], v[208:211], v[82:85]
	v_mfma_f32_16x16x32_bf16 v[66:69], v[184:187], v[216:219], v[66:69]
	s_setprio 0
	s_barrier
; #define PG8_STAGE(bufoff, gbase, voff) do { _Pragma("unroll") for (int _i = 0; _i < 2; ++_i) \
;         __builtin_amdgcn_global_load_lds((const unsigned*)((const char*)(gbase) + (voff)[_i]), (LAS unsigned*)(lds + (bufoff) + ldsw + _i * 8192), 16, 0, 0); } while (0)
; #define PG8_LDA(dst, b, h) do { _Pragma("unroll") for (int m = 0; m < 4; ++m) _Pragma("unroll") for (int k = 0; k < 2; ++k) dst[m][k] = *(const LAS bf16x8*)(lds + PG8_SA(b, h) + aoff + m * 2048 + k * 1024); } while (0)
; #define PG8_LDB(dst, b, h) do { _Pragma("unroll") for (int n = 0; n < 2; ++n) _Pragma("unroll") for (int k = 0; k < 2; ++k) dst[n][k] = *(const LAS bf16x8*)(lds + PG8_SB(b, h) + boff + n * 2048 + k * 1024); } while (0)
; #define PG8_MMA(ai, bj, At, Bt) do { __builtin_amdgcn_s_setprio(1); _Pragma("unroll") for (int m = 0; m < 4; ++m) _Pragma("unroll") for (int n = 0; n < 2; ++n) _Pragma("unroll") for (int k = 0; k < 2; ++k) \
;         acc[ai][bj][m][n] = __builtin_amdgcn_mfma_f32_16x16x32_bf16(Bt[n][k], At[m][k], acc[ai][bj][m][n], 0, 0, 0); __builtin_amdgcn_s_setprio(0); } while (0)
; #define PG8_WAIT_V(n) asm volatile("s_waitcnt vmcnt(" #n ")" ::: "memory")
; #define PG8_BAR __builtin_amdgcn_s_barrier()
; template <class Epi, bool ALIGN_EPI, bool SPLITA>
; __device__ __forceinline__ void gemm_phase(LAS unsigned char* lds, const Gemm g, const StaticOrder& S, const Epi& E) {
;     ...
;             PG8_LDB(B0, 0, 0); PG8_LDB(B1, 0, 1); PG8_SCHED; PG8_LDA(At, 0, 0); PG8_STAGE(PG8_SA(1, 1), a1h, vo1);
;             PG8_WAIT_V(8); PG8_WAIT_L(0); PG8_BAR; PG8_MMA(0, 0, At, B0); PG8_MMA(0, 1, At, B1); PG8_BAR; PG8_SCHED;
;             PG8_LDA(At, 0, 1); PG8_STAGE(PG8_SB(0, 0), b2, voffB); PG8_STAGE(PG8_SB(0, 1), b2 + hstepB, voffB); PG8_STAGE(PG8_SA(0, 0), a2, vo2);
;             PG8_WAIT_V(8); PG8_WAIT_L(0); PG8_BAR; PG8_MMA(1, 0, At, B0); PG8_MMA(1, 1, At, B1); PG8_BAR; PG8_SCHED;
;             PG8_LDB(B0, 1, 0); PG8_LDB(B1, 1, 1); PG8_SCHED; PG8_LDA(At, 1, 0); PG8_STAGE(PG8_SA(0, 1), a2h, vo2);
;             PG8_WAIT_V(8); PG8_WAIT_L(0); PG8_BAR; PG8_MMA(0, 0, At, B0); PG8_MMA(0, 1, At, B1); PG8_BAR; PG8_SCHED;
;             PG8_LDA(At, 1, 1); PG8_STAGE(PG8_SB(1, 0), b3, voffB); PG8_STAGE(PG8_SB(1, 1), b3 + hstepB, voffB); PG8_STAGE(PG8_SA(1, 0), a3, vo2);
;             PG8_WAIT_V(8); PG8_WAIT_L(0); PG8_BAR; PG8_MMA(1, 0, At, B0); PG8_MMA(1, 1, At, B1); PG8_BAR; PG8_SCHED;
	s_add_i32 s46, s89, s33
	s_mov_b32 m0, s46
	ds_read_b128 v[188:191], v154 offset:49152
	ds_read_b128 v[192:195], v154 offset:50176
	ds_read_b128 v[196:199], v154 offset:51200
	ds_read_b128 v[200:203], v154 offset:52224
	ds_read_b128 v[204:207], v154 offset:53248
	ds_read_b128 v[208:211], v154 offset:54272
	ds_read_b128 v[212:215], v154 offset:55296
	ds_read_b128 v[216:219], v154 offset:56320
	global_load_lds_dwordx4 v134, s[98:99]
	s_add_i32 m0, s46, 0x2000
	s_add_u32 s44, s44, 0x200080
	s_addc_u32 s45, s45, 0
	s_add_i32 s46, s92, s33
	global_load_lds_dwordx4 v130, s[98:99]
	s_mov_b32 m0, s46
	s_nop 0
	global_load_lds_dwordx4 v134, s[44:45]
	s_add_i32 m0, s46, 0x2000
	s_nop 0
	global_load_lds_dwordx4 v130, s[44:45]
	s_mov_b32 m0, s72
	s_nop 0
	global_load_lds_dwordx4 v136, s[100:101]
	s_mov_b32 m0, s73
	s_nop 0
	global_load_lds_dwordx4 v132, s[100:101]
	s_waitcnt vmcnt(8)
	s_waitcnt lgkmcnt(0)
	s_barrier
	s_setprio 1
	s_waitcnt lgkmcnt(0)
	v_mfma_f32_16x16x32_bf16 v[54:57], v[146:149], v[188:191], v[54:57]
	v_mfma_f32_16x16x32_bf16 v[22:25], v[146:149], v[196:199], v[22:25]
	v_mfma_f32_16x16x32_bf16 v[14:17], v[146:149], v[204:207], v[14:17]
	v_mfma_f32_16x16x32_bf16 v[6:9], v[146:149], v[212:215], v[6:9]
	v_mfma_f32_16x16x32_bf16 v[50:53], v[164:167], v[188:191], v[50:53]
	v_mfma_f32_16x16x32_bf16 v[18:21], v[164:167], v[196:199], v[18:21]
	v_mfma_f32_16x16x32_bf16 v[10:13], v[164:167], v[204:207], v[10:13]
	v_mfma_f32_16x16x32_bf16 v[2:5], v[164:167], v[212:215], v[2:5]
	v_mfma_f32_16x16x32_bf16 v[54:57], v[156:159], v[192:195], v[54:57]
	v_mfma_f32_16x16x32_bf16 v[22:25], v[156:159], v[200:203], v[22:25]
	v_mfma_f32_16x16x32_bf16 v[14:17], v[156:159], v[208:211], v[14:17]
	v_mfma_f32_16x16x32_bf16 v[6:9], v[156:159], v[216:219], v[6:9]
	v_mfma_f32_16x16x32_bf16 v[50:53], v[168:171], v[192:195], v[50:53]
	v_mfma_f32_16x16x32_bf16 v[18:21], v[168:171], v[200:203], v[18:21]
	v_mfma_f32_16x16x32_bf16 v[10:13], v[168:171], v[208:211], v[10:13]
	v_mfma_f32_16x16x32_bf16 v[2:5], v[168:171], v[216:219], v[2:5]
	s_setprio 0
	s_setprio 1
	v_mfma_f32_16x16x32_bf16 v[38:41], v[172:175], v[188:191], v[38:41]
	v_mfma_f32_16x16x32_bf16 v[58:61], v[172:175], v[196:199], v[58:61]
	v_mfma_f32_16x16x32_bf16 v[42:45], v[172:175], v[204:207], v[42:45]
	v_mfma_f32_16x16x32_bf16 v[26:29], v[172:175], v[212:215], v[26:29]
	v_mfma_f32_16x16x32_bf16 v[34:37], v[180:183], v[188:191], v[34:37]
	v_mfma_f32_16x16x32_bf16 v[62:65], v[180:183], v[196:199], v[62:65]
	v_mfma_f32_16x16x32_bf16 v[46:49], v[180:183], v[204:207], v[46:49]
	v_mfma_f32_16x16x32_bf16 v[30:33], v[180:183], v[212:215], v[30:33]
	v_mfma_f32_16x16x32_bf16 v[38:41], v[176:179], v[192:195], v[38:41]
	v_mfma_f32_16x16x32_bf16 v[58:61], v[176:179], v[200:203], v[58:61]
	v_mfma_f32_16x16x32_bf16 v[42:45], v[176:179], v[208:211], v[42:45]
	v_mfma_f32_16x16x32_bf16 v[26:29], v[176:179], v[216:219], v[26:29]
	v_mfma_f32_16x16x32_bf16 v[34:37], v[184:187], v[192:195], v[34:37]
	v_mfma_f32_16x16x32_bf16 v[62:65], v[184:187], v[200:203], v[62:65]
	v_mfma_f32_16x16x32_bf16 v[46:49], v[184:187], v[208:211], v[46:49]
	v_mfma_f32_16x16x32_bf16 v[30:33], v[184:187], v[216:219], v[30:33]
	s_setprio 0
	s_barrier
	s_add_i32 s91, s91, 2
	s_add_u32 s0, s0, 0x100
	s_addc_u32 s1, s1, 0
	s_add_u32 s29, s29, 0x100
	s_addc_u32 s90, s90, 0
.LBB0_265:
	ds_read_b128 v[146:149], v152
	ds_read_b128 v[156:159], v152 offset:1024
	ds_read_b128 v[164:167], v152 offset:2048
	ds_read_b128 v[168:171], v152 offset:3072
	ds_read_b128 v[172:175], v153
	ds_read_b128 v[176:179], v153 offset:1024
	ds_read_b128 v[180:183], v153 offset:2048
	ds_read_b128 v[184:187], v153 offset:3072
	s_add_u32 s44, s0, 0xfffc0080
	s_addc_u32 s45, s1, -1
	s_cmp_eq_u32 s91, 12
	s_cselect_b32 s47, s13, s45
	s_cselect_b32 s46, s27, s44
	s_cselect_b32 s45, s39, s90
	s_cselect_b32 s44, s38, s29
	s_add_i32 m0, s43, 0xc000
	ds_read_b128 v[188:191], v154
	ds_read_b128 v[192:195], v154 offset:1024
	ds_read_b128 v[196:199], v154 offset:2048
	ds_read_b128 v[200:203], v154 offset:3072
	ds_read_b128 v[204:207], v154 offset:4096
	ds_read_b128 v[208:211], v154 offset:5120
	ds_read_b128 v[212:215], v154 offset:6144
	ds_read_b128 v[216:219], v154 offset:7168
	global_load_lds_dwordx4 v138, s[0:1]
	s_add_i32 m0, s43, 0xe000
	s_nop 0
	global_load_lds_dwordx4 v140, s[0:1]
	s_waitcnt vmcnt(8)
	s_waitcnt lgkmcnt(0)
	s_barrier
	s_setprio 1
	s_waitcnt lgkmcnt(0)
	v_mfma_f32_16x16x32_bf16 v[126:129], v[146:149], v[188:191], v[126:129]
	v_mfma_f32_16x16x32_bf16 v[110:113], v[146:149], v[196:199], v[110:113]
	v_mfma_f32_16x16x32_bf16 v[94:97], v[146:149], v[204:207], v[94:97]
	v_mfma_f32_16x16x32_bf16 v[78:81], v[146:149], v[212:215], v[78:81]
	v_mfma_f32_16x16x32_bf16 v[122:125], v[164:167], v[188:191], v[122:125]
	v_mfma_f32_16x16x32_bf16 v[106:109], v[164:167], v[196:199], v[106:109]
	v_mfma_f32_16x16x32_bf16 v[90:93], v[164:167], v[204:207], v[90:93]
	v_mfma_f32_16x16x32_bf16 v[74:77], v[164:167], v[212:215], v[74:77]
	v_mfma_f32_16x16x32_bf16 v[126:129], v[156:159], v[192:195], v[126:129]
	v_mfma_f32_16x16x32_bf16 v[110:113], v[156:159], v[200:203], v[110:113]
	v_mfma_f32_16x16x32_bf16 v[94:97], v[156:159], v[208:211], v[94:97]
	v_mfma_f32_16x16x32_bf16 v[78:81], v[156:159], v[216:219], v[78:81]
	v_mfma_f32_16x16x32_bf16 v[122:125], v[168:171], v[192:195], v[122:125]
	v_mfma_f32_16x16x32_bf16 v[106:109], v[168:171], v[200:203], v[106:109]
	v_mfma_f32_16x16x32_bf16 v[90:93], v[168:171], v[208:211], v[90:93]
	v_mfma_f32_16x16x32_bf16 v[74:77], v[168:171], v[216:219], v[74:77]
	s_setprio 0
	s_setprio 1
	v_mfma_f32_16x16x32_bf16 v[118:121], v[172:175], v[188:191], v[118:121]
	v_mfma_f32_16x16x32_bf16 v[102:105], v[172:175], v[196:199], v[102:105]
	v_mfma_f32_16x16x32_bf16 v[86:89], v[172:175], v[204:207], v[86:89]
	v_mfma_f32_16x16x32_bf16 v[70:73], v[172:175], v[212:215], v[70:73]
	v_mfma_f32_16x16x32_bf16 v[114:117], v[180:183], v[188:191], v[114:117]
	v_mfma_f32_16x16x32_bf16 v[98:101], v[180:183], v[196:199], v[98:101]
	v_mfma_f32_16x16x32_bf16 v[82:85], v[180:183], v[204:207], v[82:85]
	v_mfma_f32_16x16x32_bf16 v[66:69], v[180:183], v[212:215], v[66:69]
	v_mfma_f32_16x16x32_bf16 v[118:121], v[176:179], v[192:195], v[118:121]
	v_mfma_f32_16x16x32_bf16 v[102:105], v[176:179], v[200:203], v[102:105]
	v_mfma_f32_16x16x32_bf16 v[86:89], v[176:179], v[208:211], v[86:89]
	v_mfma_f32_16x16x32_bf16 v[70:73], v[176:179], v[216:219], v[70:73]
	v_mfma_f32_16x16x32_bf16 v[114:117], v[184:187], v[192:195], v[114:117]
	v_mfma_f32_16x16x32_bf16 v[98:101], v[184:187], v[200:203], v[98:101]
	v_mfma_f32_16x16x32_bf16 v[82:85], v[184:187], v[208:211], v[82:85]
	v_mfma_f32_16x16x32_bf16 v[66:69], v[184:187], v[216:219], v[66:69]
	s_setprio 0
	s_barrier
; #define PG8_STAGE(bufoff, gbase, voff) do { _Pragma("unroll") for (int _i = 0; _i < 2; ++_i) \
;         __builtin_amdgcn_global_load_lds((const unsigned*)((const char*)(gbase) + (voff)[_i]), (LAS unsigned*)(lds + (bufoff) + ldsw + _i * 8192), 16, 0, 0); } while (0)
; #define PG8_LDA(dst, b, h) do { _Pragma("unroll") for (int m = 0; m < 4; ++m) _Pragma("unroll") for (int k = 0; k < 2; ++k) dst[m][k] = *(const LAS bf16x8*)(lds + PG8_SA(b, h) + aoff + m * 2048 + k * 1024); } while (0)
; #define PG8_LDB(dst, b, h) do { _Pragma("unroll") for (int n = 0; n < 2; ++n) _Pragma("unroll") for (int k = 0; k < 2; ++k) dst[n][k] = *(const LAS bf16x8*)(lds + PG8_SB(b, h) + boff + n * 2048 + k * 1024); } while (0)
; #define PG8_MMA(ai, bj, At, Bt) do { __builtin_amdgcn_s_setprio(1); _Pragma("unroll") for (int m = 0; m < 4; ++m) _Pragma("unroll") for (int n = 0; n < 2; ++n) _Pragma("unroll") for (int k = 0; k < 2; ++k) \
;         acc[ai][bj][m][n] = __builtin_amdgcn_mfma_f32_16x16x32_bf16(Bt[n][k], At[m][k], acc[ai][bj][m][n], 0, 0, 0); __builtin_amdgcn_s_setprio(0); } while (0)
; #define PG8_WAIT_V(n) asm volatile("s_waitcnt vmcnt(" #n ")" ::: "memory")
; #define PG8_WAIT_L(n) asm volatile("s_waitcnt lgkmcnt(" #n ")" ::: "memory")
; #define PG8_BAR __builtin_amdgcn_s_barrier()
; #define PG8_SCHED __builtin_amdgcn_sched_barrier(0)
; template <class Epi, bool ALIGN_EPI, bool SPLITA>
; __device__ __forceinline__ void gemm_phase(LAS unsigned char* lds, const Gemm g, const StaticOrder& S, const Epi& E) {
;     ...
;             PG8_LDA(At, 0, 1); PG8_STAGE(PG8_SB(0, 0), b2, voffB); PG8_STAGE(PG8_SB(0, 1), b2 + hstepB, voffB); PG8_STAGE(PG8_SA(0, 0), a2, vo2);
;             PG8_WAIT_V(8); PG8_WAIT_L(0); PG8_BAR; PG8_MMA(1, 0, At, B0); PG8_MMA(1, 1, At, B1); PG8_BAR; PG8_SCHED;
;             PG8_LDB(B0, 1, 0); PG8_LDB(B1, 1, 1); PG8_SCHED; PG8_LDA(At, 1, 0); PG8_STAGE(PG8_SA(0, 1), a2h, vo2);
;             PG8_WAIT_V(8); PG8_WAIT_L(0); PG8_BAR; PG8_MMA(0, 0, At, B0); PG8_MMA(0, 1, At, B1); PG8_BAR; PG8_SCHED;
	s_add_u32 s98, s44, s8
	s_addc_u32 s99, s45, s9
	s_add_u32 s100, s46, s8
	s_addc_u32 s101, s47, s9
	s_add_i32 s89, s79, s33
	s_mov_b32 m0, s89
	ds_read_b128 v[188:191], v154 offset:16384
	ds_read_b128 v[192:195], v154 offset:17408
	ds_read_b128 v[196:199], v154 offset:18432
	ds_read_b128 v[200:203], v154 offset:19456
	ds_read_b128 v[204:207], v154 offset:20480
	ds_read_b128 v[208:211], v154 offset:21504
	ds_read_b128 v[212:215], v154 offset:22528
	ds_read_b128 v[216:219], v154 offset:23552
	global_load_lds_dwordx4 v134, s[44:45]
	s_add_i32 m0, s89, 0x2000
	s_add_u32 s92, s44, 0x200000
	s_addc_u32 s93, s45, 0
	s_add_i32 s89, s80, s33
	global_load_lds_dwordx4 v130, s[44:45]
	s_mov_b32 m0, s89
	s_nop 0
	global_load_lds_dwordx4 v134, s[92:93]
	s_add_i32 m0, s89, 0x2000
	s_nop 0
	global_load_lds_dwordx4 v130, s[92:93]
	s_mov_b32 m0, s43
	s_nop 0
	global_load_lds_dwordx4 v136, s[46:47]
	s_mov_b32 m0, s60
	s_nop 0
	global_load_lds_dwordx4 v132, s[46:47]
	s_waitcnt vmcnt(8)
	s_waitcnt lgkmcnt(0)
	s_barrier
	s_setprio 1
	s_waitcnt lgkmcnt(0)
	v_mfma_f32_16x16x32_bf16 v[54:57], v[146:149], v[188:191], v[54:57]
	v_mfma_f32_16x16x32_bf16 v[22:25], v[146:149], v[196:199], v[22:25]
	v_mfma_f32_16x16x32_bf16 v[14:17], v[146:149], v[204:207], v[14:17]
	v_mfma_f32_16x16x32_bf16 v[6:9], v[146:149], v[212:215], v[6:9]
	v_mfma_f32_16x16x32_bf16 v[50:53], v[164:167], v[188:191], v[50:53]
	v_mfma_f32_16x16x32_bf16 v[18:21], v[164:167], v[196:199], v[18:21]
	v_mfma_f32_16x16x32_bf16 v[10:13], v[164:167], v[204:207], v[10:13]
	v_mfma_f32_16x16x32_bf16 v[2:5], v[164:167], v[212:215], v[2:5]
	v_mfma_f32_16x16x32_bf16 v[54:57], v[156:159], v[192:195], v[54:57]
	v_mfma_f32_16x16x32_bf16 v[22:25], v[156:159], v[200:203], v[22:25]
	v_mfma_f32_16x16x32_bf16 v[14:17], v[156:159], v[208:211], v[14:17]
	v_mfma_f32_16x16x32_bf16 v[6:9], v[156:159], v[216:219], v[6:9]
	v_mfma_f32_16x16x32_bf16 v[50:53], v[168:171], v[192:195], v[50:53]
	v_mfma_f32_16x16x32_bf16 v[18:21], v[168:171], v[200:203], v[18:21]
	v_mfma_f32_16x16x32_bf16 v[10:13], v[168:171], v[208:211], v[10:13]
	v_mfma_f32_16x16x32_bf16 v[2:5], v[168:171], v[216:219], v[2:5]
	s_setprio 0
	s_setprio 1
	v_mfma_f32_16x16x32_bf16 v[38:41], v[172:175], v[188:191], v[38:41]
	v_mfma_f32_16x16x32_bf16 v[58:61], v[172:175], v[196:199], v[58:61]
	v_mfma_f32_16x16x32_bf16 v[42:45], v[172:175], v[204:207], v[42:45]
	v_mfma_f32_16x16x32_bf16 v[26:29], v[172:175], v[212:215], v[26:29]
	v_mfma_f32_16x16x32_bf16 v[34:37], v[180:183], v[188:191], v[34:37]
	v_mfma_f32_16x16x32_bf16 v[62:65], v[180:183], v[196:199], v[62:65]
	v_mfma_f32_16x16x32_bf16 v[46:49], v[180:183], v[204:207], v[46:49]
	v_mfma_f32_16x16x32_bf16 v[30:33], v[180:183], v[212:215], v[30:33]
	v_mfma_f32_16x16x32_bf16 v[38:41], v[176:179], v[192:195], v[38:41]
	v_mfma_f32_16x16x32_bf16 v[58:61], v[176:179], v[200:203], v[58:61]
	v_mfma_f32_16x16x32_bf16 v[42:45], v[176:179], v[208:211], v[42:45]
	v_mfma_f32_16x16x32_bf16 v[26:29], v[176:179], v[216:219], v[26:29]
	v_mfma_f32_16x16x32_bf16 v[34:37], v[184:187], v[192:195], v[34:37]
	v_mfma_f32_16x16x32_bf16 v[62:65], v[184:187], v[200:203], v[62:65]
	v_mfma_f32_16x16x32_bf16 v[46:49], v[184:187], v[208:211], v[46:49]
	v_mfma_f32_16x16x32_bf16 v[30:33], v[184:187], v[216:219], v[30:33]
	s_setprio 0
	s_barrier
	s_add_i32 s89, 0, 0x18000
	v_add_u32_e32 v155, s89, v150
	s_add_i32 s92, 0, 0x1c000
	ds_read_b128 v[146:149], v155
	ds_read_b128 v[156:159], v155 offset:1024
	ds_read_b128 v[164:167], v155 offset:2048
	ds_read_b128 v[168:171], v155 offset:3072
	v_add_u32_e32 v155, s92, v150
	ds_read_b128 v[172:175], v155
	ds_read_b128 v[176:179], v155 offset:1024
	ds_read_b128 v[180:183], v155 offset:2048
	ds_read_b128 v[184:187], v155 offset:3072
	s_add_u32 s46, s46, 0x40000
	s_addc_u32 s47, s47, 0
	s_mov_b32 m0, s61
	ds_read_b128 v[188:191], v154 offset:32768
	ds_read_b128 v[192:195], v154 offset:33792
	ds_read_b128 v[196:199], v154 offset:34816
	ds_read_b128 v[200:203], v154 offset:35840
	ds_read_b128 v[204:207], v154 offset:36864
	ds_read_b128 v[208:211], v154 offset:37888
	ds_read_b128 v[212:215], v154 offset:38912
	ds_read_b128 v[216:219], v154 offset:39936
	global_load_lds_dwordx4 v136, s[46:47]
	s_mov_b32 m0, s64
	s_nop 0
	global_load_lds_dwordx4 v132, s[46:47]
	s_waitcnt vmcnt(8)
	s_waitcnt lgkmcnt(0)
	s_barrier
; #define PG8_STAGE(bufoff, gbase, voff) do { _Pragma("unroll") for (int _i = 0; _i < 2; ++_i) \
;         __builtin_amdgcn_global_load_lds((const unsigned*)((const char*)(gbase) + (voff)[_i]), (LAS unsigned*)(lds + (bufoff) + ldsw + _i * 8192), 16, 0, 0); } while (0)
; #define PG8_LDA(dst, b, h) do { _Pragma("unroll") for (int m = 0; m < 4; ++m) _Pragma("unroll") for (int k = 0; k < 2; ++k) dst[m][k] = *(const LAS bf16x8*)(lds + PG8_SA(b, h) + aoff + m * 2048 + k * 1024); } while (0)
; #define PG8_MMA(ai, bj, At, Bt) do { __builtin_amdgcn_s_setprio(1); _Pragma("unroll") for (int m = 0; m < 4; ++m) _Pragma("unroll") for (int n = 0; n < 2; ++n) _Pragma("unroll") for (int k = 0; k < 2; ++k) \
;         acc[ai][bj][m][n] = __builtin_amdgcn_mfma_f32_16x16x32_bf16(Bt[n][k], At[m][k], acc[ai][bj][m][n], 0, 0, 0); __builtin_amdgcn_s_setprio(0); } while (0)
; #define PG8_WAIT_V(n) asm volatile("s_waitcnt vmcnt(" #n ")" ::: "memory")
; #define PG8_WAIT_L(n) asm volatile("s_waitcnt lgkmcnt(" #n ")" ::: "memory")
; #define PG8_BAR __builtin_amdgcn_s_barrier()
; #define PG8_SCHED __builtin_amdgcn_sched_barrier(0)
; template <class Epi, bool ALIGN_EPI, bool SPLITA>
; __device__ __forceinline__ void gemm_phase(LAS unsigned char* lds, const Gemm g, const StaticOrder& S, const Epi& E) {
;     ...
;             PG8_WAIT_V(8); PG8_WAIT_L(0); PG8_BAR; PG8_MMA(0, 0, At, B0); PG8_MMA(0, 1, At, B1); PG8_BAR; PG8_SCHED;
;             PG8_LDA(At, 1, 1); PG8_STAGE(PG8_SB(1, 0), b3, voffB); PG8_STAGE(PG8_SB(1, 1), b3 + hstepB, voffB); PG8_STAGE(PG8_SA(1, 0), a3, vo2);
;             PG8_WAIT_V(8); PG8_WAIT_L(0); PG8_BAR; PG8_MMA(1, 0, At, B0); PG8_MMA(1, 1, At, B1); PG8_BAR; PG8_SCHED;
;         }
;         if constexpr (ALIGN_EPI) { if (wr == 0) PG8_BAR; }
	s_setprio 1
	s_waitcnt lgkmcnt(0)
	v_mfma_f32_16x16x32_bf16 v[126:129], v[146:149], v[188:191], v[126:129]
	v_mfma_f32_16x16x32_bf16 v[110:113], v[146:149], v[196:199], v[110:113]
	v_mfma_f32_16x16x32_bf16 v[94:97], v[146:149], v[204:207], v[94:97]
	v_mfma_f32_16x16x32_bf16 v[78:81], v[146:149], v[212:215], v[78:81]
	v_mfma_f32_16x16x32_bf16 v[122:125], v[164:167], v[188:191], v[122:125]
	v_mfma_f32_16x16x32_bf16 v[106:109], v[164:167], v[196:199], v[106:109]
	v_mfma_f32_16x16x32_bf16 v[90:93], v[164:167], v[204:207], v[90:93]
	v_mfma_f32_16x16x32_bf16 v[74:77], v[164:167], v[212:215], v[74:77]
	v_mfma_f32_16x16x32_bf16 v[126:129], v[156:159], v[192:195], v[126:129]
	v_mfma_f32_16x16x32_bf16 v[110:113], v[156:159], v[200:203], v[110:113]
	v_mfma_f32_16x16x32_bf16 v[94:97], v[156:159], v[208:211], v[94:97]
	v_mfma_f32_16x16x32_bf16 v[78:81], v[156:159], v[216:219], v[78:81]
	v_mfma_f32_16x16x32_bf16 v[122:125], v[168:171], v[192:195], v[122:125]
	v_mfma_f32_16x16x32_bf16 v[106:109], v[168:171], v[200:203], v[106:109]
	v_mfma_f32_16x16x32_bf16 v[90:93], v[168:171], v[208:211], v[90:93]
	v_mfma_f32_16x16x32_bf16 v[74:77], v[168:171], v[216:219], v[74:77]
	s_setprio 0
	s_setprio 1
	v_mfma_f32_16x16x32_bf16 v[118:121], v[172:175], v[188:191], v[118:121]
	v_mfma_f32_16x16x32_bf16 v[102:105], v[172:175], v[196:199], v[102:105]
	v_mfma_f32_16x16x32_bf16 v[86:89], v[172:175], v[204:207], v[86:89]
	v_mfma_f32_16x16x32_bf16 v[70:73], v[172:175], v[212:215], v[70:73]
	v_mfma_f32_16x16x32_bf16 v[114:117], v[180:183], v[188:191], v[114:117]
	v_mfma_f32_16x16x32_bf16 v[98:101], v[180:183], v[196:199], v[98:101]
	v_mfma_f32_16x16x32_bf16 v[82:85], v[180:183], v[204:207], v[82:85]
	v_mfma_f32_16x16x32_bf16 v[66:69], v[180:183], v[212:215], v[66:69]
	v_mfma_f32_16x16x32_bf16 v[118:121], v[176:179], v[192:195], v[118:121]
	v_mfma_f32_16x16x32_bf16 v[102:105], v[176:179], v[200:203], v[102:105]
	v_mfma_f32_16x16x32_bf16 v[86:89], v[176:179], v[208:211], v[86:89]
	v_mfma_f32_16x16x32_bf16 v[70:73], v[176:179], v[216:219], v[70:73]
	v_mfma_f32_16x16x32_bf16 v[114:117], v[184:187], v[192:195], v[114:117]
	v_mfma_f32_16x16x32_bf16 v[98:101], v[184:187], v[200:203], v[98:101]
	v_mfma_f32_16x16x32_bf16 v[82:85], v[184:187], v[208:211], v[82:85]
	v_mfma_f32_16x16x32_bf16 v[66:69], v[184:187], v[216:219], v[66:69]
	s_setprio 0
	s_barrier
	s_add_i32 s46, s89, s33
	s_mov_b32 m0, s46
	ds_read_b128 v[188:191], v154 offset:49152
	ds_read_b128 v[192:195], v154 offset:50176
	ds_read_b128 v[196:199], v154 offset:51200
	ds_read_b128 v[200:203], v154 offset:52224
	ds_read_b128 v[204:207], v154 offset:53248
	ds_read_b128 v[208:211], v154 offset:54272
	ds_read_b128 v[212:215], v154 offset:55296
	ds_read_b128 v[216:219], v154 offset:56320
	global_load_lds_dwordx4 v134, s[98:99]
	s_add_i32 m0, s46, 0x2000
	s_add_u32 s44, s44, 0x200080
	s_addc_u32 s45, s45, 0
	s_add_i32 s46, s92, s33
	global_load_lds_dwordx4 v130, s[98:99]
	s_mov_b32 m0, s46
	s_nop 0
	global_load_lds_dwordx4 v134, s[44:45]
	s_add_i32 m0, s46, 0x2000
	s_nop 0
	global_load_lds_dwordx4 v130, s[44:45]
	s_mov_b32 m0, s72
	s_nop 0
	global_load_lds_dwordx4 v136, s[100:101]
	s_mov_b32 m0, s73
	s_nop 0
	global_load_lds_dwordx4 v132, s[100:101]
	s_waitcnt vmcnt(8)
	s_waitcnt lgkmcnt(0)
	s_barrier
	s_setprio 1
	s_waitcnt lgkmcnt(0)
	v_mfma_f32_16x16x32_bf16 v[54:57], v[146:149], v[188:191], v[54:57]
	v_mfma_f32_16x16x32_bf16 v[22:25], v[146:149], v[196:199], v[22:25]
	v_mfma_f32_16x16x32_bf16 v[14:17], v[146:149], v[204:207], v[14:17]
	v_mfma_f32_16x16x32_bf16 v[6:9], v[146:149], v[212:215], v[6:9]
	v_mfma_f32_16x16x32_bf16 v[50:53], v[164:167], v[188:191], v[50:53]
	v_mfma_f32_16x16x32_bf16 v[18:21], v[164:167], v[196:199], v[18:21]
	v_mfma_f32_16x16x32_bf16 v[10:13], v[164:167], v[204:207], v[10:13]
	v_mfma_f32_16x16x32_bf16 v[2:5], v[164:167], v[212:215], v[2:5]
	v_mfma_f32_16x16x32_bf16 v[54:57], v[156:159], v[192:195], v[54:57]
	v_mfma_f32_16x16x32_bf16 v[22:25], v[156:159], v[200:203], v[22:25]
	v_mfma_f32_16x16x32_bf16 v[14:17], v[156:159], v[208:211], v[14:17]
	v_mfma_f32_16x16x32_bf16 v[6:9], v[156:159], v[216:219], v[6:9]
	v_mfma_f32_16x16x32_bf16 v[50:53], v[168:171], v[192:195], v[50:53]
	v_mfma_f32_16x16x32_bf16 v[18:21], v[168:171], v[200:203], v[18:21]
	v_mfma_f32_16x16x32_bf16 v[10:13], v[168:171], v[208:211], v[10:13]
	v_mfma_f32_16x16x32_bf16 v[2:5], v[168:171], v[216:219], v[2:5]
	s_setprio 0
	s_setprio 1
	v_mfma_f32_16x16x32_bf16 v[38:41], v[172:175], v[188:191], v[38:41]
	v_mfma_f32_16x16x32_bf16 v[58:61], v[172:175], v[196:199], v[58:61]
	v_mfma_f32_16x16x32_bf16 v[42:45], v[172:175], v[204:207], v[42:45]
	v_mfma_f32_16x16x32_bf16 v[26:29], v[172:175], v[212:215], v[26:29]
	v_mfma_f32_16x16x32_bf16 v[34:37], v[180:183], v[188:191], v[34:37]
	v_mfma_f32_16x16x32_bf16 v[62:65], v[180:183], v[196:199], v[62:65]
	v_mfma_f32_16x16x32_bf16 v[46:49], v[180:183], v[204:207], v[46:49]
	v_mfma_f32_16x16x32_bf16 v[30:33], v[180:183], v[212:215], v[30:33]
	v_mfma_f32_16x16x32_bf16 v[38:41], v[176:179], v[192:195], v[38:41]
	v_mfma_f32_16x16x32_bf16 v[58:61], v[176:179], v[200:203], v[58:61]
	v_mfma_f32_16x16x32_bf16 v[42:45], v[176:179], v[208:211], v[42:45]
	v_mfma_f32_16x16x32_bf16 v[26:29], v[176:179], v[216:219], v[26:29]
	v_mfma_f32_16x16x32_bf16 v[34:37], v[184:187], v[192:195], v[34:37]
	v_mfma_f32_16x16x32_bf16 v[62:65], v[184:187], v[200:203], v[62:65]
	v_mfma_f32_16x16x32_bf16 v[46:49], v[184:187], v[208:211], v[46:49]
	v_mfma_f32_16x16x32_bf16 v[30:33], v[184:187], v[216:219], v[30:33]
	s_setprio 0
	s_barrier
	s_add_i32 s91, s91, 2
	s_add_u32 s0, s0, 0x100
	s_addc_u32 s1, s1, 0
	s_add_u32 s29, s29, 0x100
	s_addc_u32 s90, s90, 0
	s_cmp_gt_u32 s91, 13
	s_cbranch_scc0 .LBB0_265
	s_and_b64 vcc, exec, s[10:11]
	s_cbranch_vccz .LBB0_268
	s_barrier

; #define PG8_STAGE(bufoff, gbase, voff) do { _Pragma("unroll") for (int _i = 0; _i < 2; ++_i) \
;         __builtin_amdgcn_global_load_lds((const unsigned*)((const char*)(gbase) + (voff)[_i]), (LAS unsigned*)(lds + (bufoff) + ldsw + _i * 8192), 16, 0, 0); } while (0)
; #define PG8_WAIT_V(n) asm volatile("s_waitcnt vmcnt(" #n ")" ::: "memory")
; template <class Epi, bool ALIGN_EPI, bool SPLITA>
; __device__ __forceinline__ void gemm_phase(LAS unsigned char* lds, const Gemm g, const StaticOrder& S, const Epi& E) {
;     ...
;                 a1 = (t + 1 < g.ksplit) ? cA + (size_t)(t + 1) * kstep : cA2 + (size_t)(t + 1 - g.ksplit) * 2048;
;                 a2 = last ? nA : ((t + 2 < g.ksplit) ? cA + (size_t)(t + 2) * kstep : cA2 + (size_t)(t + 2 - g.ksplit) * 2048);
;             } else { a1 = cA + kofs(t + 1); a2 = last ? nA : cA + kofs(t + 2); }
;             const char* b2 = last ? nB : cB + (size_t)(t + 2) * kstepB;
;             const bool s2a = SPLITA && (t + 1 >= g.ksplit), s2b = SPLITA && !last && (t + 2 >= g.ksplit);
;             const char* a3 = a2 + ((Epi::KSUB || s2b) ? (size_t)2048 : kstep); const char* b3 = b2 + kstepB;
;             const bool m1 = SPLITA && mirC && (t + 1 < g.ksplit), m2 = SPLITA && (last ? mirN : (mirC && (t + 2 < g.ksplit)));
;             const unsigned vo1[2] = {s2a ? voffA2[0] : m1 ? voffAm[0] : voffA[0], s2a ? voffA2[1] : m1 ? voffAm[1] : voffA[1]}, vo2[2] = {s2b ? voffA2[0] : m2 ? voffAm[0] : voffA[0], s2b ? voffA2[1] : m2 ? voffAm[1] : voffA[1]};
;             const char* a1h = m1 ? a1 - hstepA : a1 + hstepA; const char* a2h = m2 ? a2 - hstepA : a2 + hstepA;
;             PG8_LDB(B0, 0, 0); PG8_LDB(B1, 0, 1); PG8_SCHED; PG8_LDA(At, 0, 0); PG8_STAGE(PG8_SA(1, 1), a1h, vo1);
;             PG8_WAIT_V(8); PG8_WAIT_L(0); PG8_BAR; PG8_MMA(0, 0, At, B0); PG8_MMA(0, 1, At, B1); PG8_BAR; PG8_SCHED;
;             PG8_LDA(At, 0, 1); PG8_STAGE(PG8_SB(0, 0), b2, voffB); PG8_STAGE(PG8_SB(0, 1), b2 + hstepB, voffB); PG8_STAGE(PG8_SA(0, 0), a2, vo2);
;             PG8_WAIT_V(8); PG8_WAIT_L(0); PG8_BAR; PG8_MMA(1, 0, At, B0); PG8_MMA(1, 1, At, B1); PG8_BAR; PG8_SCHED;
;             PG8_LDB(B0, 1, 0); PG8_LDB(B1, 1, 1); PG8_SCHED; PG8_LDA(At, 1, 0); PG8_STAGE(PG8_SA(0, 1), a2h, vo2);
;             PG8_WAIT_V(8); PG8_WAIT_L(0); PG8_BAR; PG8_MMA(0, 0, At, B0); PG8_MMA(0, 1, At, B1); PG8_BAR; PG8_SCHED;
.LBB0_414:
	s_add_u32 s48, s48, 0x40080
	s_addc_u32 s49, s49, 0
	s_add_u32 s5, s50, 0x100
	s_addc_u32 s11, s51, 0
	s_mov_b32 s31, -2
	ds_read_b128 v[146:149], v156
	ds_read_b128 v[150:153], v156 offset:1024
	ds_read_b128 v[160:163], v156 offset:2048
	ds_read_b128 v[164:167], v156 offset:3072
	ds_read_b128 v[168:171], v157
	ds_read_b128 v[172:175], v157 offset:1024
	ds_read_b128 v[176:179], v157 offset:2048
	ds_read_b128 v[180:183], v157 offset:3072
	s_add_u32 s12, s48, 0xfffc0080
	s_addc_u32 s13, s49, -1
	s_cmp_eq_u32 s31, 12
	s_cselect_b32 s53, s1, s13
	s_cselect_b32 s52, s0, s12
	s_cselect_b32 s51, s47, s11
	s_cselect_b32 s50, s46, s5
	s_add_i32 m0, s54, 0xc000
	ds_read_b128 v[184:187], v158
	ds_read_b128 v[188:191], v158 offset:1024
	ds_read_b128 v[192:195], v158 offset:2048
	ds_read_b128 v[196:199], v158 offset:3072
	ds_read_b128 v[200:203], v158 offset:4096
	ds_read_b128 v[204:207], v158 offset:5120
	ds_read_b128 v[208:211], v158 offset:6144
	ds_read_b128 v[212:215], v158 offset:7168
	global_load_lds_dwordx4 v138, s[48:49]
	s_add_i32 m0, s54, 0xe000
	s_nop 0
	global_load_lds_dwordx4 v140, s[48:49]
	s_waitcnt vmcnt(8)
	s_waitcnt lgkmcnt(0)
	s_barrier
	s_setprio 1
	s_waitcnt lgkmcnt(0)
	v_mfma_f32_16x16x32_bf16 v[126:129], v[146:149], v[184:187], 0
	v_mfma_f32_16x16x32_bf16 v[110:113], v[146:149], v[192:195], 0
	v_mfma_f32_16x16x32_bf16 v[94:97], v[146:149], v[200:203], 0
	v_mfma_f32_16x16x32_bf16 v[78:81], v[146:149], v[208:211], 0
	v_mfma_f32_16x16x32_bf16 v[122:125], v[160:163], v[184:187], 0
	v_mfma_f32_16x16x32_bf16 v[106:109], v[160:163], v[192:195], 0
	v_mfma_f32_16x16x32_bf16 v[90:93], v[160:163], v[200:203], 0
	v_mfma_f32_16x16x32_bf16 v[74:77], v[160:163], v[208:211], 0
	v_mfma_f32_16x16x32_bf16 v[126:129], v[150:153], v[188:191], v[126:129]
	v_mfma_f32_16x16x32_bf16 v[110:113], v[150:153], v[196:199], v[110:113]
	v_mfma_f32_16x16x32_bf16 v[94:97], v[150:153], v[204:207], v[94:97]
	v_mfma_f32_16x16x32_bf16 v[78:81], v[150:153], v[212:215], v[78:81]
	v_mfma_f32_16x16x32_bf16 v[122:125], v[164:167], v[188:191], v[122:125]
	v_mfma_f32_16x16x32_bf16 v[106:109], v[164:167], v[196:199], v[106:109]
	v_mfma_f32_16x16x32_bf16 v[90:93], v[164:167], v[204:207], v[90:93]
	v_mfma_f32_16x16x32_bf16 v[74:77], v[164:167], v[212:215], v[74:77]
	s_setprio 0
	s_setprio 1
	v_mfma_f32_16x16x32_bf16 v[118:121], v[168:171], v[184:187], 0
	v_mfma_f32_16x16x32_bf16 v[102:105], v[168:171], v[192:195], 0
	v_mfma_f32_16x16x32_bf16 v[86:89], v[168:171], v[200:203], 0
	v_mfma_f32_16x16x32_bf16 v[70:73], v[168:171], v[208:211], 0
	v_mfma_f32_16x16x32_bf16 v[114:117], v[176:179], v[184:187], 0
	v_mfma_f32_16x16x32_bf16 v[98:101], v[176:179], v[192:195], 0
	v_mfma_f32_16x16x32_bf16 v[82:85], v[176:179], v[200:203], 0
	v_mfma_f32_16x16x32_bf16 v[66:69], v[176:179], v[208:211], 0
	v_mfma_f32_16x16x32_bf16 v[118:121], v[172:175], v[188:191], v[118:121]
	v_mfma_f32_16x16x32_bf16 v[102:105], v[172:175], v[196:199], v[102:105]
	v_mfma_f32_16x16x32_bf16 v[86:89], v[172:175], v[204:207], v[86:89]
	v_mfma_f32_16x16x32_bf16 v[70:73], v[172:175], v[212:215], v[70:73]
	v_mfma_f32_16x16x32_bf16 v[114:117], v[180:183], v[188:191], v[114:117]
	v_mfma_f32_16x16x32_bf16 v[98:101], v[180:183], v[196:199], v[98:101]
	v_mfma_f32_16x16x32_bf16 v[82:85], v[180:183], v[204:207], v[82:85]
	v_mfma_f32_16x16x32_bf16 v[66:69], v[180:183], v[212:215], v[66:69]
	s_setprio 0
	s_barrier
	s_add_u32 s98, s50, s18
	s_addc_u32 s99, s51, s19
	s_add_u32 s100, s52, s18
	s_addc_u32 s101, s53, s19
	s_add_i32 s12, s65, s33
	s_mov_b32 m0, s12
	ds_read_b128 v[184:187], v158 offset:16384
	ds_read_b128 v[188:191], v158 offset:17408
	ds_read_b128 v[192:195], v158 offset:18432
	ds_read_b128 v[196:199], v158 offset:19456
	ds_read_b128 v[200:203], v158 offset:20480
	ds_read_b128 v[204:207], v158 offset:21504
	ds_read_b128 v[208:211], v158 offset:22528
	ds_read_b128 v[212:215], v158 offset:23552
	global_load_lds_dwordx4 v132, s[50:51]
	s_add_i32 m0, s12, 0x2000
	s_add_u32 s76, s50, 0xc00000
	s_addc_u32 s77, s51, 0
	s_add_i32 s12, s72, s33
	global_load_lds_dwordx4 v136, s[50:51]
	s_mov_b32 m0, s12
	s_nop 0
	global_load_lds_dwordx4 v132, s[76:77]
	s_add_i32 m0, s12, 0x2000
	s_nop 0
	global_load_lds_dwordx4 v136, s[76:77]
	s_mov_b32 m0, s54
	s_nop 0
	global_load_lds_dwordx4 v130, s[52:53]
	s_mov_b32 m0, s55
	s_nop 0
	global_load_lds_dwordx4 v134, s[52:53]
	s_waitcnt vmcnt(8)
	s_waitcnt lgkmcnt(0)
	s_barrier
	s_setprio 1
	s_waitcnt lgkmcnt(0)
	v_mfma_f32_16x16x32_bf16 v[62:65], v[146:149], v[184:187], 0
	v_mfma_f32_16x16x32_bf16 v[38:41], v[146:149], v[192:195], 0
	v_mfma_f32_16x16x32_bf16 v[22:25], v[146:149], v[200:203], 0
	v_mfma_f32_16x16x32_bf16 v[6:9], v[146:149], v[208:211], 0
	v_mfma_f32_16x16x32_bf16 v[58:61], v[160:163], v[184:187], 0
	v_mfma_f32_16x16x32_bf16 v[34:37], v[160:163], v[192:195], 0
	v_mfma_f32_16x16x32_bf16 v[18:21], v[160:163], v[200:203], 0
	v_mfma_f32_16x16x32_bf16 v[2:5], v[160:163], v[208:211], 0
	v_mfma_f32_16x16x32_bf16 v[62:65], v[150:153], v[188:191], v[62:65]
	v_mfma_f32_16x16x32_bf16 v[38:41], v[150:153], v[196:199], v[38:41]
	v_mfma_f32_16x16x32_bf16 v[22:25], v[150:153], v[204:207], v[22:25]
	v_mfma_f32_16x16x32_bf16 v[6:9], v[150:153], v[212:215], v[6:9]
	v_mfma_f32_16x16x32_bf16 v[58:61], v[164:167], v[188:191], v[58:61]
	v_mfma_f32_16x16x32_bf16 v[34:37], v[164:167], v[196:199], v[34:37]
	v_mfma_f32_16x16x32_bf16 v[18:21], v[164:167], v[204:207], v[18:21]
	v_mfma_f32_16x16x32_bf16 v[2:5], v[164:167], v[212:215], v[2:5]
	s_setprio 0
	s_setprio 1
	v_mfma_f32_16x16x32_bf16 v[54:57], v[168:171], v[184:187], 0
	v_mfma_f32_16x16x32_bf16 v[42:45], v[168:171], v[192:195], 0
	v_mfma_f32_16x16x32_bf16 v[26:29], v[168:171], v[200:203], 0
	v_mfma_f32_16x16x32_bf16 v[10:13], v[168:171], v[208:211], 0
	v_mfma_f32_16x16x32_bf16 v[50:53], v[176:179], v[184:187], 0
	v_mfma_f32_16x16x32_bf16 v[46:49], v[176:179], v[192:195], 0
	v_mfma_f32_16x16x32_bf16 v[30:33], v[176:179], v[200:203], 0
	v_mfma_f32_16x16x32_bf16 v[14:17], v[176:179], v[208:211], 0
	v_mfma_f32_16x16x32_bf16 v[54:57], v[172:175], v[188:191], v[54:57]
	v_mfma_f32_16x16x32_bf16 v[42:45], v[172:175], v[196:199], v[42:45]
	v_mfma_f32_16x16x32_bf16 v[26:29], v[172:175], v[204:207], v[26:29]
	v_mfma_f32_16x16x32_bf16 v[10:13], v[172:175], v[212:215], v[10:13]
	v_mfma_f32_16x16x32_bf16 v[50:53], v[180:183], v[188:191], v[50:53]
	v_mfma_f32_16x16x32_bf16 v[46:49], v[180:183], v[196:199], v[46:49]
	v_mfma_f32_16x16x32_bf16 v[30:33], v[180:183], v[204:207], v[30:33]
	v_mfma_f32_16x16x32_bf16 v[14:17], v[180:183], v[212:215], v[14:17]
	s_setprio 0
	s_barrier
; #define PG8_STAGE(bufoff, gbase, voff) do { _Pragma("unroll") for (int _i = 0; _i < 2; ++_i) \
;         __builtin_amdgcn_global_load_lds((const unsigned*)((const char*)(gbase) + (voff)[_i]), (LAS unsigned*)(lds + (bufoff) + ldsw + _i * 8192), 16, 0, 0); } while (0)
; #define PG8_LDA(dst, b, h) do { _Pragma("unroll") for (int m = 0; m < 4; ++m) _Pragma("unroll") for (int k = 0; k < 2; ++k) dst[m][k] = *(const LAS bf16x8*)(lds + PG8_SA(b, h) + aoff + m * 2048 + k * 1024); } while (0)
; #define PG8_LDB(dst, b, h) do { _Pragma("unroll") for (int n = 0; n < 2; ++n) _Pragma("unroll") for (int k = 0; k < 2; ++k) dst[n][k] = *(const LAS bf16x8*)(lds + PG8_SB(b, h) + boff + n * 2048 + k * 1024); } while (0)
; #define PG8_MMA(ai, bj, At, Bt) do { __builtin_amdgcn_s_setprio(1); _Pragma("unroll") for (int m = 0; m < 4; ++m) _Pragma("unroll") for (int n = 0; n < 2; ++n) _Pragma("unroll") for (int k = 0; k < 2; ++k) \
;         acc[ai][bj][m][n] = __builtin_amdgcn_mfma_f32_16x16x32_bf16(Bt[n][k], At[m][k], acc[ai][bj][m][n], 0, 0, 0); __builtin_amdgcn_s_setprio(0); } while (0)
; #define PG8_WAIT_V(n) asm volatile("s_waitcnt vmcnt(" #n ")" ::: "memory")
; #define PG8_WAIT_L(n) asm volatile("s_waitcnt lgkmcnt(" #n ")" ::: "memory")
; #define PG8_BAR __builtin_amdgcn_s_barrier()
; #define PG8_SCHED __builtin_amdgcn_sched_barrier(0)
; template <class Epi, bool ALIGN_EPI, bool SPLITA>
; __device__ __forceinline__ void gemm_phase(LAS unsigned char* lds, const Gemm g, const StaticOrder& S, const Epi& E) {
;     ...
;             PG8_LDB(B0, 1, 0); PG8_LDB(B1, 1, 1); PG8_SCHED; PG8_LDA(At, 1, 0); PG8_STAGE(PG8_SA(0, 1), a2h, vo2);
;             PG8_WAIT_V(8); PG8_WAIT_L(0); PG8_BAR; PG8_MMA(0, 0, At, B0); PG8_MMA(0, 1, At, B1); PG8_BAR; PG8_SCHED;
;             PG8_LDA(At, 1, 1); PG8_STAGE(PG8_SB(1, 0), b3, voffB); PG8_STAGE(PG8_SB(1, 1), b3 + hstepB, voffB); PG8_STAGE(PG8_SA(1, 0), a3, vo2);
;             PG8_WAIT_V(8); PG8_WAIT_L(0); PG8_BAR; PG8_MMA(1, 0, At, B0); PG8_MMA(1, 1, At, B1); PG8_BAR; PG8_SCHED;
	s_add_i32 s12, 0, 0x18000
	v_add_u32_e32 v159, s12, v154
	s_add_i32 s13, 0, 0x1c000
	ds_read_b128 v[146:149], v159
	ds_read_b128 v[150:153], v159 offset:1024
	ds_read_b128 v[160:163], v159 offset:2048
	ds_read_b128 v[164:167], v159 offset:3072
	v_add_u32_e32 v159, s13, v154
	ds_read_b128 v[168:171], v159
	ds_read_b128 v[172:175], v159 offset:1024
	ds_read_b128 v[176:179], v159 offset:2048
	ds_read_b128 v[180:183], v159 offset:3072
	s_add_u32 s52, s52, 0x40000
	s_addc_u32 s53, s53, 0
	s_mov_b32 m0, s56
	ds_read_b128 v[184:187], v158 offset:32768
	ds_read_b128 v[188:191], v158 offset:33792
	ds_read_b128 v[192:195], v158 offset:34816
	ds_read_b128 v[196:199], v158 offset:35840
	ds_read_b128 v[200:203], v158 offset:36864
	ds_read_b128 v[204:207], v158 offset:37888
	ds_read_b128 v[208:211], v158 offset:38912
	ds_read_b128 v[212:215], v158 offset:39936
	global_load_lds_dwordx4 v130, s[52:53]
	s_mov_b32 m0, s57
	s_nop 0
	global_load_lds_dwordx4 v134, s[52:53]
	s_waitcnt vmcnt(8)
	s_waitcnt lgkmcnt(0)
	s_barrier
	s_setprio 1
	s_waitcnt lgkmcnt(0)
	v_mfma_f32_16x16x32_bf16 v[126:129], v[146:149], v[184:187], v[126:129]
	v_mfma_f32_16x16x32_bf16 v[110:113], v[146:149], v[192:195], v[110:113]
	v_mfma_f32_16x16x32_bf16 v[94:97], v[146:149], v[200:203], v[94:97]
	v_mfma_f32_16x16x32_bf16 v[78:81], v[146:149], v[208:211], v[78:81]
	v_mfma_f32_16x16x32_bf16 v[122:125], v[160:163], v[184:187], v[122:125]
	v_mfma_f32_16x16x32_bf16 v[106:109], v[160:163], v[192:195], v[106:109]
	v_mfma_f32_16x16x32_bf16 v[90:93], v[160:163], v[200:203], v[90:93]
	v_mfma_f32_16x16x32_bf16 v[74:77], v[160:163], v[208:211], v[74:77]
	v_mfma_f32_16x16x32_bf16 v[126:129], v[150:153], v[188:191], v[126:129]
	v_mfma_f32_16x16x32_bf16 v[110:113], v[150:153], v[196:199], v[110:113]
	v_mfma_f32_16x16x32_bf16 v[94:97], v[150:153], v[204:207], v[94:97]
	v_mfma_f32_16x16x32_bf16 v[78:81], v[150:153], v[212:215], v[78:81]
	v_mfma_f32_16x16x32_bf16 v[122:125], v[164:167], v[188:191], v[122:125]
	v_mfma_f32_16x16x32_bf16 v[106:109], v[164:167], v[196:199], v[106:109]
	v_mfma_f32_16x16x32_bf16 v[90:93], v[164:167], v[204:207], v[90:93]
	v_mfma_f32_16x16x32_bf16 v[74:77], v[164:167], v[212:215], v[74:77]
	s_setprio 0
	s_setprio 1
	v_mfma_f32_16x16x32_bf16 v[118:121], v[168:171], v[184:187], v[118:121]
	v_mfma_f32_16x16x32_bf16 v[102:105], v[168:171], v[192:195], v[102:105]
	v_mfma_f32_16x16x32_bf16 v[86:89], v[168:171], v[200:203], v[86:89]
	v_mfma_f32_16x16x32_bf16 v[70:73], v[168:171], v[208:211], v[70:73]
	v_mfma_f32_16x16x32_bf16 v[114:117], v[176:179], v[184:187], v[114:117]
	v_mfma_f32_16x16x32_bf16 v[98:101], v[176:179], v[192:195], v[98:101]
	v_mfma_f32_16x16x32_bf16 v[82:85], v[176:179], v[200:203], v[82:85]
	v_mfma_f32_16x16x32_bf16 v[66:69], v[176:179], v[208:211], v[66:69]
	v_mfma_f32_16x16x32_bf16 v[118:121], v[172:175], v[188:191], v[118:121]
	v_mfma_f32_16x16x32_bf16 v[102:105], v[172:175], v[196:199], v[102:105]
	v_mfma_f32_16x16x32_bf16 v[86:89], v[172:175], v[204:207], v[86:89]
	v_mfma_f32_16x16x32_bf16 v[70:73], v[172:175], v[212:215], v[70:73]
	v_mfma_f32_16x16x32_bf16 v[114:117], v[180:183], v[188:191], v[114:117]
	v_mfma_f32_16x16x32_bf16 v[98:101], v[180:183], v[196:199], v[98:101]
	v_mfma_f32_16x16x32_bf16 v[82:85], v[180:183], v[204:207], v[82:85]
	v_mfma_f32_16x16x32_bf16 v[66:69], v[180:183], v[212:215], v[66:69]
	s_setprio 0
	s_barrier
	s_add_i32 s12, s12, s33
	s_mov_b32 m0, s12
	ds_read_b128 v[184:187], v158 offset:49152
	ds_read_b128 v[188:191], v158 offset:50176
	ds_read_b128 v[192:195], v158 offset:51200
	ds_read_b128 v[196:199], v158 offset:52224
	ds_read_b128 v[200:203], v158 offset:53248
	ds_read_b128 v[204:207], v158 offset:54272
	ds_read_b128 v[208:211], v158 offset:55296
	ds_read_b128 v[212:215], v158 offset:56320
	global_load_lds_dwordx4 v132, s[98:99]
	s_add_i32 m0, s12, 0x2000
	s_add_u32 s50, s50, 0xc00080
	s_addc_u32 s51, s51, 0
	s_add_i32 s12, s13, s33
	global_load_lds_dwordx4 v136, s[98:99]
	s_mov_b32 m0, s12
	s_nop 0
	global_load_lds_dwordx4 v132, s[50:51]
	s_add_i32 m0, s12, 0x2000
	s_nop 0
	global_load_lds_dwordx4 v136, s[50:51]
	s_mov_b32 m0, s61
	s_nop 0
	global_load_lds_dwordx4 v130, s[100:101]
	s_mov_b32 m0, s64
	s_nop 0
	global_load_lds_dwordx4 v134, s[100:101]
	s_waitcnt vmcnt(8)
	s_waitcnt lgkmcnt(0)
	s_barrier
	s_setprio 1
	s_waitcnt lgkmcnt(0)
	v_mfma_f32_16x16x32_bf16 v[62:65], v[146:149], v[184:187], v[62:65]
	v_mfma_f32_16x16x32_bf16 v[38:41], v[146:149], v[192:195], v[38:41]
	v_mfma_f32_16x16x32_bf16 v[22:25], v[146:149], v[200:203], v[22:25]
	v_mfma_f32_16x16x32_bf16 v[6:9], v[146:149], v[208:211], v[6:9]
	v_mfma_f32_16x16x32_bf16 v[58:61], v[160:163], v[184:187], v[58:61]
	v_mfma_f32_16x16x32_bf16 v[34:37], v[160:163], v[192:195], v[34:37]
	v_mfma_f32_16x16x32_bf16 v[18:21], v[160:163], v[200:203], v[18:21]
	v_mfma_f32_16x16x32_bf16 v[2:5], v[160:163], v[208:211], v[2:5]
	v_mfma_f32_16x16x32_bf16 v[62:65], v[150:153], v[188:191], v[62:65]
	v_mfma_f32_16x16x32_bf16 v[38:41], v[150:153], v[196:199], v[38:41]
	v_mfma_f32_16x16x32_bf16 v[22:25], v[150:153], v[204:207], v[22:25]
	v_mfma_f32_16x16x32_bf16 v[6:9], v[150:153], v[212:215], v[6:9]
	v_mfma_f32_16x16x32_bf16 v[58:61], v[164:167], v[188:191], v[58:61]
	v_mfma_f32_16x16x32_bf16 v[34:37], v[164:167], v[196:199], v[34:37]
	v_mfma_f32_16x16x32_bf16 v[18:21], v[164:167], v[204:207], v[18:21]
	v_mfma_f32_16x16x32_bf16 v[2:5], v[164:167], v[212:215], v[2:5]
	s_setprio 0
	s_setprio 1
	v_mfma_f32_16x16x32_bf16 v[54:57], v[168:171], v[184:187], v[54:57]
	v_mfma_f32_16x16x32_bf16 v[42:45], v[168:171], v[192:195], v[42:45]
	v_mfma_f32_16x16x32_bf16 v[26:29], v[168:171], v[200:203], v[26:29]
	v_mfma_f32_16x16x32_bf16 v[10:13], v[168:171], v[208:211], v[10:13]
	v_mfma_f32_16x16x32_bf16 v[50:53], v[176:179], v[184:187], v[50:53]
	v_mfma_f32_16x16x32_bf16 v[46:49], v[176:179], v[192:195], v[46:49]
	v_mfma_f32_16x16x32_bf16 v[30:33], v[176:179], v[200:203], v[30:33]
	v_mfma_f32_16x16x32_bf16 v[14:17], v[176:179], v[208:211], v[14:17]
	v_mfma_f32_16x16x32_bf16 v[54:57], v[172:175], v[188:191], v[54:57]
	v_mfma_f32_16x16x32_bf16 v[42:45], v[172:175], v[196:199], v[42:45]
	v_mfma_f32_16x16x32_bf16 v[26:29], v[172:175], v[204:207], v[26:29]
	v_mfma_f32_16x16x32_bf16 v[10:13], v[172:175], v[212:215], v[10:13]
	v_mfma_f32_16x16x32_bf16 v[50:53], v[180:183], v[188:191], v[50:53]
	v_mfma_f32_16x16x32_bf16 v[46:49], v[180:183], v[196:199], v[46:49]
	v_mfma_f32_16x16x32_bf16 v[30:33], v[180:183], v[204:207], v[30:33]
	v_mfma_f32_16x16x32_bf16 v[14:17], v[180:183], v[212:215], v[14:17]
	s_setprio 0
	s_barrier
	s_add_i32 s31, s31, 2
	s_add_u32 s48, s48, 0x100
	s_addc_u32 s49, s49, 0
	s_add_u32 s5, s5, 0x100
	s_addc_u32 s11, s11, 0
; #define PG8_STAGE(bufoff, gbase, voff) do { _Pragma("unroll") for (int _i = 0; _i < 2; ++_i) \
;         __builtin_amdgcn_global_load_lds((const unsigned*)((const char*)(gbase) + (voff)[_i]), (LAS unsigned*)(lds + (bufoff) + ldsw + _i * 8192), 16, 0, 0); } while (0)
; #define PG8_LDA(dst, b, h) do { _Pragma("unroll") for (int m = 0; m < 4; ++m) _Pragma("unroll") for (int k = 0; k < 2; ++k) dst[m][k] = *(const LAS bf16x8*)(lds + PG8_SA(b, h) + aoff + m * 2048 + k * 1024); } while (0)
; #define PG8_LDB(dst, b, h) do { _Pragma("unroll") for (int n = 0; n < 2; ++n) _Pragma("unroll") for (int k = 0; k < 2; ++k) dst[n][k] = *(const LAS bf16x8*)(lds + PG8_SB(b, h) + boff + n * 2048 + k * 1024); } while (0)
; #define PG8_MMA(ai, bj, At, Bt) do { __builtin_amdgcn_s_setprio(1); _Pragma("unroll") for (int m = 0; m < 4; ++m) _Pragma("unroll") for (int n = 0; n < 2; ++n) _Pragma("unroll") for (int k = 0; k < 2; ++k) \
;         acc[ai][bj][m][n] = __builtin_amdgcn_mfma_f32_16x16x32_bf16(Bt[n][k], At[m][k], acc[ai][bj][m][n], 0, 0, 0); __builtin_amdgcn_s_setprio(0); } while (0)
; #define PG8_WAIT_V(n) asm volatile("s_waitcnt vmcnt(" #n ")" ::: "memory")
; #define PG8_WAIT_L(n) asm volatile("s_waitcnt lgkmcnt(" #n ")" ::: "memory")
; #define PG8_BAR __builtin_amdgcn_s_barrier()
; #define PG8_SCHED __builtin_amdgcn_sched_barrier(0)
; template <class Epi, bool ALIGN_EPI, bool SPLITA>
; __device__ __forceinline__ void gemm_phase(LAS unsigned char* lds, const Gemm g, const StaticOrder& S, const Epi& E) {
;     ...
;             PG8_LDB(B0, 0, 0); PG8_LDB(B1, 0, 1); PG8_SCHED; PG8_LDA(At, 0, 0); PG8_STAGE(PG8_SA(1, 1), a1h, vo1);
;             PG8_WAIT_V(8); PG8_WAIT_L(0); PG8_BAR; PG8_MMA(0, 0, At, B0); PG8_MMA(0, 1, At, B1); PG8_BAR; PG8_SCHED;
;             PG8_LDA(At, 0, 1); PG8_STAGE(PG8_SB(0, 0), b2, voffB); PG8_STAGE(PG8_SB(0, 1), b2 + hstepB, voffB); PG8_STAGE(PG8_SA(0, 0), a2, vo2);
;             PG8_WAIT_V(8); PG8_WAIT_L(0); PG8_BAR; PG8_MMA(1, 0, At, B0); PG8_MMA(1, 1, At, B1); PG8_BAR; PG8_SCHED;
;             PG8_LDB(B0, 1, 0); PG8_LDB(B1, 1, 1); PG8_SCHED; PG8_LDA(At, 1, 0); PG8_STAGE(PG8_SA(0, 1), a2h, vo2);
;             PG8_WAIT_V(8); PG8_WAIT_L(0); PG8_BAR; PG8_MMA(0, 0, At, B0); PG8_MMA(0, 1, At, B1); PG8_BAR; PG8_SCHED;
.LBB0_415:
	ds_read_b128 v[146:149], v156
	ds_read_b128 v[150:153], v156 offset:1024
	ds_read_b128 v[160:163], v156 offset:2048
	ds_read_b128 v[164:167], v156 offset:3072
	ds_read_b128 v[168:171], v157
	ds_read_b128 v[172:175], v157 offset:1024
	ds_read_b128 v[176:179], v157 offset:2048
	ds_read_b128 v[180:183], v157 offset:3072
	s_add_u32 s12, s48, 0xfffc0080
	s_addc_u32 s13, s49, -1
	s_cmp_eq_u32 s31, 12
	s_cselect_b32 s53, s1, s13
	s_cselect_b32 s52, s0, s12
	s_cselect_b32 s51, s47, s11
	s_cselect_b32 s50, s46, s5
	s_add_i32 m0, s54, 0xc000
	ds_read_b128 v[184:187], v158
	ds_read_b128 v[188:191], v158 offset:1024
	ds_read_b128 v[192:195], v158 offset:2048
	ds_read_b128 v[196:199], v158 offset:3072
	ds_read_b128 v[200:203], v158 offset:4096
	ds_read_b128 v[204:207], v158 offset:5120
	ds_read_b128 v[208:211], v158 offset:6144
	ds_read_b128 v[212:215], v158 offset:7168
	global_load_lds_dwordx4 v138, s[48:49]
	s_add_i32 m0, s54, 0xe000
	s_nop 0
	global_load_lds_dwordx4 v140, s[48:49]
	s_waitcnt vmcnt(8)
	s_waitcnt lgkmcnt(0)
	s_barrier
	s_setprio 1
	s_waitcnt lgkmcnt(0)
	v_mfma_f32_16x16x32_bf16 v[126:129], v[146:149], v[184:187], v[126:129]
	v_mfma_f32_16x16x32_bf16 v[110:113], v[146:149], v[192:195], v[110:113]
	v_mfma_f32_16x16x32_bf16 v[94:97], v[146:149], v[200:203], v[94:97]
	v_mfma_f32_16x16x32_bf16 v[78:81], v[146:149], v[208:211], v[78:81]
	v_mfma_f32_16x16x32_bf16 v[122:125], v[160:163], v[184:187], v[122:125]
	v_mfma_f32_16x16x32_bf16 v[106:109], v[160:163], v[192:195], v[106:109]
	v_mfma_f32_16x16x32_bf16 v[90:93], v[160:163], v[200:203], v[90:93]
	v_mfma_f32_16x16x32_bf16 v[74:77], v[160:163], v[208:211], v[74:77]
	v_mfma_f32_16x16x32_bf16 v[126:129], v[150:153], v[188:191], v[126:129]
	v_mfma_f32_16x16x32_bf16 v[110:113], v[150:153], v[196:199], v[110:113]
	v_mfma_f32_16x16x32_bf16 v[94:97], v[150:153], v[204:207], v[94:97]
	v_mfma_f32_16x16x32_bf16 v[78:81], v[150:153], v[212:215], v[78:81]
	v_mfma_f32_16x16x32_bf16 v[122:125], v[164:167], v[188:191], v[122:125]
	v_mfma_f32_16x16x32_bf16 v[106:109], v[164:167], v[196:199], v[106:109]
	v_mfma_f32_16x16x32_bf16 v[90:93], v[164:167], v[204:207], v[90:93]
	v_mfma_f32_16x16x32_bf16 v[74:77], v[164:167], v[212:215], v[74:77]
	s_setprio 0
	s_setprio 1
	v_mfma_f32_16x16x32_bf16 v[118:121], v[168:171], v[184:187], v[118:121]
	v_mfma_f32_16x16x32_bf16 v[102:105], v[168:171], v[192:195], v[102:105]
	v_mfma_f32_16x16x32_bf16 v[86:89], v[168:171], v[200:203], v[86:89]
	v_mfma_f32_16x16x32_bf16 v[70:73], v[168:171], v[208:211], v[70:73]
	v_mfma_f32_16x16x32_bf16 v[114:117], v[176:179], v[184:187], v[114:117]
	v_mfma_f32_16x16x32_bf16 v[98:101], v[176:179], v[192:195], v[98:101]
	v_mfma_f32_16x16x32_bf16 v[82:85], v[176:179], v[200:203], v[82:85]
	v_mfma_f32_16x16x32_bf16 v[66:69], v[176:179], v[208:211], v[66:69]
	v_mfma_f32_16x16x32_bf16 v[118:121], v[172:175], v[188:191], v[118:121]
	v_mfma_f32_16x16x32_bf16 v[102:105], v[172:175], v[196:199], v[102:105]
	v_mfma_f32_16x16x32_bf16 v[86:89], v[172:175], v[204:207], v[86:89]
	v_mfma_f32_16x16x32_bf16 v[70:73], v[172:175], v[212:215], v[70:73]
	v_mfma_f32_16x16x32_bf16 v[114:117], v[180:183], v[188:191], v[114:117]
	v_mfma_f32_16x16x32_bf16 v[98:101], v[180:183], v[196:199], v[98:101]
	v_mfma_f32_16x16x32_bf16 v[82:85], v[180:183], v[204:207], v[82:85]
	v_mfma_f32_16x16x32_bf16 v[66:69], v[180:183], v[212:215], v[66:69]
	s_setprio 0
	s_barrier
	s_add_u32 s98, s50, s18
	s_addc_u32 s99, s51, s19
	s_add_u32 s100, s52, s18
	s_addc_u32 s101, s53, s19
	s_add_i32 s12, s65, s33
	s_mov_b32 m0, s12
	ds_read_b128 v[184:187], v158 offset:16384
	ds_read_b128 v[188:191], v158 offset:17408
	ds_read_b128 v[192:195], v158 offset:18432
	ds_read_b128 v[196:199], v158 offset:19456
	ds_read_b128 v[200:203], v158 offset:20480
	ds_read_b128 v[204:207], v158 offset:21504
	ds_read_b128 v[208:211], v158 offset:22528
	ds_read_b128 v[212:215], v158 offset:23552
	global_load_lds_dwordx4 v132, s[50:51]
	s_add_i32 m0, s12, 0x2000
	s_add_u32 s76, s50, 0xc00000
	s_addc_u32 s77, s51, 0
	s_add_i32 s12, s72, s33
	global_load_lds_dwordx4 v136, s[50:51]
	s_mov_b32 m0, s12
	s_nop 0
	global_load_lds_dwordx4 v132, s[76:77]
	s_add_i32 m0, s12, 0x2000
	s_nop 0
	global_load_lds_dwordx4 v136, s[76:77]
	s_mov_b32 m0, s54
	s_nop 0
	global_load_lds_dwordx4 v130, s[52:53]
	s_mov_b32 m0, s55
	s_nop 0
	global_load_lds_dwordx4 v134, s[52:53]
	s_waitcnt vmcnt(8)
	s_waitcnt lgkmcnt(0)
	s_barrier
	s_setprio 1
	s_waitcnt lgkmcnt(0)
	v_mfma_f32_16x16x32_bf16 v[62:65], v[146:149], v[184:187], v[62:65]
	v_mfma_f32_16x16x32_bf16 v[38:41], v[146:149], v[192:195], v[38:41]
	v_mfma_f32_16x16x32_bf16 v[22:25], v[146:149], v[200:203], v[22:25]
	v_mfma_f32_16x16x32_bf16 v[6:9], v[146:149], v[208:211], v[6:9]
	v_mfma_f32_16x16x32_bf16 v[58:61], v[160:163], v[184:187], v[58:61]
	v_mfma_f32_16x16x32_bf16 v[34:37], v[160:163], v[192:195], v[34:37]
	v_mfma_f32_16x16x32_bf16 v[18:21], v[160:163], v[200:203], v[18:21]
	v_mfma_f32_16x16x32_bf16 v[2:5], v[160:163], v[208:211], v[2:5]
	v_mfma_f32_16x16x32_bf16 v[62:65], v[150:153], v[188:191], v[62:65]
	v_mfma_f32_16x16x32_bf16 v[38:41], v[150:153], v[196:199], v[38:41]
	v_mfma_f32_16x16x32_bf16 v[22:25], v[150:153], v[204:207], v[22:25]
	v_mfma_f32_16x16x32_bf16 v[6:9], v[150:153], v[212:215], v[6:9]
	v_mfma_f32_16x16x32_bf16 v[58:61], v[164:167], v[188:191], v[58:61]
	v_mfma_f32_16x16x32_bf16 v[34:37], v[164:167], v[196:199], v[34:37]
	v_mfma_f32_16x16x32_bf16 v[18:21], v[164:167], v[204:207], v[18:21]
	v_mfma_f32_16x16x32_bf16 v[2:5], v[164:167], v[212:215], v[2:5]
	s_setprio 0
	s_setprio 1
	v_mfma_f32_16x16x32_bf16 v[54:57], v[168:171], v[184:187], v[54:57]
	v_mfma_f32_16x16x32_bf16 v[42:45], v[168:171], v[192:195], v[42:45]
	v_mfma_f32_16x16x32_bf16 v[26:29], v[168:171], v[200:203], v[26:29]
	v_mfma_f32_16x16x32_bf16 v[10:13], v[168:171], v[208:211], v[10:13]
	v_mfma_f32_16x16x32_bf16 v[50:53], v[176:179], v[184:187], v[50:53]
	v_mfma_f32_16x16x32_bf16 v[46:49], v[176:179], v[192:195], v[46:49]
	v_mfma_f32_16x16x32_bf16 v[30:33], v[176:179], v[200:203], v[30:33]
	v_mfma_f32_16x16x32_bf16 v[14:17], v[176:179], v[208:211], v[14:17]
	v_mfma_f32_16x16x32_bf16 v[54:57], v[172:175], v[188:191], v[54:57]
	v_mfma_f32_16x16x32_bf16 v[42:45], v[172:175], v[196:199], v[42:45]
	v_mfma_f32_16x16x32_bf16 v[26:29], v[172:175], v[204:207], v[26:29]
	v_mfma_f32_16x16x32_bf16 v[10:13], v[172:175], v[212:215], v[10:13]
	v_mfma_f32_16x16x32_bf16 v[50:53], v[180:183], v[188:191], v[50:53]
	v_mfma_f32_16x16x32_bf16 v[46:49], v[180:183], v[196:199], v[46:49]
	v_mfma_f32_16x16x32_bf16 v[30:33], v[180:183], v[204:207], v[30:33]
	v_mfma_f32_16x16x32_bf16 v[14:17], v[180:183], v[212:215], v[14:17]
	s_setprio 0
	s_barrier
; #define PG8_STAGE(bufoff, gbase, voff) do { _Pragma("unroll") for (int _i = 0; _i < 2; ++_i) \
;         __builtin_amdgcn_global_load_lds((const unsigned*)((const char*)(gbase) + (voff)[_i]), (LAS unsigned*)(lds + (bufoff) + ldsw + _i * 8192), 16, 0, 0); } while (0)
; #define PG8_LDA(dst, b, h) do { _Pragma("unroll") for (int m = 0; m < 4; ++m) _Pragma("unroll") for (int k = 0; k < 2; ++k) dst[m][k] = *(const LAS bf16x8*)(lds + PG8_SA(b, h) + aoff + m * 2048 + k * 1024); } while (0)
; #define PG8_MMA(ai, bj, At, Bt) do { __builtin_amdgcn_s_setprio(1); _Pragma("unroll") for (int m = 0; m < 4; ++m) _Pragma("unroll") for (int n = 0; n < 2; ++n) _Pragma("unroll") for (int k = 0; k < 2; ++k) \
;         acc[ai][bj][m][n] = __builtin_amdgcn_mfma_f32_16x16x32_bf16(Bt[n][k], At[m][k], acc[ai][bj][m][n], 0, 0, 0); __builtin_amdgcn_s_setprio(0); } while (0)
; #define PG8_WAIT_V(n) asm volatile("s_waitcnt vmcnt(" #n ")" ::: "memory")
; #define PG8_WAIT_L(n) asm volatile("s_waitcnt lgkmcnt(" #n ")" ::: "memory")
; #define PG8_BAR __builtin_amdgcn_s_barrier()
; #define PG8_SCHED __builtin_amdgcn_sched_barrier(0)
; template <class Epi, bool ALIGN_EPI, bool SPLITA>
; __device__ __forceinline__ void gemm_phase(LAS unsigned char* lds, const Gemm g, const StaticOrder& S, const Epi& E) {
;     ...
;             PG8_WAIT_V(8); PG8_WAIT_L(0); PG8_BAR; PG8_MMA(0, 0, At, B0); PG8_MMA(0, 1, At, B1); PG8_BAR; PG8_SCHED;
;             PG8_LDA(At, 1, 1); PG8_STAGE(PG8_SB(1, 0), b3, voffB); PG8_STAGE(PG8_SB(1, 1), b3 + hstepB, voffB); PG8_STAGE(PG8_SA(1, 0), a3, vo2);
;             PG8_WAIT_V(8); PG8_WAIT_L(0); PG8_BAR; PG8_MMA(1, 0, At, B0); PG8_MMA(1, 1, At, B1); PG8_BAR; PG8_SCHED;
;         }
;         if constexpr (ALIGN_EPI) { if (wr == 0) PG8_BAR; }
	s_add_i32 s12, 0, 0x18000
	v_add_u32_e32 v159, s12, v154
	s_add_i32 s13, 0, 0x1c000
	ds_read_b128 v[146:149], v159
	ds_read_b128 v[150:153], v159 offset:1024
	ds_read_b128 v[160:163], v159 offset:2048
	ds_read_b128 v[164:167], v159 offset:3072
	v_add_u32_e32 v159, s13, v154
	ds_read_b128 v[168:171], v159
	ds_read_b128 v[172:175], v159 offset:1024
	ds_read_b128 v[176:179], v159 offset:2048
	ds_read_b128 v[180:183], v159 offset:3072
	s_add_u32 s52, s52, 0x40000
	s_addc_u32 s53, s53, 0
	s_mov_b32 m0, s56
	ds_read_b128 v[184:187], v158 offset:32768
	ds_read_b128 v[188:191], v158 offset:33792
	ds_read_b128 v[192:195], v158 offset:34816
	ds_read_b128 v[196:199], v158 offset:35840
	ds_read_b128 v[200:203], v158 offset:36864
	ds_read_b128 v[204:207], v158 offset:37888
	ds_read_b128 v[208:211], v158 offset:38912
	ds_read_b128 v[212:215], v158 offset:39936
	global_load_lds_dwordx4 v130, s[52:53]
	s_mov_b32 m0, s57
	s_nop 0
	global_load_lds_dwordx4 v134, s[52:53]
	s_waitcnt vmcnt(8)
	s_waitcnt lgkmcnt(0)
	s_barrier
	s_setprio 1
	s_waitcnt lgkmcnt(0)
	v_mfma_f32_16x16x32_bf16 v[126:129], v[146:149], v[184:187], v[126:129]
	v_mfma_f32_16x16x32_bf16 v[110:113], v[146:149], v[192:195], v[110:113]
	v_mfma_f32_16x16x32_bf16 v[94:97], v[146:149], v[200:203], v[94:97]
	v_mfma_f32_16x16x32_bf16 v[78:81], v[146:149], v[208:211], v[78:81]
	v_mfma_f32_16x16x32_bf16 v[122:125], v[160:163], v[184:187], v[122:125]
	v_mfma_f32_16x16x32_bf16 v[106:109], v[160:163], v[192:195], v[106:109]
	v_mfma_f32_16x16x32_bf16 v[90:93], v[160:163], v[200:203], v[90:93]
	v_mfma_f32_16x16x32_bf16 v[74:77], v[160:163], v[208:211], v[74:77]
	v_mfma_f32_16x16x32_bf16 v[126:129], v[150:153], v[188:191], v[126:129]
	v_mfma_f32_16x16x32_bf16 v[110:113], v[150:153], v[196:199], v[110:113]
	v_mfma_f32_16x16x32_bf16 v[94:97], v[150:153], v[204:207], v[94:97]
	v_mfma_f32_16x16x32_bf16 v[78:81], v[150:153], v[212:215], v[78:81]
	v_mfma_f32_16x16x32_bf16 v[122:125], v[164:167], v[188:191], v[122:125]
	v_mfma_f32_16x16x32_bf16 v[106:109], v[164:167], v[196:199], v[106:109]
	v_mfma_f32_16x16x32_bf16 v[90:93], v[164:167], v[204:207], v[90:93]
	v_mfma_f32_16x16x32_bf16 v[74:77], v[164:167], v[212:215], v[74:77]
	s_setprio 0
	s_setprio 1
	v_mfma_f32_16x16x32_bf16 v[118:121], v[168:171], v[184:187], v[118:121]
	v_mfma_f32_16x16x32_bf16 v[102:105], v[168:171], v[192:195], v[102:105]
	v_mfma_f32_16x16x32_bf16 v[86:89], v[168:171], v[200:203], v[86:89]
	v_mfma_f32_16x16x32_bf16 v[70:73], v[168:171], v[208:211], v[70:73]
	v_mfma_f32_16x16x32_bf16 v[114:117], v[176:179], v[184:187], v[114:117]
	v_mfma_f32_16x16x32_bf16 v[98:101], v[176:179], v[192:195], v[98:101]
	v_mfma_f32_16x16x32_bf16 v[82:85], v[176:179], v[200:203], v[82:85]
	v_mfma_f32_16x16x32_bf16 v[66:69], v[176:179], v[208:211], v[66:69]
	v_mfma_f32_16x16x32_bf16 v[118:121], v[172:175], v[188:191], v[118:121]
	v_mfma_f32_16x16x32_bf16 v[102:105], v[172:175], v[196:199], v[102:105]
	v_mfma_f32_16x16x32_bf16 v[86:89], v[172:175], v[204:207], v[86:89]
	v_mfma_f32_16x16x32_bf16 v[70:73], v[172:175], v[212:215], v[70:73]
	v_mfma_f32_16x16x32_bf16 v[114:117], v[180:183], v[188:191], v[114:117]
	v_mfma_f32_16x16x32_bf16 v[98:101], v[180:183], v[196:199], v[98:101]
	v_mfma_f32_16x16x32_bf16 v[82:85], v[180:183], v[204:207], v[82:85]
	v_mfma_f32_16x16x32_bf16 v[66:69], v[180:183], v[212:215], v[66:69]
	s_setprio 0
	s_barrier
	s_add_i32 s12, s12, s33
	s_mov_b32 m0, s12
	ds_read_b128 v[184:187], v158 offset:49152
	ds_read_b128 v[188:191], v158 offset:50176
	ds_read_b128 v[192:195], v158 offset:51200
	ds_read_b128 v[196:199], v158 offset:52224
	ds_read_b128 v[200:203], v158 offset:53248
	ds_read_b128 v[204:207], v158 offset:54272
	ds_read_b128 v[208:211], v158 offset:55296
	ds_read_b128 v[212:215], v158 offset:56320
	global_load_lds_dwordx4 v132, s[98:99]
	s_add_i32 m0, s12, 0x2000
	s_add_u32 s50, s50, 0xc00080
	s_addc_u32 s51, s51, 0
	s_add_i32 s12, s13, s33
	global_load_lds_dwordx4 v136, s[98:99]
	s_mov_b32 m0, s12
	s_nop 0
	global_load_lds_dwordx4 v132, s[50:51]
	s_add_i32 m0, s12, 0x2000
	s_nop 0
	global_load_lds_dwordx4 v136, s[50:51]
	s_mov_b32 m0, s61
	s_nop 0
	global_load_lds_dwordx4 v130, s[100:101]
	s_mov_b32 m0, s64
	s_nop 0
	global_load_lds_dwordx4 v134, s[100:101]
	s_waitcnt vmcnt(8)
	s_waitcnt lgkmcnt(0)
	s_barrier
	s_setprio 1
	s_waitcnt lgkmcnt(0)
	v_mfma_f32_16x16x32_bf16 v[62:65], v[146:149], v[184:187], v[62:65]
	v_mfma_f32_16x16x32_bf16 v[38:41], v[146:149], v[192:195], v[38:41]
	v_mfma_f32_16x16x32_bf16 v[22:25], v[146:149], v[200:203], v[22:25]
	v_mfma_f32_16x16x32_bf16 v[6:9], v[146:149], v[208:211], v[6:9]
	v_mfma_f32_16x16x32_bf16 v[58:61], v[160:163], v[184:187], v[58:61]
	v_mfma_f32_16x16x32_bf16 v[34:37], v[160:163], v[192:195], v[34:37]
	v_mfma_f32_16x16x32_bf16 v[18:21], v[160:163], v[200:203], v[18:21]
	v_mfma_f32_16x16x32_bf16 v[2:5], v[160:163], v[208:211], v[2:5]
	v_mfma_f32_16x16x32_bf16 v[62:65], v[150:153], v[188:191], v[62:65]
	v_mfma_f32_16x16x32_bf16 v[38:41], v[150:153], v[196:199], v[38:41]
	v_mfma_f32_16x16x32_bf16 v[22:25], v[150:153], v[204:207], v[22:25]
	v_mfma_f32_16x16x32_bf16 v[6:9], v[150:153], v[212:215], v[6:9]
	v_mfma_f32_16x16x32_bf16 v[58:61], v[164:167], v[188:191], v[58:61]
	v_mfma_f32_16x16x32_bf16 v[34:37], v[164:167], v[196:199], v[34:37]
	v_mfma_f32_16x16x32_bf16 v[18:21], v[164:167], v[204:207], v[18:21]
	v_mfma_f32_16x16x32_bf16 v[2:5], v[164:167], v[212:215], v[2:5]
	s_setprio 0
	s_setprio 1
	v_mfma_f32_16x16x32_bf16 v[54:57], v[168:171], v[184:187], v[54:57]
	v_mfma_f32_16x16x32_bf16 v[42:45], v[168:171], v[192:195], v[42:45]
	v_mfma_f32_16x16x32_bf16 v[26:29], v[168:171], v[200:203], v[26:29]
	v_mfma_f32_16x16x32_bf16 v[10:13], v[168:171], v[208:211], v[10:13]
	v_mfma_f32_16x16x32_bf16 v[50:53], v[176:179], v[184:187], v[50:53]
	v_mfma_f32_16x16x32_bf16 v[46:49], v[176:179], v[192:195], v[46:49]
	v_mfma_f32_16x16x32_bf16 v[30:33], v[176:179], v[200:203], v[30:33]
	v_mfma_f32_16x16x32_bf16 v[14:17], v[176:179], v[208:211], v[14:17]
	v_mfma_f32_16x16x32_bf16 v[54:57], v[172:175], v[188:191], v[54:57]
	v_mfma_f32_16x16x32_bf16 v[42:45], v[172:175], v[196:199], v[42:45]
	v_mfma_f32_16x16x32_bf16 v[26:29], v[172:175], v[204:207], v[26:29]
	v_mfma_f32_16x16x32_bf16 v[10:13], v[172:175], v[212:215], v[10:13]
	v_mfma_f32_16x16x32_bf16 v[50:53], v[180:183], v[188:191], v[50:53]
	v_mfma_f32_16x16x32_bf16 v[46:49], v[180:183], v[196:199], v[46:49]
	v_mfma_f32_16x16x32_bf16 v[30:33], v[180:183], v[204:207], v[30:33]
	v_mfma_f32_16x16x32_bf16 v[14:17], v[180:183], v[212:215], v[14:17]
	s_setprio 0
	s_barrier
	s_add_i32 s31, s31, 2
	s_add_u32 s48, s48, 0x100
	s_addc_u32 s49, s49, 0
	s_add_u32 s5, s5, 0x100
	s_addc_u32 s11, s11, 0
	s_cmp_gt_u32 s31, 13
	s_cbranch_scc0 .LBB0_415
	s_and_b64 vcc, exec, s[20:21]
	s_cbranch_vccz .LBB0_418
	s_barrier

; #define PG8_STAGE(bufoff, gbase, voff) do { _Pragma("unroll") for (int _i = 0; _i < 2; ++_i) \
;         __builtin_amdgcn_global_load_lds((const unsigned*)((const char*)(gbase) + (voff)[_i]), (LAS unsigned*)(lds + (bufoff) + ldsw + _i * 8192), 16, 0, 0); } while (0)
; #define PG8_WAIT_V(n) asm volatile("s_waitcnt vmcnt(" #n ")" ::: "memory")
; template <class Epi, bool ALIGN_EPI, bool SPLITA>
; __device__ __forceinline__ void gemm_phase(LAS unsigned char* lds, const Gemm g, const StaticOrder& S, const Epi& E) {
;     ...
;         for (int t = 0; t < nt; t += 2) {
;             const bool last = (t == nt - 2);
;             if constexpr (Epi::MIDK) { if (t == g.ksplit) E.mid(acc, cur, wr, wc, fr, fq); }
;             const char *a1, *a2;
;             if constexpr (SPLITA) {
;                 a1 = (t + 1 < g.ksplit) ? cA + (size_t)(t + 1) * kstep : cA2 + (size_t)(t + 1 - g.ksplit) * 2048;
;                 a2 = last ? nA : ((t + 2 < g.ksplit) ? cA + (size_t)(t + 2) * kstep : cA2 + (size_t)(t + 2 - g.ksplit) * 2048);
;             } else { a1 = cA + kofs(t + 1); a2 = last ? nA : cA + kofs(t + 2); }
;             const char* b2 = last ? nB : cB + (size_t)(t + 2) * kstepB;
;             const bool s2a = SPLITA && (t + 1 >= g.ksplit), s2b = SPLITA && !last && (t + 2 >= g.ksplit);
;             const char* a3 = a2 + ((Epi::KSUB || s2b) ? (size_t)2048 : kstep); const char* b3 = b2 + kstepB;
;             const bool m1 = SPLITA && mirC && (t + 1 < g.ksplit), m2 = SPLITA && (last ? mirN : (mirC && (t + 2 < g.ksplit)));
;             const unsigned vo1[2] = {s2a ? voffA2[0] : m1 ? voffAm[0] : voffA[0], s2a ? voffA2[1] : m1 ? voffAm[1] : voffA[1]}, vo2[2] = {s2b ? voffA2[0] : m2 ? voffAm[0] : voffA[0], s2b ? voffA2[1] : m2 ? voffAm[1] : voffA[1]};
;             const char* a1h = m1 ? a1 - hstepA : a1 + hstepA; const char* a2h = m2 ? a2 - hstepA : a2 + hstepA;
;             PG8_LDB(B0, 0, 0); PG8_LDB(B1, 0, 1); PG8_SCHED; PG8_LDA(At, 0, 0); PG8_STAGE(PG8_SA(1, 1), a1h, vo1);
;             PG8_WAIT_V(8); PG8_WAIT_L(0); PG8_BAR; PG8_MMA(0, 0, At, B0); PG8_MMA(0, 1, At, B1); PG8_BAR; PG8_SCHED;
;             PG8_LDA(At, 0, 1); PG8_STAGE(PG8_SB(0, 0), b2, voffB); PG8_STAGE(PG8_SB(0, 1), b2 + hstepB, voffB); PG8_STAGE(PG8_SA(0, 0), a2, vo2);
;             PG8_WAIT_V(8); PG8_WAIT_L(0); PG8_BAR; PG8_MMA(1, 0, At, B0); PG8_MMA(1, 1, At, B1); PG8_BAR; PG8_SCHED;
.LBB0_626:
	s_cmp_lt_u32 s37, 16
	s_cselect_b64 vcc, -1, 0
	s_and_b64 s[0:1], vcc, exec
	s_cselect_b32 s0, 0, -16
	s_add_i32 s0, s0, s72
	s_add_i32 s10, s0, 15
	s_and_b64 s[0:1], vcc, exec
	s_cselect_b32 s0, 7, 11
	s_cselect_b32 s8, s51, s19
	s_cselect_b32 s9, s50, s17
	s_lshl_b64 s[0:1], s[10:11], s0
	s_add_u32 s10, s9, s0
	s_addc_u32 s43, s8, s1
	s_add_u32 s73, s52, s74
	s_addc_u32 s88, s53, s75
	s_cmp_gt_u32 s37, 13
	s_cselect_b64 s[0:1], -1, 0
	s_and_b64 s[0:1], s[80:81], s[0:1]
	s_and_b64 s[78:79], s[0:1], exec
	s_movk_i32 s8, 0x800
	s_cselect_b32 s8, s8, 0x80
	s_add_u32 s78, s76, s8
	s_addc_u32 s79, s77, 0
	s_and_b64 s[8:9], s[54:55], vcc
	s_cmp_lt_u32 s37, 14
	s_cselect_b64 s[12:13], -1, 0
	s_and_b64 s[12:13], s[54:55], s[12:13]
	v_cndmask_b32_e64 v132, 0, 1, s[12:13]
	v_cndmask_b32_e64 v133, 0, 1, s[4:5]
	s_and_b64 s[12:13], s[80:81], exec
	v_readfirstlane_b32 s12, v132
	v_readfirstlane_b32 s13, v133
	s_cselect_b32 s12, s12, s13
	s_and_b32 s12, 1, s12
	s_and_b64 s[8:9], s[8:9], exec
	s_cselect_b32 s8, s7, 0x40000
	s_cselect_b32 s9, -1, 0
	s_cmp_eq_u32 s12, 1
	v_cndmask_b32_e32 v2, v197, v193, vcc
	v_cndmask_b32_e32 v203, v198, v202, vcc
	s_cselect_b64 vcc, -1, 0
	v_cndmask_b32_e32 v132, v1, v195, vcc
	v_cndmask_b32_e64 v226, v132, v197, s[0:1]
	v_cndmask_b32_e32 v132, v194, v196, vcc
	v_add_u32_e32 v144, s97, v200
	v_add_u32_e32 v160, s33, v200
	v_cndmask_b32_e64 v227, v132, v198, s[0:1]
	ds_read_b128 v[132:135], v144
	ds_read_b128 v[136:139], v144 offset:1024
	ds_read_b128 v[140:143], v144 offset:2048
	ds_read_b128 v[144:147], v144 offset:3072
	ds_read_b128 v[148:151], v160
	ds_read_b128 v[152:155], v160 offset:1024
	ds_read_b128 v[156:159], v160 offset:2048
	ds_read_b128 v[160:163], v160 offset:3072
	s_and_b64 s[0:1], vcc, exec
	s_cselect_b32 s12, -1, 0
	s_cselect_b32 s13, s7, 0x40000
	s_and_b64 s[0:1], s[80:81], exec
	s_cselect_b32 s1, s88, s47
	s_cselect_b32 s0, s73, s46
	s_add_u32 s8, s10, s8
	s_addc_u32 s9, s43, s9
	s_add_i32 m0, s31, 0xc000
	ds_read_b128 v[164:167], v201
	ds_read_b128 v[168:171], v201 offset:1024
	ds_read_b128 v[172:175], v201 offset:2048
	ds_read_b128 v[176:179], v201 offset:3072
	ds_read_b128 v[204:207], v201 offset:4096
	ds_read_b128 v[208:211], v201 offset:5120
	ds_read_b128 v[212:215], v201 offset:6144
	ds_read_b128 v[216:219], v201 offset:7168
	global_load_lds_dwordx4 v2, s[8:9]
	s_add_i32 m0, s31, 0xe000
	s_nop 0
	global_load_lds_dwordx4 v203, s[8:9]
	s_waitcnt vmcnt(8)
	s_waitcnt lgkmcnt(0)
	s_barrier
	s_setprio 1
	s_waitcnt lgkmcnt(0)
	v_mfma_f32_16x16x32_bf16 v[128:131], v[132:135], v[164:167], v[128:131]
	v_mfma_f32_16x16x32_bf16 v[112:115], v[132:135], v[172:175], v[112:115]
	v_mfma_f32_16x16x32_bf16 v[96:99], v[132:135], v[204:207], v[96:99]
	v_mfma_f32_16x16x32_bf16 v[80:83], v[132:135], v[212:215], v[80:83]
	v_mfma_f32_16x16x32_bf16 v[124:127], v[140:143], v[164:167], v[124:127]
	v_mfma_f32_16x16x32_bf16 v[108:111], v[140:143], v[172:175], v[108:111]
	v_mfma_f32_16x16x32_bf16 v[92:95], v[140:143], v[204:207], v[92:95]
	v_mfma_f32_16x16x32_bf16 v[76:79], v[140:143], v[212:215], v[76:79]
	v_mfma_f32_16x16x32_bf16 v[128:131], v[136:139], v[168:171], v[128:131]
	v_mfma_f32_16x16x32_bf16 v[112:115], v[136:139], v[176:179], v[112:115]
	v_mfma_f32_16x16x32_bf16 v[96:99], v[136:139], v[208:211], v[96:99]
	v_mfma_f32_16x16x32_bf16 v[80:83], v[136:139], v[216:219], v[80:83]
	v_mfma_f32_16x16x32_bf16 v[124:127], v[144:147], v[168:171], v[124:127]
	v_mfma_f32_16x16x32_bf16 v[108:111], v[144:147], v[176:179], v[108:111]
	v_mfma_f32_16x16x32_bf16 v[92:95], v[144:147], v[208:211], v[92:95]
	v_mfma_f32_16x16x32_bf16 v[76:79], v[144:147], v[216:219], v[76:79]
	s_setprio 0
	s_setprio 1
	v_mfma_f32_16x16x32_bf16 v[120:123], v[148:151], v[164:167], v[120:123]
	v_mfma_f32_16x16x32_bf16 v[104:107], v[148:151], v[172:175], v[104:107]
	v_mfma_f32_16x16x32_bf16 v[88:91], v[148:151], v[204:207], v[88:91]
	v_mfma_f32_16x16x32_bf16 v[72:75], v[148:151], v[212:215], v[72:75]
	v_mfma_f32_16x16x32_bf16 v[116:119], v[156:159], v[164:167], v[116:119]
	v_mfma_f32_16x16x32_bf16 v[100:103], v[156:159], v[172:175], v[100:103]
	v_mfma_f32_16x16x32_bf16 v[84:87], v[156:159], v[204:207], v[84:87]
	v_mfma_f32_16x16x32_bf16 v[68:71], v[156:159], v[212:215], v[68:71]
	v_mfma_f32_16x16x32_bf16 v[120:123], v[152:155], v[168:171], v[120:123]
	v_mfma_f32_16x16x32_bf16 v[104:107], v[152:155], v[176:179], v[104:107]
	v_mfma_f32_16x16x32_bf16 v[88:91], v[152:155], v[208:211], v[88:91]
	v_mfma_f32_16x16x32_bf16 v[72:75], v[152:155], v[216:219], v[72:75]
	v_mfma_f32_16x16x32_bf16 v[116:119], v[160:163], v[168:171], v[116:119]
	v_mfma_f32_16x16x32_bf16 v[100:103], v[160:163], v[176:179], v[100:103]
	v_mfma_f32_16x16x32_bf16 v[84:87], v[160:163], v[208:211], v[84:87]
	v_mfma_f32_16x16x32_bf16 v[68:71], v[160:163], v[216:219], v[68:71]
	s_setprio 0
	s_barrier
	s_add_u32 s98, s0, s22
	s_addc_u32 s99, s1, s23
	s_add_i32 s8, s97, s6
	s_mov_b32 m0, s8
	ds_read_b128 v[164:167], v201 offset:16384
	ds_read_b128 v[168:171], v201 offset:17408
	ds_read_b128 v[172:175], v201 offset:18432
	ds_read_b128 v[176:179], v201 offset:19456
	ds_read_b128 v[204:207], v201 offset:20480
	ds_read_b128 v[208:211], v201 offset:21504
	ds_read_b128 v[212:215], v201 offset:22528
	ds_read_b128 v[216:219], v201 offset:23552
	global_load_lds_dwordx4 v180, s[0:1]
	s_add_i32 m0, s8, 0x2000
	s_add_u32 s8, s0, 0x80000
	s_addc_u32 s9, s1, 0
	s_add_i32 s10, s33, s6
	global_load_lds_dwordx4 v182, s[0:1]
	s_mov_b32 m0, s10
	s_nop 0
	global_load_lds_dwordx4 v180, s[8:9]
	s_add_i32 m0, s10, 0x2000
	s_nop 0
	global_load_lds_dwordx4 v182, s[8:9]
	s_mov_b32 m0, s31
	s_nop 0
	global_load_lds_dwordx4 v226, s[76:77]
	s_mov_b32 m0, s64
	s_nop 0
	global_load_lds_dwordx4 v227, s[76:77]
	s_waitcnt vmcnt(8)
	s_waitcnt lgkmcnt(0)
	s_barrier
; #define PG8_STAGE(bufoff, gbase, voff) do { _Pragma("unroll") for (int _i = 0; _i < 2; ++_i) \
;         __builtin_amdgcn_global_load_lds((const unsigned*)((const char*)(gbase) + (voff)[_i]), (LAS unsigned*)(lds + (bufoff) + ldsw + _i * 8192), 16, 0, 0); } while (0)
; #define PG8_LDA(dst, b, h) do { _Pragma("unroll") for (int m = 0; m < 4; ++m) _Pragma("unroll") for (int k = 0; k < 2; ++k) dst[m][k] = *(const LAS bf16x8*)(lds + PG8_SA(b, h) + aoff + m * 2048 + k * 1024); } while (0)
; #define PG8_LDB(dst, b, h) do { _Pragma("unroll") for (int n = 0; n < 2; ++n) _Pragma("unroll") for (int k = 0; k < 2; ++k) dst[n][k] = *(const LAS bf16x8*)(lds + PG8_SB(b, h) + boff + n * 2048 + k * 1024); } while (0)
; #define PG8_MMA(ai, bj, At, Bt) do { __builtin_amdgcn_s_setprio(1); _Pragma("unroll") for (int m = 0; m < 4; ++m) _Pragma("unroll") for (int n = 0; n < 2; ++n) _Pragma("unroll") for (int k = 0; k < 2; ++k) \
;         acc[ai][bj][m][n] = __builtin_amdgcn_mfma_f32_16x16x32_bf16(Bt[n][k], At[m][k], acc[ai][bj][m][n], 0, 0, 0); __builtin_amdgcn_s_setprio(0); } while (0)
; #define PG8_WAIT_V(n) asm volatile("s_waitcnt vmcnt(" #n ")" ::: "memory")
; #define PG8_WAIT_L(n) asm volatile("s_waitcnt lgkmcnt(" #n ")" ::: "memory")
; #define PG8_BAR __builtin_amdgcn_s_barrier()
; #define PG8_SCHED __builtin_amdgcn_sched_barrier(0)
; template <class Epi, bool ALIGN_EPI, bool SPLITA>
; __device__ __forceinline__ void gemm_phase(LAS unsigned char* lds, const Gemm g, const StaticOrder& S, const Epi& E) {
;     ...
;             PG8_WAIT_V(8); PG8_WAIT_L(0); PG8_BAR; PG8_MMA(1, 0, At, B0); PG8_MMA(1, 1, At, B1); PG8_BAR; PG8_SCHED;
;             PG8_LDB(B0, 1, 0); PG8_LDB(B1, 1, 1); PG8_SCHED; PG8_LDA(At, 1, 0); PG8_STAGE(PG8_SA(0, 1), a2h, vo2);
;             PG8_WAIT_V(8); PG8_WAIT_L(0); PG8_BAR; PG8_MMA(0, 0, At, B0); PG8_MMA(0, 1, At, B1); PG8_BAR; PG8_SCHED;
;             PG8_LDA(At, 1, 1); PG8_STAGE(PG8_SB(1, 0), b3, voffB); PG8_STAGE(PG8_SB(1, 1), b3 + hstepB, voffB); PG8_STAGE(PG8_SA(1, 0), a3, vo2);
	s_setprio 1
	s_waitcnt lgkmcnt(0)
	v_mfma_f32_16x16x32_bf16 v[64:67], v[132:135], v[164:167], v[64:67]
	v_mfma_f32_16x16x32_bf16 v[48:51], v[132:135], v[172:175], v[48:51]
	v_mfma_f32_16x16x32_bf16 v[32:35], v[132:135], v[204:207], v[32:35]
	v_mfma_f32_16x16x32_bf16 v[16:19], v[132:135], v[212:215], v[16:19]
	v_mfma_f32_16x16x32_bf16 v[60:63], v[140:143], v[164:167], v[60:63]
	v_mfma_f32_16x16x32_bf16 v[44:47], v[140:143], v[172:175], v[44:47]
	v_mfma_f32_16x16x32_bf16 v[28:31], v[140:143], v[204:207], v[28:31]
	v_mfma_f32_16x16x32_bf16 v[8:11], v[140:143], v[212:215], v[8:11]
	v_mfma_f32_16x16x32_bf16 v[64:67], v[136:139], v[168:171], v[64:67]
	v_mfma_f32_16x16x32_bf16 v[48:51], v[136:139], v[176:179], v[48:51]
	v_mfma_f32_16x16x32_bf16 v[32:35], v[136:139], v[208:211], v[32:35]
	v_mfma_f32_16x16x32_bf16 v[16:19], v[136:139], v[216:219], v[16:19]
	v_mfma_f32_16x16x32_bf16 v[60:63], v[144:147], v[168:171], v[60:63]
	v_mfma_f32_16x16x32_bf16 v[44:47], v[144:147], v[176:179], v[44:47]
	v_mfma_f32_16x16x32_bf16 v[28:31], v[144:147], v[208:211], v[28:31]
	v_mfma_f32_16x16x32_bf16 v[8:11], v[144:147], v[216:219], v[8:11]
	s_setprio 0
	s_setprio 1
	v_mfma_f32_16x16x32_bf16 v[56:59], v[148:151], v[164:167], v[56:59]
	v_mfma_f32_16x16x32_bf16 v[40:43], v[148:151], v[172:175], v[40:43]
	v_mfma_f32_16x16x32_bf16 v[24:27], v[148:151], v[204:207], v[24:27]
	v_mfma_f32_16x16x32_bf16 v[12:15], v[148:151], v[212:215], v[12:15]
	v_mfma_f32_16x16x32_bf16 v[52:55], v[156:159], v[164:167], v[52:55]
	v_mfma_f32_16x16x32_bf16 v[36:39], v[156:159], v[172:175], v[36:39]
	v_mfma_f32_16x16x32_bf16 v[20:23], v[156:159], v[204:207], v[20:23]
	v_mfma_f32_16x16x32_bf16 v[4:7], v[156:159], v[212:215], v[4:7]
	v_mfma_f32_16x16x32_bf16 v[56:59], v[152:155], v[168:171], v[56:59]
	v_mfma_f32_16x16x32_bf16 v[40:43], v[152:155], v[176:179], v[40:43]
	v_mfma_f32_16x16x32_bf16 v[24:27], v[152:155], v[208:211], v[24:27]
	v_mfma_f32_16x16x32_bf16 v[12:15], v[152:155], v[216:219], v[12:15]
	v_mfma_f32_16x16x32_bf16 v[52:55], v[160:163], v[168:171], v[52:55]
	v_mfma_f32_16x16x32_bf16 v[36:39], v[160:163], v[176:179], v[36:39]
	v_mfma_f32_16x16x32_bf16 v[20:23], v[160:163], v[208:211], v[20:23]
	v_mfma_f32_16x16x32_bf16 v[4:7], v[160:163], v[216:219], v[4:7]
	s_setprio 0
	s_barrier
	s_add_i32 s10, 0, 0x18000
	v_add_u32_e32 v2, s10, v200
	s_add_i32 s43, 0, 0x1c000
	ds_read_b128 v[132:135], v2
	ds_read_b128 v[136:139], v2 offset:1024
	ds_read_b128 v[140:143], v2 offset:2048
	ds_read_b128 v[144:147], v2 offset:3072
	v_add_u32_e32 v2, s43, v200
	ds_read_b128 v[148:151], v2
	ds_read_b128 v[152:155], v2 offset:1024
	ds_read_b128 v[156:159], v2 offset:2048
	ds_read_b128 v[160:163], v2 offset:3072
	s_add_u32 s8, s76, s13
	s_addc_u32 s9, s77, s12
	s_mov_b32 m0, s65
	ds_read_b128 v[164:167], v201 offset:32768
	ds_read_b128 v[168:171], v201 offset:33792
	ds_read_b128 v[172:175], v201 offset:34816
	ds_read_b128 v[176:179], v201 offset:35840
	ds_read_b128 v[204:207], v201 offset:36864
	ds_read_b128 v[208:211], v201 offset:37888
	ds_read_b128 v[212:215], v201 offset:38912
	ds_read_b128 v[216:219], v201 offset:39936
	global_load_lds_dwordx4 v226, s[8:9]
	s_mov_b32 m0, s86
	s_nop 0
	global_load_lds_dwordx4 v227, s[8:9]
	s_waitcnt vmcnt(8)
	s_waitcnt lgkmcnt(0)
	s_barrier
	s_setprio 1
	s_waitcnt lgkmcnt(0)
	v_mfma_f32_16x16x32_bf16 v[128:131], v[132:135], v[164:167], v[128:131]
	v_mfma_f32_16x16x32_bf16 v[112:115], v[132:135], v[172:175], v[112:115]
	v_mfma_f32_16x16x32_bf16 v[96:99], v[132:135], v[204:207], v[96:99]
	v_mfma_f32_16x16x32_bf16 v[80:83], v[132:135], v[212:215], v[80:83]
	v_mfma_f32_16x16x32_bf16 v[124:127], v[140:143], v[164:167], v[124:127]
	v_mfma_f32_16x16x32_bf16 v[108:111], v[140:143], v[172:175], v[108:111]
	v_mfma_f32_16x16x32_bf16 v[92:95], v[140:143], v[204:207], v[92:95]
	v_mfma_f32_16x16x32_bf16 v[76:79], v[140:143], v[212:215], v[76:79]
	v_mfma_f32_16x16x32_bf16 v[128:131], v[136:139], v[168:171], v[128:131]
	v_mfma_f32_16x16x32_bf16 v[112:115], v[136:139], v[176:179], v[112:115]
	v_mfma_f32_16x16x32_bf16 v[96:99], v[136:139], v[208:211], v[96:99]
	v_mfma_f32_16x16x32_bf16 v[80:83], v[136:139], v[216:219], v[80:83]
	v_mfma_f32_16x16x32_bf16 v[124:127], v[144:147], v[168:171], v[124:127]
	v_mfma_f32_16x16x32_bf16 v[108:111], v[144:147], v[176:179], v[108:111]
	v_mfma_f32_16x16x32_bf16 v[92:95], v[144:147], v[208:211], v[92:95]
	v_mfma_f32_16x16x32_bf16 v[76:79], v[144:147], v[216:219], v[76:79]
	s_setprio 0
	s_setprio 1
	v_mfma_f32_16x16x32_bf16 v[120:123], v[148:151], v[164:167], v[120:123]
	v_mfma_f32_16x16x32_bf16 v[104:107], v[148:151], v[172:175], v[104:107]
	v_mfma_f32_16x16x32_bf16 v[88:91], v[148:151], v[204:207], v[88:91]
	v_mfma_f32_16x16x32_bf16 v[72:75], v[148:151], v[212:215], v[72:75]
	v_mfma_f32_16x16x32_bf16 v[116:119], v[156:159], v[164:167], v[116:119]
	v_mfma_f32_16x16x32_bf16 v[100:103], v[156:159], v[172:175], v[100:103]
	v_mfma_f32_16x16x32_bf16 v[84:87], v[156:159], v[204:207], v[84:87]
	v_mfma_f32_16x16x32_bf16 v[68:71], v[156:159], v[212:215], v[68:71]
	v_mfma_f32_16x16x32_bf16 v[120:123], v[152:155], v[168:171], v[120:123]
	v_mfma_f32_16x16x32_bf16 v[104:107], v[152:155], v[176:179], v[104:107]
	v_mfma_f32_16x16x32_bf16 v[88:91], v[152:155], v[208:211], v[88:91]
	v_mfma_f32_16x16x32_bf16 v[72:75], v[152:155], v[216:219], v[72:75]
	v_mfma_f32_16x16x32_bf16 v[116:119], v[160:163], v[168:171], v[116:119]
	v_mfma_f32_16x16x32_bf16 v[100:103], v[160:163], v[176:179], v[100:103]
	v_mfma_f32_16x16x32_bf16 v[84:87], v[160:163], v[208:211], v[84:87]
	v_mfma_f32_16x16x32_bf16 v[68:71], v[160:163], v[216:219], v[68:71]
	s_setprio 0
	s_barrier
; #define PG8_STAGE(bufoff, gbase, voff) do { _Pragma("unroll") for (int _i = 0; _i < 2; ++_i) \
;         __builtin_amdgcn_global_load_lds((const unsigned*)((const char*)(gbase) + (voff)[_i]), (LAS unsigned*)(lds + (bufoff) + ldsw + _i * 8192), 16, 0, 0); } while (0)
; #define PG8_LDA(dst, b, h) do { _Pragma("unroll") for (int m = 0; m < 4; ++m) _Pragma("unroll") for (int k = 0; k < 2; ++k) dst[m][k] = *(const LAS bf16x8*)(lds + PG8_SA(b, h) + aoff + m * 2048 + k * 1024); } while (0)
; #define PG8_MMA(ai, bj, At, Bt) do { __builtin_amdgcn_s_setprio(1); _Pragma("unroll") for (int m = 0; m < 4; ++m) _Pragma("unroll") for (int n = 0; n < 2; ++n) _Pragma("unroll") for (int k = 0; k < 2; ++k) \
;         acc[ai][bj][m][n] = __builtin_amdgcn_mfma_f32_16x16x32_bf16(Bt[n][k], At[m][k], acc[ai][bj][m][n], 0, 0, 0); __builtin_amdgcn_s_setprio(0); } while (0)
; #define PG8_WAIT_V(n) asm volatile("s_waitcnt vmcnt(" #n ")" ::: "memory")
; #define PG8_WAIT_L(n) asm volatile("s_waitcnt lgkmcnt(" #n ")" ::: "memory")
; #define PG8_BAR __builtin_amdgcn_s_barrier()
; #define PG8_SCHED __builtin_amdgcn_sched_barrier(0)
; template <class Epi, bool ALIGN_EPI, bool SPLITA>
; __device__ __forceinline__ void gemm_phase(LAS unsigned char* lds, const Gemm g, const StaticOrder& S, const Epi& E) {
;     ...
;         for (int t = 0; t < nt; t += 2) {
;     ...
;             PG8_LDA(At, 1, 1); PG8_STAGE(PG8_SB(1, 0), b3, voffB); PG8_STAGE(PG8_SB(1, 1), b3 + hstepB, voffB); PG8_STAGE(PG8_SA(1, 0), a3, vo2);
;             PG8_WAIT_V(8); PG8_WAIT_L(0); PG8_BAR; PG8_MMA(1, 0, At, B0); PG8_MMA(1, 1, At, B1); PG8_BAR; PG8_SCHED;
	s_add_i32 s8, s10, s6
	s_mov_b32 m0, s8
	ds_read_b128 v[164:167], v201 offset:49152
	ds_read_b128 v[168:171], v201 offset:50176
	ds_read_b128 v[172:175], v201 offset:51200
	ds_read_b128 v[176:179], v201 offset:52224
	ds_read_b128 v[204:207], v201 offset:53248
	ds_read_b128 v[208:211], v201 offset:54272
	ds_read_b128 v[212:215], v201 offset:55296
	ds_read_b128 v[216:219], v201 offset:56320
	global_load_lds_dwordx4 v180, s[98:99]
	s_add_i32 m0, s8, 0x2000
	s_add_u32 s0, s0, 0x80080
	s_addc_u32 s1, s1, 0
	s_add_i32 s8, s43, s6
	global_load_lds_dwordx4 v182, s[98:99]
	s_mov_b32 m0, s8
	s_nop 0
	global_load_lds_dwordx4 v180, s[0:1]
	s_add_i32 m0, s8, 0x2000
	s_nop 0
	global_load_lds_dwordx4 v182, s[0:1]
	s_mov_b32 m0, s95
	s_nop 0
	global_load_lds_dwordx4 v226, s[78:79]
	s_mov_b32 m0, s96
	s_nop 0
	global_load_lds_dwordx4 v227, s[78:79]
	s_waitcnt vmcnt(8)
	s_waitcnt lgkmcnt(0)
	s_barrier
	s_setprio 1
	s_waitcnt lgkmcnt(0)
	v_mfma_f32_16x16x32_bf16 v[64:67], v[132:135], v[164:167], v[64:67]
	v_mfma_f32_16x16x32_bf16 v[48:51], v[132:135], v[172:175], v[48:51]
	v_mfma_f32_16x16x32_bf16 v[32:35], v[132:135], v[204:207], v[32:35]
	v_mfma_f32_16x16x32_bf16 v[16:19], v[132:135], v[212:215], v[16:19]
	v_mfma_f32_16x16x32_bf16 v[60:63], v[140:143], v[164:167], v[60:63]
	v_mfma_f32_16x16x32_bf16 v[44:47], v[140:143], v[172:175], v[44:47]
	v_mfma_f32_16x16x32_bf16 v[28:31], v[140:143], v[204:207], v[28:31]
	v_mfma_f32_16x16x32_bf16 v[8:11], v[140:143], v[212:215], v[8:11]
	v_mfma_f32_16x16x32_bf16 v[64:67], v[136:139], v[168:171], v[64:67]
	v_mfma_f32_16x16x32_bf16 v[48:51], v[136:139], v[176:179], v[48:51]
	v_mfma_f32_16x16x32_bf16 v[32:35], v[136:139], v[208:211], v[32:35]
	v_mfma_f32_16x16x32_bf16 v[16:19], v[136:139], v[216:219], v[16:19]
	v_mfma_f32_16x16x32_bf16 v[60:63], v[144:147], v[168:171], v[60:63]
	v_mfma_f32_16x16x32_bf16 v[44:47], v[144:147], v[176:179], v[44:47]
	v_mfma_f32_16x16x32_bf16 v[28:31], v[144:147], v[208:211], v[28:31]
	v_mfma_f32_16x16x32_bf16 v[8:11], v[144:147], v[216:219], v[8:11]
	s_setprio 0
	s_setprio 1
	v_mfma_f32_16x16x32_bf16 v[56:59], v[148:151], v[164:167], v[56:59]
	v_mfma_f32_16x16x32_bf16 v[40:43], v[148:151], v[172:175], v[40:43]
	v_mfma_f32_16x16x32_bf16 v[24:27], v[148:151], v[204:207], v[24:27]
	v_mfma_f32_16x16x32_bf16 v[12:15], v[148:151], v[212:215], v[12:15]
	v_mfma_f32_16x16x32_bf16 v[52:55], v[156:159], v[164:167], v[52:55]
	v_mfma_f32_16x16x32_bf16 v[36:39], v[156:159], v[172:175], v[36:39]
	v_mfma_f32_16x16x32_bf16 v[20:23], v[156:159], v[204:207], v[20:23]
	v_mfma_f32_16x16x32_bf16 v[4:7], v[156:159], v[212:215], v[4:7]
	v_mfma_f32_16x16x32_bf16 v[56:59], v[152:155], v[168:171], v[56:59]
	v_mfma_f32_16x16x32_bf16 v[40:43], v[152:155], v[176:179], v[40:43]
	v_mfma_f32_16x16x32_bf16 v[24:27], v[152:155], v[208:211], v[24:27]
	v_mfma_f32_16x16x32_bf16 v[12:15], v[152:155], v[216:219], v[12:15]
	v_mfma_f32_16x16x32_bf16 v[52:55], v[160:163], v[168:171], v[52:55]
	v_mfma_f32_16x16x32_bf16 v[36:39], v[160:163], v[176:179], v[36:39]
	v_mfma_f32_16x16x32_bf16 v[20:23], v[160:163], v[208:211], v[20:23]
	v_mfma_f32_16x16x32_bf16 v[4:7], v[160:163], v[216:219], v[4:7]
	s_setprio 0
	s_barrier
	s_add_i32 s72, s72, 2
	s_add_u32 s74, s74, 0x100
	s_addc_u32 s75, s75, 0
	s_cmp_gt_u32 s37, 29
	s_cbranch_scc1 .LBB0_634

; #define PG8_WAIT_V(n) asm volatile("s_waitcnt vmcnt(" #n ")" ::: "memory")
; #define PG8_BAR __builtin_amdgcn_s_barrier()
; template <class Epi, bool ALIGN_EPI, bool SPLITA>
; __device__ __forceinline__ void gemm_phase(LAS unsigned char* lds, const Gemm g, const StaticOrder& S, const Epi& E) {
;     ...
;         const bool has_next = S.next(ui + 1, nxt);
;         const char* nA = has_next ? baseA1(nxt) : cA;
;         const char* nB = has_next ? baseB(nxt) : cB;
;         const bool mirN = has_next ? mirrored(nxt) : mirC;
;         for (int t = 0; t < nt; t += 2) {
;             const bool last = (t == nt - 2);
;             if constexpr (Epi::MIDK) { if (t == g.ksplit) E.mid(acc, cur, wr, wc, fr, fq); }
;             const char *a1, *a2;
;             if constexpr (SPLITA) {
;                 a1 = (t + 1 < g.ksplit) ? cA + (size_t)(t + 1) * kstep : cA2 + (size_t)(t + 1 - g.ksplit) * 2048;
;                 a2 = last ? nA : ((t + 2 < g.ksplit) ? cA + (size_t)(t + 2) * kstep : cA2 + (size_t)(t + 2 - g.ksplit) * 2048);
;             } else { a1 = cA + kofs(t + 1); a2 = last ? nA : cA + kofs(t + 2); }
;             const char* b2 = last ? nB : cB + (size_t)(t + 2) * kstepB;
;             const bool s2a = SPLITA && (t + 1 >= g.ksplit), s2b = SPLITA && !last && (t + 2 >= g.ksplit);
;             const char* a3 = a2 + ((Epi::KSUB || s2b) ? (size_t)2048 : kstep); const char* b3 = b2 + kstepB;
;             const bool m1 = SPLITA && mirC && (t + 1 < g.ksplit), m2 = SPLITA && (last ? mirN : (mirC && (t + 2 < g.ksplit)));
;             const unsigned vo1[2] = {s2a ? voffA2[0] : m1 ? voffAm[0] : voffA[0], s2a ? voffA2[1] : m1 ? voffAm[1] : voffA[1]}, vo2[2] = {s2b ? voffA2[0] : m2 ? voffAm[0] : voffA[0], s2b ? voffA2[1] : m2 ? voffAm[1] : voffA[1]};
;             const char* a1h = m1 ? a1 - hstepA : a1 + hstepA; const char* a2h = m2 ? a2 - hstepA : a2 + hstepA;
;             PG8_LDB(B0, 0, 0); PG8_LDB(B1, 0, 1); PG8_SCHED; PG8_LDA(At, 0, 0); PG8_STAGE(PG8_SA(1, 1), a1h, vo1);
;             PG8_WAIT_V(8); PG8_WAIT_L(0); PG8_BAR; PG8_MMA(0, 0, At, B0); PG8_MMA(0, 1, At, B1); PG8_BAR; PG8_SCHED;
;             PG8_LDA(At, 0, 1); PG8_STAGE(PG8_SB(0, 0), b2, voffB); PG8_STAGE(PG8_SB(0, 1), b2 + hstepB, voffB); PG8_STAGE(PG8_SA(0, 0), a2, vo2);
;             PG8_WAIT_V(8); PG8_WAIT_L(0); PG8_BAR; PG8_MMA(1, 0, At, B0); PG8_MMA(1, 1, At, B1); PG8_BAR; PG8_SCHED;
.LBB0_708:
	s_ashr_i32 s23, s22, 31
	s_lshl_b64 s[12:13], s[22:23], 19
	s_add_u32 s30, s84, s12
	s_addc_u32 s31, s85, s13
	s_and_b64 s[12:13], s[4:5], exec
	s_cselect_b32 s23, s31, s43
	s_cselect_b32 s39, s30, s42
	s_ashr_i32 s25, s24, 31
	s_lshl_b64 s[12:13], s[24:25], 19
	s_add_u32 s36, s28, s12
	s_addc_u32 s37, s29, s13
	s_and_b64 s[12:13], s[4:5], exec
	s_cselect_b32 s25, s37, s45
	s_cselect_b32 s57, s36, s44
	s_add_u32 s60, s44, 0x100
	s_addc_u32 s61, s45, 0
	s_mov_b32 s44, -2
	s_movk_i32 s64, 0x1000
	s_add_i32 s65, s44, 2
	s_lshr_b32 s8, s65, 2
	s_lshl_b64 s[12:13], s[8:9], 17
	s_add_i32 s8, s64, 0xfffff000
	s_and_b32 s8, s8, 0x1000
	s_add_u32 s12, s42, s12
	s_addc_u32 s13, s43, s13
	s_add_u32 s45, s12, s8
	s_addc_u32 s46, s13, 0
	s_add_i32 s8, s44, 4
	ds_read_b128 v[130:133], v189
	ds_read_b128 v[134:137], v189 offset:1024
	ds_read_b128 v[138:141], v189 offset:2048
	ds_read_b128 v[142:145], v189 offset:3072
	ds_read_b128 v[146:149], v192
	ds_read_b128 v[150:153], v192 offset:1024
	ds_read_b128 v[166:169], v192 offset:2048
	ds_read_b128 v[170:173], v192 offset:3072
	s_lshr_b32 s8, s8, 2
	s_lshl_b64 s[12:13], s[8:9], 17
	s_and_b32 s8, s64, 0x1000
	s_add_u32 s12, s42, s12
	s_addc_u32 s13, s43, s13
	s_add_u32 s8, s12, s8
	s_addc_u32 s47, s13, 0
	s_add_u32 s12, s45, 0x10800
	s_addc_u32 s13, s46, 0
	s_cmp_eq_u32 s44, 12
	s_cselect_b32 s44, s57, s60
	s_cselect_b32 s47, s23, s47
	s_cselect_b32 s46, s39, s8
	s_cselect_b32 s45, s25, s61
	s_add_i32 m0, s7, 0xc000
	ds_read_b128 v[178:181], v193
	ds_read_b128 v[184:187], v193 offset:1024
	ds_read_b128 v[194:197], v193 offset:2048
	ds_read_b128 v[198:201], v193 offset:3072
	ds_read_b128 v[202:205], v193 offset:4096
	ds_read_b128 v[206:209], v193 offset:5120
	ds_read_b128 v[210:213], v193 offset:6144
	ds_read_b128 v[214:217], v193 offset:7168
	global_load_lds_dwordx4 v154, s[12:13]
	s_add_i32 m0, s7, 0xe000
	s_nop 0
	global_load_lds_dwordx4 v158, s[12:13]
	s_waitcnt vmcnt(8)
	s_waitcnt lgkmcnt(0)
	s_barrier
	s_setprio 1
	s_waitcnt lgkmcnt(0)
	v_mfma_f32_16x16x32_bf16 v[126:129], v[130:133], v[178:181], 0
	v_mfma_f32_16x16x32_bf16 v[110:113], v[130:133], v[194:197], 0
	v_mfma_f32_16x16x32_bf16 v[94:97], v[130:133], v[202:205], 0
	v_mfma_f32_16x16x32_bf16 v[78:81], v[130:133], v[210:213], 0
	v_mfma_f32_16x16x32_bf16 v[122:125], v[138:141], v[178:181], 0
	v_mfma_f32_16x16x32_bf16 v[106:109], v[138:141], v[194:197], 0
	v_mfma_f32_16x16x32_bf16 v[90:93], v[138:141], v[202:205], 0
	v_mfma_f32_16x16x32_bf16 v[74:77], v[138:141], v[210:213], 0
	v_mfma_f32_16x16x32_bf16 v[126:129], v[134:137], v[184:187], v[126:129]
	v_mfma_f32_16x16x32_bf16 v[110:113], v[134:137], v[198:201], v[110:113]
	v_mfma_f32_16x16x32_bf16 v[94:97], v[134:137], v[206:209], v[94:97]
	v_mfma_f32_16x16x32_bf16 v[78:81], v[134:137], v[214:217], v[78:81]
	v_mfma_f32_16x16x32_bf16 v[122:125], v[142:145], v[184:187], v[122:125]
	v_mfma_f32_16x16x32_bf16 v[106:109], v[142:145], v[198:201], v[106:109]
	v_mfma_f32_16x16x32_bf16 v[90:93], v[142:145], v[206:209], v[90:93]
	v_mfma_f32_16x16x32_bf16 v[74:77], v[142:145], v[214:217], v[74:77]
	s_setprio 0
	s_setprio 1
	v_mfma_f32_16x16x32_bf16 v[118:121], v[146:149], v[178:181], 0
	v_mfma_f32_16x16x32_bf16 v[102:105], v[146:149], v[194:197], 0
	v_mfma_f32_16x16x32_bf16 v[86:89], v[146:149], v[202:205], 0
	v_mfma_f32_16x16x32_bf16 v[70:73], v[146:149], v[210:213], 0
	v_mfma_f32_16x16x32_bf16 v[114:117], v[166:169], v[178:181], 0
	v_mfma_f32_16x16x32_bf16 v[98:101], v[166:169], v[194:197], 0
	v_mfma_f32_16x16x32_bf16 v[82:85], v[166:169], v[202:205], 0
	v_mfma_f32_16x16x32_bf16 v[66:69], v[166:169], v[210:213], 0
	v_mfma_f32_16x16x32_bf16 v[118:121], v[150:153], v[184:187], v[118:121]
	v_mfma_f32_16x16x32_bf16 v[102:105], v[150:153], v[198:201], v[102:105]
	v_mfma_f32_16x16x32_bf16 v[86:89], v[150:153], v[206:209], v[86:89]
	v_mfma_f32_16x16x32_bf16 v[70:73], v[150:153], v[214:217], v[70:73]
	v_mfma_f32_16x16x32_bf16 v[114:117], v[170:173], v[184:187], v[114:117]
	v_mfma_f32_16x16x32_bf16 v[98:101], v[170:173], v[198:201], v[98:101]
	v_mfma_f32_16x16x32_bf16 v[82:85], v[170:173], v[206:209], v[82:85]
	v_mfma_f32_16x16x32_bf16 v[66:69], v[170:173], v[214:217], v[66:69]
	s_setprio 0
	s_barrier
	s_add_u32 s98, s44, s16
	s_addc_u32 s99, s45, s17
	s_add_u32 s100, s46, s18
	s_addc_u32 s101, s47, s19
	s_add_i32 s8, s54, s6
	s_mov_b32 m0, s8
	ds_read_b128 v[178:181], v193 offset:16384
	ds_read_b128 v[184:187], v193 offset:17408
	ds_read_b128 v[194:197], v193 offset:18432
	ds_read_b128 v[198:201], v193 offset:19456
	ds_read_b128 v[202:205], v193 offset:20480
	ds_read_b128 v[206:209], v193 offset:21504
	ds_read_b128 v[210:213], v193 offset:22528
	ds_read_b128 v[214:217], v193 offset:23552
	global_load_lds_dwordx4 v156, s[44:45]
	s_add_i32 m0, s8, 0x2000
	s_add_u32 s12, s44, 0x40000
	s_addc_u32 s13, s45, 0
	s_add_i32 s8, s55, s6
	global_load_lds_dwordx4 v160, s[44:45]
	s_mov_b32 m0, s8
	s_nop 0
	global_load_lds_dwordx4 v156, s[12:13]
	s_add_i32 m0, s8, 0x2000
	s_nop 0
	global_load_lds_dwordx4 v160, s[12:13]
	s_mov_b32 m0, s7
	s_nop 0
	global_load_lds_dwordx4 v154, s[46:47]
	s_mov_b32 m0, s33
	s_nop 0
	global_load_lds_dwordx4 v158, s[46:47]
	s_waitcnt vmcnt(8)
	s_waitcnt lgkmcnt(0)
	s_barrier
; #define PG8_STAGE(bufoff, gbase, voff) do { _Pragma("unroll") for (int _i = 0; _i < 2; ++_i) \
;         __builtin_amdgcn_global_load_lds((const unsigned*)((const char*)(gbase) + (voff)[_i]), (LAS unsigned*)(lds + (bufoff) + ldsw + _i * 8192), 16, 0, 0); } while (0)
; #define PG8_LDA(dst, b, h) do { _Pragma("unroll") for (int m = 0; m < 4; ++m) _Pragma("unroll") for (int k = 0; k < 2; ++k) dst[m][k] = *(const LAS bf16x8*)(lds + PG8_SA(b, h) + aoff + m * 2048 + k * 1024); } while (0)
; #define PG8_LDB(dst, b, h) do { _Pragma("unroll") for (int n = 0; n < 2; ++n) _Pragma("unroll") for (int k = 0; k < 2; ++k) dst[n][k] = *(const LAS bf16x8*)(lds + PG8_SB(b, h) + boff + n * 2048 + k * 1024); } while (0)
; #define PG8_MMA(ai, bj, At, Bt) do { __builtin_amdgcn_s_setprio(1); _Pragma("unroll") for (int m = 0; m < 4; ++m) _Pragma("unroll") for (int n = 0; n < 2; ++n) _Pragma("unroll") for (int k = 0; k < 2; ++k) \
;         acc[ai][bj][m][n] = __builtin_amdgcn_mfma_f32_16x16x32_bf16(Bt[n][k], At[m][k], acc[ai][bj][m][n], 0, 0, 0); __builtin_amdgcn_s_setprio(0); } while (0)
; #define PG8_WAIT_V(n) asm volatile("s_waitcnt vmcnt(" #n ")" ::: "memory")
; #define PG8_WAIT_L(n) asm volatile("s_waitcnt lgkmcnt(" #n ")" ::: "memory")
; #define PG8_BAR __builtin_amdgcn_s_barrier()
; #define PG8_SCHED __builtin_amdgcn_sched_barrier(0)
; template <class Epi, bool ALIGN_EPI, bool SPLITA>
; __device__ __forceinline__ void gemm_phase(LAS unsigned char* lds, const Gemm g, const StaticOrder& S, const Epi& E) {
;     ...
;             PG8_WAIT_V(8); PG8_WAIT_L(0); PG8_BAR; PG8_MMA(1, 0, At, B0); PG8_MMA(1, 1, At, B1); PG8_BAR; PG8_SCHED;
;             PG8_LDB(B0, 1, 0); PG8_LDB(B1, 1, 1); PG8_SCHED; PG8_LDA(At, 1, 0); PG8_STAGE(PG8_SA(0, 1), a2h, vo2);
;             PG8_WAIT_V(8); PG8_WAIT_L(0); PG8_BAR; PG8_MMA(0, 0, At, B0); PG8_MMA(0, 1, At, B1); PG8_BAR; PG8_SCHED;
	s_setprio 1
	s_waitcnt lgkmcnt(0)
	v_mfma_f32_16x16x32_bf16 v[62:65], v[130:133], v[178:181], 0
	v_mfma_f32_16x16x32_bf16 v[38:41], v[130:133], v[194:197], 0
	v_mfma_f32_16x16x32_bf16 v[22:25], v[130:133], v[202:205], 0
	v_mfma_f32_16x16x32_bf16 v[6:9], v[130:133], v[210:213], 0
	v_mfma_f32_16x16x32_bf16 v[58:61], v[138:141], v[178:181], 0
	v_mfma_f32_16x16x32_bf16 v[34:37], v[138:141], v[194:197], 0
	v_mfma_f32_16x16x32_bf16 v[18:21], v[138:141], v[202:205], 0
	v_mfma_f32_16x16x32_bf16 v[2:5], v[138:141], v[210:213], 0
	v_mfma_f32_16x16x32_bf16 v[62:65], v[134:137], v[184:187], v[62:65]
	v_mfma_f32_16x16x32_bf16 v[38:41], v[134:137], v[198:201], v[38:41]
	v_mfma_f32_16x16x32_bf16 v[22:25], v[134:137], v[206:209], v[22:25]
	v_mfma_f32_16x16x32_bf16 v[6:9], v[134:137], v[214:217], v[6:9]
	v_mfma_f32_16x16x32_bf16 v[58:61], v[142:145], v[184:187], v[58:61]
	v_mfma_f32_16x16x32_bf16 v[34:37], v[142:145], v[198:201], v[34:37]
	v_mfma_f32_16x16x32_bf16 v[18:21], v[142:145], v[206:209], v[18:21]
	v_mfma_f32_16x16x32_bf16 v[2:5], v[142:145], v[214:217], v[2:5]
	s_setprio 0
	s_setprio 1
	v_mfma_f32_16x16x32_bf16 v[54:57], v[146:149], v[178:181], 0
	v_mfma_f32_16x16x32_bf16 v[50:53], v[146:149], v[194:197], 0
	v_mfma_f32_16x16x32_bf16 v[30:33], v[146:149], v[202:205], 0
	v_mfma_f32_16x16x32_bf16 v[14:17], v[146:149], v[210:213], 0
	v_mfma_f32_16x16x32_bf16 v[46:49], v[166:169], v[178:181], 0
	v_mfma_f32_16x16x32_bf16 v[42:45], v[166:169], v[194:197], 0
	v_mfma_f32_16x16x32_bf16 v[26:29], v[166:169], v[202:205], 0
	v_mfma_f32_16x16x32_bf16 v[10:13], v[166:169], v[210:213], 0
	v_mfma_f32_16x16x32_bf16 v[54:57], v[150:153], v[184:187], v[54:57]
	v_mfma_f32_16x16x32_bf16 v[50:53], v[150:153], v[198:201], v[50:53]
	v_mfma_f32_16x16x32_bf16 v[30:33], v[150:153], v[206:209], v[30:33]
	v_mfma_f32_16x16x32_bf16 v[14:17], v[150:153], v[214:217], v[14:17]
	v_mfma_f32_16x16x32_bf16 v[46:49], v[170:173], v[184:187], v[46:49]
	v_mfma_f32_16x16x32_bf16 v[42:45], v[170:173], v[198:201], v[42:45]
	v_mfma_f32_16x16x32_bf16 v[26:29], v[170:173], v[206:209], v[26:29]
	v_mfma_f32_16x16x32_bf16 v[10:13], v[170:173], v[214:217], v[10:13]
	s_setprio 0
	s_barrier
	s_add_i32 s8, 0, 0x18000
	s_add_i32 s70, 0, 0x1c000
	v_add_u32_e32 v142, s8, v177
	v_add_u32_e32 v170, s70, v177
	ds_read_b128 v[130:133], v142
	ds_read_b128 v[134:137], v142 offset:1024
	ds_read_b128 v[138:141], v142 offset:2048
	ds_read_b128 v[142:145], v142 offset:3072
	ds_read_b128 v[146:149], v170
	ds_read_b128 v[150:153], v170 offset:1024
	ds_read_b128 v[166:169], v170 offset:2048
	ds_read_b128 v[170:173], v170 offset:3072
	s_add_u32 s12, s46, 0x10000
	s_addc_u32 s13, s47, 0
	s_mov_b32 m0, s41
	ds_read_b128 v[178:181], v193 offset:32768
	ds_read_b128 v[184:187], v193 offset:33792
	ds_read_b128 v[194:197], v193 offset:34816
	ds_read_b128 v[198:201], v193 offset:35840
	ds_read_b128 v[202:205], v193 offset:36864
	ds_read_b128 v[206:209], v193 offset:37888
	ds_read_b128 v[210:213], v193 offset:38912
	ds_read_b128 v[214:217], v193 offset:39936
	global_load_lds_dwordx4 v154, s[12:13]
	s_mov_b32 m0, s48
	s_nop 0
	global_load_lds_dwordx4 v158, s[12:13]
	s_waitcnt vmcnt(8)
	s_waitcnt lgkmcnt(0)
	s_barrier
	s_setprio 1
	s_waitcnt lgkmcnt(0)
	v_mfma_f32_16x16x32_bf16 v[126:129], v[130:133], v[178:181], v[126:129]
	v_mfma_f32_16x16x32_bf16 v[110:113], v[130:133], v[194:197], v[110:113]
	v_mfma_f32_16x16x32_bf16 v[94:97], v[130:133], v[202:205], v[94:97]
	v_mfma_f32_16x16x32_bf16 v[78:81], v[130:133], v[210:213], v[78:81]
	v_mfma_f32_16x16x32_bf16 v[122:125], v[138:141], v[178:181], v[122:125]
	v_mfma_f32_16x16x32_bf16 v[106:109], v[138:141], v[194:197], v[106:109]
	v_mfma_f32_16x16x32_bf16 v[90:93], v[138:141], v[202:205], v[90:93]
	v_mfma_f32_16x16x32_bf16 v[74:77], v[138:141], v[210:213], v[74:77]
	v_mfma_f32_16x16x32_bf16 v[126:129], v[134:137], v[184:187], v[126:129]
	v_mfma_f32_16x16x32_bf16 v[110:113], v[134:137], v[198:201], v[110:113]
	v_mfma_f32_16x16x32_bf16 v[94:97], v[134:137], v[206:209], v[94:97]
	v_mfma_f32_16x16x32_bf16 v[78:81], v[134:137], v[214:217], v[78:81]
	v_mfma_f32_16x16x32_bf16 v[122:125], v[142:145], v[184:187], v[122:125]
	v_mfma_f32_16x16x32_bf16 v[106:109], v[142:145], v[198:201], v[106:109]
	v_mfma_f32_16x16x32_bf16 v[90:93], v[142:145], v[206:209], v[90:93]
	v_mfma_f32_16x16x32_bf16 v[74:77], v[142:145], v[214:217], v[74:77]
	s_setprio 0
	s_setprio 1
	v_mfma_f32_16x16x32_bf16 v[118:121], v[146:149], v[178:181], v[118:121]
	v_mfma_f32_16x16x32_bf16 v[102:105], v[146:149], v[194:197], v[102:105]
	v_mfma_f32_16x16x32_bf16 v[86:89], v[146:149], v[202:205], v[86:89]
	v_mfma_f32_16x16x32_bf16 v[70:73], v[146:149], v[210:213], v[70:73]
	v_mfma_f32_16x16x32_bf16 v[114:117], v[166:169], v[178:181], v[114:117]
	v_mfma_f32_16x16x32_bf16 v[98:101], v[166:169], v[194:197], v[98:101]
	v_mfma_f32_16x16x32_bf16 v[82:85], v[166:169], v[202:205], v[82:85]
	v_mfma_f32_16x16x32_bf16 v[66:69], v[166:169], v[210:213], v[66:69]
	v_mfma_f32_16x16x32_bf16 v[118:121], v[150:153], v[184:187], v[118:121]
	v_mfma_f32_16x16x32_bf16 v[102:105], v[150:153], v[198:201], v[102:105]
	v_mfma_f32_16x16x32_bf16 v[86:89], v[150:153], v[206:209], v[86:89]
	v_mfma_f32_16x16x32_bf16 v[70:73], v[150:153], v[214:217], v[70:73]
	v_mfma_f32_16x16x32_bf16 v[114:117], v[170:173], v[184:187], v[114:117]
	v_mfma_f32_16x16x32_bf16 v[98:101], v[170:173], v[198:201], v[98:101]
	v_mfma_f32_16x16x32_bf16 v[82:85], v[170:173], v[206:209], v[82:85]
	v_mfma_f32_16x16x32_bf16 v[66:69], v[170:173], v[214:217], v[66:69]
	s_setprio 0
	s_barrier
; #define PG8_STAGE(bufoff, gbase, voff) do { _Pragma("unroll") for (int _i = 0; _i < 2; ++_i) \
;         __builtin_amdgcn_global_load_lds((const unsigned*)((const char*)(gbase) + (voff)[_i]), (LAS unsigned*)(lds + (bufoff) + ldsw + _i * 8192), 16, 0, 0); } while (0)
; #define PG8_WAIT_V(n) asm volatile("s_waitcnt vmcnt(" #n ")" ::: "memory")
; template <class Epi, bool ALIGN_EPI, bool SPLITA>
; __device__ __forceinline__ void gemm_phase(LAS unsigned char* lds, const Gemm g, const StaticOrder& S, const Epi& E) {
;     ...
;         for (int t = 0; t < nt; t += 2) {
;             const bool last = (t == nt - 2);
;             if constexpr (Epi::MIDK) { if (t == g.ksplit) E.mid(acc, cur, wr, wc, fr, fq); }
;             const char *a1, *a2;
;             if constexpr (SPLITA) {
;                 a1 = (t + 1 < g.ksplit) ? cA + (size_t)(t + 1) * kstep : cA2 + (size_t)(t + 1 - g.ksplit) * 2048;
;                 a2 = last ? nA : ((t + 2 < g.ksplit) ? cA + (size_t)(t + 2) * kstep : cA2 + (size_t)(t + 2 - g.ksplit) * 2048);
;             } else { a1 = cA + kofs(t + 1); a2 = last ? nA : cA + kofs(t + 2); }
;             const char* b2 = last ? nB : cB + (size_t)(t + 2) * kstepB;
;             const bool s2a = SPLITA && (t + 1 >= g.ksplit), s2b = SPLITA && !last && (t + 2 >= g.ksplit);
;             const char* a3 = a2 + ((Epi::KSUB || s2b) ? (size_t)2048 : kstep); const char* b3 = b2 + kstepB;
;             const bool m1 = SPLITA && mirC && (t + 1 < g.ksplit), m2 = SPLITA && (last ? mirN : (mirC && (t + 2 < g.ksplit)));
;             const unsigned vo1[2] = {s2a ? voffA2[0] : m1 ? voffAm[0] : voffA[0], s2a ? voffA2[1] : m1 ? voffAm[1] : voffA[1]}, vo2[2] = {s2b ? voffA2[0] : m2 ? voffAm[0] : voffA[0], s2b ? voffA2[1] : m2 ? voffAm[1] : voffA[1]};
;             const char* a1h = m1 ? a1 - hstepA : a1 + hstepA; const char* a2h = m2 ? a2 - hstepA : a2 + hstepA;
;             PG8_LDB(B0, 0, 0); PG8_LDB(B1, 0, 1); PG8_SCHED; PG8_LDA(At, 0, 0); PG8_STAGE(PG8_SA(1, 1), a1h, vo1);
;             PG8_WAIT_V(8); PG8_WAIT_L(0); PG8_BAR; PG8_MMA(0, 0, At, B0); PG8_MMA(0, 1, At, B1); PG8_BAR; PG8_SCHED;
;     ...
;             PG8_LDA(At, 1, 1); PG8_STAGE(PG8_SB(1, 0), b3, voffB); PG8_STAGE(PG8_SB(1, 1), b3 + hstepB, voffB); PG8_STAGE(PG8_SA(1, 0), a3, vo2);
;             PG8_WAIT_V(8); PG8_WAIT_L(0); PG8_BAR; PG8_MMA(1, 0, At, B0); PG8_MMA(1, 1, At, B1); PG8_BAR; PG8_SCHED;
	s_add_i32 s8, s8, s6
	s_mov_b32 m0, s8
	ds_read_b128 v[178:181], v193 offset:49152
	ds_read_b128 v[184:187], v193 offset:50176
	ds_read_b128 v[194:197], v193 offset:51200
	ds_read_b128 v[198:201], v193 offset:52224
	ds_read_b128 v[202:205], v193 offset:53248
	ds_read_b128 v[206:209], v193 offset:54272
	ds_read_b128 v[210:213], v193 offset:55296
	ds_read_b128 v[214:217], v193 offset:56320
	global_load_lds_dwordx4 v156, s[98:99]
	s_add_i32 m0, s8, 0x2000
	s_add_u32 s12, s44, 0x40080
	s_addc_u32 s13, s45, 0
	s_add_i32 s8, s70, s6
	global_load_lds_dwordx4 v160, s[98:99]
	s_mov_b32 m0, s8
	s_nop 0
	global_load_lds_dwordx4 v156, s[12:13]
	s_add_i32 m0, s8, 0x2000
	s_nop 0
	global_load_lds_dwordx4 v160, s[12:13]
	s_mov_b32 m0, s49
	s_nop 0
	global_load_lds_dwordx4 v154, s[100:101]
	s_mov_b32 m0, s50
	s_nop 0
	global_load_lds_dwordx4 v158, s[100:101]
	s_waitcnt vmcnt(8)
	s_waitcnt lgkmcnt(0)
	s_barrier
	s_setprio 1
	s_waitcnt lgkmcnt(0)
	v_mfma_f32_16x16x32_bf16 v[62:65], v[130:133], v[178:181], v[62:65]
	v_mfma_f32_16x16x32_bf16 v[38:41], v[130:133], v[194:197], v[38:41]
	v_mfma_f32_16x16x32_bf16 v[22:25], v[130:133], v[202:205], v[22:25]
	v_mfma_f32_16x16x32_bf16 v[6:9], v[130:133], v[210:213], v[6:9]
	v_mfma_f32_16x16x32_bf16 v[58:61], v[138:141], v[178:181], v[58:61]
	v_mfma_f32_16x16x32_bf16 v[34:37], v[138:141], v[194:197], v[34:37]
	v_mfma_f32_16x16x32_bf16 v[18:21], v[138:141], v[202:205], v[18:21]
	v_mfma_f32_16x16x32_bf16 v[2:5], v[138:141], v[210:213], v[2:5]
	v_mfma_f32_16x16x32_bf16 v[62:65], v[134:137], v[184:187], v[62:65]
	v_mfma_f32_16x16x32_bf16 v[38:41], v[134:137], v[198:201], v[38:41]
	v_mfma_f32_16x16x32_bf16 v[22:25], v[134:137], v[206:209], v[22:25]
	v_mfma_f32_16x16x32_bf16 v[6:9], v[134:137], v[214:217], v[6:9]
	v_mfma_f32_16x16x32_bf16 v[58:61], v[142:145], v[184:187], v[58:61]
	v_mfma_f32_16x16x32_bf16 v[34:37], v[142:145], v[198:201], v[34:37]
	v_mfma_f32_16x16x32_bf16 v[18:21], v[142:145], v[206:209], v[18:21]
	v_mfma_f32_16x16x32_bf16 v[2:5], v[142:145], v[214:217], v[2:5]
	s_setprio 0
	s_setprio 1
	v_mfma_f32_16x16x32_bf16 v[54:57], v[146:149], v[178:181], v[54:57]
	v_mfma_f32_16x16x32_bf16 v[50:53], v[146:149], v[194:197], v[50:53]
	v_mfma_f32_16x16x32_bf16 v[30:33], v[146:149], v[202:205], v[30:33]
	v_mfma_f32_16x16x32_bf16 v[14:17], v[146:149], v[210:213], v[14:17]
	v_mfma_f32_16x16x32_bf16 v[46:49], v[166:169], v[178:181], v[46:49]
	v_mfma_f32_16x16x32_bf16 v[42:45], v[166:169], v[194:197], v[42:45]
	v_mfma_f32_16x16x32_bf16 v[26:29], v[166:169], v[202:205], v[26:29]
	v_mfma_f32_16x16x32_bf16 v[10:13], v[166:169], v[210:213], v[10:13]
	v_mfma_f32_16x16x32_bf16 v[54:57], v[150:153], v[184:187], v[54:57]
	v_mfma_f32_16x16x32_bf16 v[50:53], v[150:153], v[198:201], v[50:53]
	v_mfma_f32_16x16x32_bf16 v[30:33], v[150:153], v[206:209], v[30:33]
	v_mfma_f32_16x16x32_bf16 v[14:17], v[150:153], v[214:217], v[14:17]
	v_mfma_f32_16x16x32_bf16 v[46:49], v[170:173], v[184:187], v[46:49]
	v_mfma_f32_16x16x32_bf16 v[42:45], v[170:173], v[198:201], v[42:45]
	v_mfma_f32_16x16x32_bf16 v[26:29], v[170:173], v[206:209], v[26:29]
	v_mfma_f32_16x16x32_bf16 v[10:13], v[170:173], v[214:217], v[10:13]
	s_setprio 0
	s_barrier
	s_add_u32 s60, s60, 0x100
	s_addc_u32 s61, s61, 0
	s_addk_i32 s64, 0x1000
	s_mov_b32 s44, s65
.LBB0_709:
	s_add_i32 s65, s44, 2
	s_lshr_b32 s8, s65, 2
	s_lshl_b64 s[12:13], s[8:9], 17
	s_add_i32 s8, s64, 0xfffff000
	s_and_b32 s8, s8, 0x1000
	s_add_u32 s12, s42, s12
	s_addc_u32 s13, s43, s13
	s_add_u32 s45, s12, s8
	s_addc_u32 s46, s13, 0
	s_add_i32 s8, s44, 4
	ds_read_b128 v[130:133], v189
	ds_read_b128 v[134:137], v189 offset:1024
	ds_read_b128 v[138:141], v189 offset:2048
	ds_read_b128 v[142:145], v189 offset:3072
	ds_read_b128 v[146:149], v192
	ds_read_b128 v[150:153], v192 offset:1024
	ds_read_b128 v[166:169], v192 offset:2048
	ds_read_b128 v[170:173], v192 offset:3072
	s_lshr_b32 s8, s8, 2
	s_lshl_b64 s[12:13], s[8:9], 17
	s_and_b32 s8, s64, 0x1000
	s_add_u32 s12, s42, s12
	s_addc_u32 s13, s43, s13
	s_add_u32 s8, s12, s8
	s_addc_u32 s47, s13, 0
	s_add_u32 s12, s45, 0x10800
	s_addc_u32 s13, s46, 0
	s_cmp_eq_u32 s44, 12
	s_cselect_b32 s44, s57, s60
	s_cselect_b32 s47, s23, s47
	s_cselect_b32 s46, s39, s8
	s_cselect_b32 s45, s25, s61
	s_add_i32 m0, s7, 0xc000
	ds_read_b128 v[178:181], v193
	ds_read_b128 v[184:187], v193 offset:1024
	ds_read_b128 v[194:197], v193 offset:2048
	ds_read_b128 v[198:201], v193 offset:3072
	ds_read_b128 v[202:205], v193 offset:4096
	ds_read_b128 v[206:209], v193 offset:5120
	ds_read_b128 v[210:213], v193 offset:6144
	ds_read_b128 v[214:217], v193 offset:7168
	global_load_lds_dwordx4 v154, s[12:13]
	s_add_i32 m0, s7, 0xe000
	s_nop 0
	global_load_lds_dwordx4 v158, s[12:13]
	s_waitcnt vmcnt(8)
	s_waitcnt lgkmcnt(0)
	s_barrier
; #define PG8_STAGE(bufoff, gbase, voff) do { _Pragma("unroll") for (int _i = 0; _i < 2; ++_i) \
;         __builtin_amdgcn_global_load_lds((const unsigned*)((const char*)(gbase) + (voff)[_i]), (LAS unsigned*)(lds + (bufoff) + ldsw + _i * 8192), 16, 0, 0); } while (0)
; #define PG8_LDA(dst, b, h) do { _Pragma("unroll") for (int m = 0; m < 4; ++m) _Pragma("unroll") for (int k = 0; k < 2; ++k) dst[m][k] = *(const LAS bf16x8*)(lds + PG8_SA(b, h) + aoff + m * 2048 + k * 1024); } while (0)
; #define PG8_LDB(dst, b, h) do { _Pragma("unroll") for (int n = 0; n < 2; ++n) _Pragma("unroll") for (int k = 0; k < 2; ++k) dst[n][k] = *(const LAS bf16x8*)(lds + PG8_SB(b, h) + boff + n * 2048 + k * 1024); } while (0)
; #define PG8_MMA(ai, bj, At, Bt) do { __builtin_amdgcn_s_setprio(1); _Pragma("unroll") for (int m = 0; m < 4; ++m) _Pragma("unroll") for (int n = 0; n < 2; ++n) _Pragma("unroll") for (int k = 0; k < 2; ++k) \
;         acc[ai][bj][m][n] = __builtin_amdgcn_mfma_f32_16x16x32_bf16(Bt[n][k], At[m][k], acc[ai][bj][m][n], 0, 0, 0); __builtin_amdgcn_s_setprio(0); } while (0)
; #define PG8_WAIT_V(n) asm volatile("s_waitcnt vmcnt(" #n ")" ::: "memory")
; #define PG8_WAIT_L(n) asm volatile("s_waitcnt lgkmcnt(" #n ")" ::: "memory")
; #define PG8_BAR __builtin_amdgcn_s_barrier()
; #define PG8_SCHED __builtin_amdgcn_sched_barrier(0)
; template <class Epi, bool ALIGN_EPI, bool SPLITA>
; __device__ __forceinline__ void gemm_phase(LAS unsigned char* lds, const Gemm g, const StaticOrder& S, const Epi& E) {
;     ...
;             PG8_WAIT_V(8); PG8_WAIT_L(0); PG8_BAR; PG8_MMA(0, 0, At, B0); PG8_MMA(0, 1, At, B1); PG8_BAR; PG8_SCHED;
;             PG8_LDA(At, 0, 1); PG8_STAGE(PG8_SB(0, 0), b2, voffB); PG8_STAGE(PG8_SB(0, 1), b2 + hstepB, voffB); PG8_STAGE(PG8_SA(0, 0), a2, vo2);
;             PG8_WAIT_V(8); PG8_WAIT_L(0); PG8_BAR; PG8_MMA(1, 0, At, B0); PG8_MMA(1, 1, At, B1); PG8_BAR; PG8_SCHED;
;             PG8_LDB(B0, 1, 0); PG8_LDB(B1, 1, 1); PG8_SCHED; PG8_LDA(At, 1, 0); PG8_STAGE(PG8_SA(0, 1), a2h, vo2);
;             PG8_WAIT_V(8); PG8_WAIT_L(0); PG8_BAR; PG8_MMA(0, 0, At, B0); PG8_MMA(0, 1, At, B1); PG8_BAR; PG8_SCHED;
	s_setprio 1
	s_waitcnt lgkmcnt(0)
	v_mfma_f32_16x16x32_bf16 v[126:129], v[130:133], v[178:181], v[126:129]
	v_mfma_f32_16x16x32_bf16 v[110:113], v[130:133], v[194:197], v[110:113]
	v_mfma_f32_16x16x32_bf16 v[94:97], v[130:133], v[202:205], v[94:97]
	v_mfma_f32_16x16x32_bf16 v[78:81], v[130:133], v[210:213], v[78:81]
	v_mfma_f32_16x16x32_bf16 v[122:125], v[138:141], v[178:181], v[122:125]
	v_mfma_f32_16x16x32_bf16 v[106:109], v[138:141], v[194:197], v[106:109]
	v_mfma_f32_16x16x32_bf16 v[90:93], v[138:141], v[202:205], v[90:93]
	v_mfma_f32_16x16x32_bf16 v[74:77], v[138:141], v[210:213], v[74:77]
	v_mfma_f32_16x16x32_bf16 v[126:129], v[134:137], v[184:187], v[126:129]
	v_mfma_f32_16x16x32_bf16 v[110:113], v[134:137], v[198:201], v[110:113]
	v_mfma_f32_16x16x32_bf16 v[94:97], v[134:137], v[206:209], v[94:97]
	v_mfma_f32_16x16x32_bf16 v[78:81], v[134:137], v[214:217], v[78:81]
	v_mfma_f32_16x16x32_bf16 v[122:125], v[142:145], v[184:187], v[122:125]
	v_mfma_f32_16x16x32_bf16 v[106:109], v[142:145], v[198:201], v[106:109]
	v_mfma_f32_16x16x32_bf16 v[90:93], v[142:145], v[206:209], v[90:93]
	v_mfma_f32_16x16x32_bf16 v[74:77], v[142:145], v[214:217], v[74:77]
	s_setprio 0
	s_setprio 1
	v_mfma_f32_16x16x32_bf16 v[118:121], v[146:149], v[178:181], v[118:121]
	v_mfma_f32_16x16x32_bf16 v[102:105], v[146:149], v[194:197], v[102:105]
	v_mfma_f32_16x16x32_bf16 v[86:89], v[146:149], v[202:205], v[86:89]
	v_mfma_f32_16x16x32_bf16 v[70:73], v[146:149], v[210:213], v[70:73]
	v_mfma_f32_16x16x32_bf16 v[114:117], v[166:169], v[178:181], v[114:117]
	v_mfma_f32_16x16x32_bf16 v[98:101], v[166:169], v[194:197], v[98:101]
	v_mfma_f32_16x16x32_bf16 v[82:85], v[166:169], v[202:205], v[82:85]
	v_mfma_f32_16x16x32_bf16 v[66:69], v[166:169], v[210:213], v[66:69]
	v_mfma_f32_16x16x32_bf16 v[118:121], v[150:153], v[184:187], v[118:121]
	v_mfma_f32_16x16x32_bf16 v[102:105], v[150:153], v[198:201], v[102:105]
	v_mfma_f32_16x16x32_bf16 v[86:89], v[150:153], v[206:209], v[86:89]
	v_mfma_f32_16x16x32_bf16 v[70:73], v[150:153], v[214:217], v[70:73]
	v_mfma_f32_16x16x32_bf16 v[114:117], v[170:173], v[184:187], v[114:117]
	v_mfma_f32_16x16x32_bf16 v[98:101], v[170:173], v[198:201], v[98:101]
	v_mfma_f32_16x16x32_bf16 v[82:85], v[170:173], v[206:209], v[82:85]
	v_mfma_f32_16x16x32_bf16 v[66:69], v[170:173], v[214:217], v[66:69]
	s_setprio 0
	s_barrier
	s_add_u32 s98, s44, s16
	s_addc_u32 s99, s45, s17
	s_add_u32 s100, s46, s18
	s_addc_u32 s101, s47, s19
	s_add_i32 s8, s54, s6
	s_mov_b32 m0, s8
	ds_read_b128 v[178:181], v193 offset:16384
	ds_read_b128 v[184:187], v193 offset:17408
	ds_read_b128 v[194:197], v193 offset:18432
	ds_read_b128 v[198:201], v193 offset:19456
	ds_read_b128 v[202:205], v193 offset:20480
	ds_read_b128 v[206:209], v193 offset:21504
	ds_read_b128 v[210:213], v193 offset:22528
	ds_read_b128 v[214:217], v193 offset:23552
	global_load_lds_dwordx4 v156, s[44:45]
	s_add_i32 m0, s8, 0x2000
	s_add_u32 s12, s44, 0x40000
	s_addc_u32 s13, s45, 0
	s_add_i32 s8, s55, s6
	global_load_lds_dwordx4 v160, s[44:45]
	s_mov_b32 m0, s8
	s_nop 0
	global_load_lds_dwordx4 v156, s[12:13]
	s_add_i32 m0, s8, 0x2000
	s_nop 0
	global_load_lds_dwordx4 v160, s[12:13]
	s_mov_b32 m0, s7
	s_nop 0
	global_load_lds_dwordx4 v154, s[46:47]
	s_mov_b32 m0, s33
	s_nop 0
	global_load_lds_dwordx4 v158, s[46:47]
	s_waitcnt vmcnt(8)
	s_waitcnt lgkmcnt(0)
	s_barrier
	s_setprio 1
	s_waitcnt lgkmcnt(0)
	v_mfma_f32_16x16x32_bf16 v[62:65], v[130:133], v[178:181], v[62:65]
	v_mfma_f32_16x16x32_bf16 v[38:41], v[130:133], v[194:197], v[38:41]
	v_mfma_f32_16x16x32_bf16 v[22:25], v[130:133], v[202:205], v[22:25]
	v_mfma_f32_16x16x32_bf16 v[6:9], v[130:133], v[210:213], v[6:9]
	v_mfma_f32_16x16x32_bf16 v[58:61], v[138:141], v[178:181], v[58:61]
	v_mfma_f32_16x16x32_bf16 v[34:37], v[138:141], v[194:197], v[34:37]
	v_mfma_f32_16x16x32_bf16 v[18:21], v[138:141], v[202:205], v[18:21]
	v_mfma_f32_16x16x32_bf16 v[2:5], v[138:141], v[210:213], v[2:5]
	v_mfma_f32_16x16x32_bf16 v[62:65], v[134:137], v[184:187], v[62:65]
	v_mfma_f32_16x16x32_bf16 v[38:41], v[134:137], v[198:201], v[38:41]
	v_mfma_f32_16x16x32_bf16 v[22:25], v[134:137], v[206:209], v[22:25]
	v_mfma_f32_16x16x32_bf16 v[6:9], v[134:137], v[214:217], v[6:9]
	v_mfma_f32_16x16x32_bf16 v[58:61], v[142:145], v[184:187], v[58:61]
	v_mfma_f32_16x16x32_bf16 v[34:37], v[142:145], v[198:201], v[34:37]
	v_mfma_f32_16x16x32_bf16 v[18:21], v[142:145], v[206:209], v[18:21]
	v_mfma_f32_16x16x32_bf16 v[2:5], v[142:145], v[214:217], v[2:5]
	s_setprio 0
	s_setprio 1
	v_mfma_f32_16x16x32_bf16 v[54:57], v[146:149], v[178:181], v[54:57]
	v_mfma_f32_16x16x32_bf16 v[50:53], v[146:149], v[194:197], v[50:53]
	v_mfma_f32_16x16x32_bf16 v[30:33], v[146:149], v[202:205], v[30:33]
	v_mfma_f32_16x16x32_bf16 v[14:17], v[146:149], v[210:213], v[14:17]
	v_mfma_f32_16x16x32_bf16 v[46:49], v[166:169], v[178:181], v[46:49]
	v_mfma_f32_16x16x32_bf16 v[42:45], v[166:169], v[194:197], v[42:45]
	v_mfma_f32_16x16x32_bf16 v[26:29], v[166:169], v[202:205], v[26:29]
	v_mfma_f32_16x16x32_bf16 v[10:13], v[166:169], v[210:213], v[10:13]
	v_mfma_f32_16x16x32_bf16 v[54:57], v[150:153], v[184:187], v[54:57]
	v_mfma_f32_16x16x32_bf16 v[50:53], v[150:153], v[198:201], v[50:53]
	v_mfma_f32_16x16x32_bf16 v[30:33], v[150:153], v[206:209], v[30:33]
	v_mfma_f32_16x16x32_bf16 v[14:17], v[150:153], v[214:217], v[14:17]
	v_mfma_f32_16x16x32_bf16 v[46:49], v[170:173], v[184:187], v[46:49]
	v_mfma_f32_16x16x32_bf16 v[42:45], v[170:173], v[198:201], v[42:45]
	v_mfma_f32_16x16x32_bf16 v[26:29], v[170:173], v[206:209], v[26:29]
	v_mfma_f32_16x16x32_bf16 v[10:13], v[170:173], v[214:217], v[10:13]
	s_setprio 0
	s_barrier
; #define PG8_STAGE(bufoff, gbase, voff) do { _Pragma("unroll") for (int _i = 0; _i < 2; ++_i) \
;         __builtin_amdgcn_global_load_lds((const unsigned*)((const char*)(gbase) + (voff)[_i]), (LAS unsigned*)(lds + (bufoff) + ldsw + _i * 8192), 16, 0, 0); } while (0)
; #define PG8_LDA(dst, b, h) do { _Pragma("unroll") for (int m = 0; m < 4; ++m) _Pragma("unroll") for (int k = 0; k < 2; ++k) dst[m][k] = *(const LAS bf16x8*)(lds + PG8_SA(b, h) + aoff + m * 2048 + k * 1024); } while (0)
; #define PG8_LDB(dst, b, h) do { _Pragma("unroll") for (int n = 0; n < 2; ++n) _Pragma("unroll") for (int k = 0; k < 2; ++k) dst[n][k] = *(const LAS bf16x8*)(lds + PG8_SB(b, h) + boff + n * 2048 + k * 1024); } while (0)
; #define PG8_MMA(ai, bj, At, Bt) do { __builtin_amdgcn_s_setprio(1); _Pragma("unroll") for (int m = 0; m < 4; ++m) _Pragma("unroll") for (int n = 0; n < 2; ++n) _Pragma("unroll") for (int k = 0; k < 2; ++k) \
;         acc[ai][bj][m][n] = __builtin_amdgcn_mfma_f32_16x16x32_bf16(Bt[n][k], At[m][k], acc[ai][bj][m][n], 0, 0, 0); __builtin_amdgcn_s_setprio(0); } while (0)
; #define PG8_WAIT_V(n) asm volatile("s_waitcnt vmcnt(" #n ")" ::: "memory")
; #define PG8_WAIT_L(n) asm volatile("s_waitcnt lgkmcnt(" #n ")" ::: "memory")
; #define PG8_BAR __builtin_amdgcn_s_barrier()
; #define PG8_SCHED __builtin_amdgcn_sched_barrier(0)
; template <class Epi, bool ALIGN_EPI, bool SPLITA>
; __device__ __forceinline__ void gemm_phase(LAS unsigned char* lds, const Gemm g, const StaticOrder& S, const Epi& E) {
;     ...
;         for (int t = 0; t < nt; t += 2) {
;     ...
;             PG8_LDB(B0, 1, 0); PG8_LDB(B1, 1, 1); PG8_SCHED; PG8_LDA(At, 1, 0); PG8_STAGE(PG8_SA(0, 1), a2h, vo2);
;             PG8_WAIT_V(8); PG8_WAIT_L(0); PG8_BAR; PG8_MMA(0, 0, At, B0); PG8_MMA(0, 1, At, B1); PG8_BAR; PG8_SCHED;
;             PG8_LDA(At, 1, 1); PG8_STAGE(PG8_SB(1, 0), b3, voffB); PG8_STAGE(PG8_SB(1, 1), b3 + hstepB, voffB); PG8_STAGE(PG8_SA(1, 0), a3, vo2);
;             PG8_WAIT_V(8); PG8_WAIT_L(0); PG8_BAR; PG8_MMA(1, 0, At, B0); PG8_MMA(1, 1, At, B1); PG8_BAR; PG8_SCHED;
	s_add_i32 s8, 0, 0x18000
	s_add_i32 s70, 0, 0x1c000
	v_add_u32_e32 v142, s8, v177
	v_add_u32_e32 v170, s70, v177
	ds_read_b128 v[130:133], v142
	ds_read_b128 v[134:137], v142 offset:1024
	ds_read_b128 v[138:141], v142 offset:2048
	ds_read_b128 v[142:145], v142 offset:3072
	ds_read_b128 v[146:149], v170
	ds_read_b128 v[150:153], v170 offset:1024
	ds_read_b128 v[166:169], v170 offset:2048
	ds_read_b128 v[170:173], v170 offset:3072
	s_add_u32 s12, s46, 0x10000
	s_addc_u32 s13, s47, 0
	s_mov_b32 m0, s41
	ds_read_b128 v[178:181], v193 offset:32768
	ds_read_b128 v[184:187], v193 offset:33792
	ds_read_b128 v[194:197], v193 offset:34816
	ds_read_b128 v[198:201], v193 offset:35840
	ds_read_b128 v[202:205], v193 offset:36864
	ds_read_b128 v[206:209], v193 offset:37888
	ds_read_b128 v[210:213], v193 offset:38912
	ds_read_b128 v[214:217], v193 offset:39936
	global_load_lds_dwordx4 v154, s[12:13]
	s_mov_b32 m0, s48
	s_nop 0
	global_load_lds_dwordx4 v158, s[12:13]
	s_waitcnt vmcnt(8)
	s_waitcnt lgkmcnt(0)
	s_barrier
	s_setprio 1
	s_waitcnt lgkmcnt(0)
	v_mfma_f32_16x16x32_bf16 v[126:129], v[130:133], v[178:181], v[126:129]
	v_mfma_f32_16x16x32_bf16 v[110:113], v[130:133], v[194:197], v[110:113]
	v_mfma_f32_16x16x32_bf16 v[94:97], v[130:133], v[202:205], v[94:97]
	v_mfma_f32_16x16x32_bf16 v[78:81], v[130:133], v[210:213], v[78:81]
	v_mfma_f32_16x16x32_bf16 v[122:125], v[138:141], v[178:181], v[122:125]
	v_mfma_f32_16x16x32_bf16 v[106:109], v[138:141], v[194:197], v[106:109]
	v_mfma_f32_16x16x32_bf16 v[90:93], v[138:141], v[202:205], v[90:93]
	v_mfma_f32_16x16x32_bf16 v[74:77], v[138:141], v[210:213], v[74:77]
	v_mfma_f32_16x16x32_bf16 v[126:129], v[134:137], v[184:187], v[126:129]
	v_mfma_f32_16x16x32_bf16 v[110:113], v[134:137], v[198:201], v[110:113]
	v_mfma_f32_16x16x32_bf16 v[94:97], v[134:137], v[206:209], v[94:97]
	v_mfma_f32_16x16x32_bf16 v[78:81], v[134:137], v[214:217], v[78:81]
	v_mfma_f32_16x16x32_bf16 v[122:125], v[142:145], v[184:187], v[122:125]
	v_mfma_f32_16x16x32_bf16 v[106:109], v[142:145], v[198:201], v[106:109]
	v_mfma_f32_16x16x32_bf16 v[90:93], v[142:145], v[206:209], v[90:93]
	v_mfma_f32_16x16x32_bf16 v[74:77], v[142:145], v[214:217], v[74:77]
	s_setprio 0
	s_setprio 1
	v_mfma_f32_16x16x32_bf16 v[118:121], v[146:149], v[178:181], v[118:121]
	v_mfma_f32_16x16x32_bf16 v[102:105], v[146:149], v[194:197], v[102:105]
	v_mfma_f32_16x16x32_bf16 v[86:89], v[146:149], v[202:205], v[86:89]
	v_mfma_f32_16x16x32_bf16 v[70:73], v[146:149], v[210:213], v[70:73]
	v_mfma_f32_16x16x32_bf16 v[114:117], v[166:169], v[178:181], v[114:117]
	v_mfma_f32_16x16x32_bf16 v[98:101], v[166:169], v[194:197], v[98:101]
	v_mfma_f32_16x16x32_bf16 v[82:85], v[166:169], v[202:205], v[82:85]
	v_mfma_f32_16x16x32_bf16 v[66:69], v[166:169], v[210:213], v[66:69]
	v_mfma_f32_16x16x32_bf16 v[118:121], v[150:153], v[184:187], v[118:121]
	v_mfma_f32_16x16x32_bf16 v[102:105], v[150:153], v[198:201], v[102:105]
	v_mfma_f32_16x16x32_bf16 v[86:89], v[150:153], v[206:209], v[86:89]
	v_mfma_f32_16x16x32_bf16 v[70:73], v[150:153], v[214:217], v[70:73]
	v_mfma_f32_16x16x32_bf16 v[114:117], v[170:173], v[184:187], v[114:117]
	v_mfma_f32_16x16x32_bf16 v[98:101], v[170:173], v[198:201], v[98:101]
	v_mfma_f32_16x16x32_bf16 v[82:85], v[170:173], v[206:209], v[82:85]
	v_mfma_f32_16x16x32_bf16 v[66:69], v[170:173], v[214:217], v[66:69]
	s_setprio 0
	s_barrier
	s_add_i32 s8, s8, s6
	s_mov_b32 m0, s8
	ds_read_b128 v[178:181], v193 offset:49152
	ds_read_b128 v[184:187], v193 offset:50176
	ds_read_b128 v[194:197], v193 offset:51200
	ds_read_b128 v[198:201], v193 offset:52224
	ds_read_b128 v[202:205], v193 offset:53248
	ds_read_b128 v[206:209], v193 offset:54272
	ds_read_b128 v[210:213], v193 offset:55296
	ds_read_b128 v[214:217], v193 offset:56320
	global_load_lds_dwordx4 v156, s[98:99]
	s_add_i32 m0, s8, 0x2000
	s_add_u32 s12, s44, 0x40080
	s_addc_u32 s13, s45, 0
	s_add_i32 s8, s70, s6
	global_load_lds_dwordx4 v160, s[98:99]
	s_mov_b32 m0, s8
	s_nop 0
	global_load_lds_dwordx4 v156, s[12:13]
	s_add_i32 m0, s8, 0x2000
	s_nop 0
	global_load_lds_dwordx4 v160, s[12:13]
	s_mov_b32 m0, s49
	s_nop 0
	global_load_lds_dwordx4 v154, s[100:101]
	s_mov_b32 m0, s50
	s_nop 0
	global_load_lds_dwordx4 v158, s[100:101]
	s_waitcnt vmcnt(8)
	s_waitcnt lgkmcnt(0)
	s_barrier
	s_setprio 1
	s_waitcnt lgkmcnt(0)
	v_mfma_f32_16x16x32_bf16 v[62:65], v[130:133], v[178:181], v[62:65]
	v_mfma_f32_16x16x32_bf16 v[38:41], v[130:133], v[194:197], v[38:41]
	v_mfma_f32_16x16x32_bf16 v[22:25], v[130:133], v[202:205], v[22:25]
	v_mfma_f32_16x16x32_bf16 v[6:9], v[130:133], v[210:213], v[6:9]
	v_mfma_f32_16x16x32_bf16 v[58:61], v[138:141], v[178:181], v[58:61]
	v_mfma_f32_16x16x32_bf16 v[34:37], v[138:141], v[194:197], v[34:37]
	v_mfma_f32_16x16x32_bf16 v[18:21], v[138:141], v[202:205], v[18:21]
	v_mfma_f32_16x16x32_bf16 v[2:5], v[138:141], v[210:213], v[2:5]
	v_mfma_f32_16x16x32_bf16 v[62:65], v[134:137], v[184:187], v[62:65]
	v_mfma_f32_16x16x32_bf16 v[38:41], v[134:137], v[198:201], v[38:41]
	v_mfma_f32_16x16x32_bf16 v[22:25], v[134:137], v[206:209], v[22:25]
	v_mfma_f32_16x16x32_bf16 v[6:9], v[134:137], v[214:217], v[6:9]
	v_mfma_f32_16x16x32_bf16 v[58:61], v[142:145], v[184:187], v[58:61]
	v_mfma_f32_16x16x32_bf16 v[34:37], v[142:145], v[198:201], v[34:37]
	v_mfma_f32_16x16x32_bf16 v[18:21], v[142:145], v[206:209], v[18:21]
	v_mfma_f32_16x16x32_bf16 v[2:5], v[142:145], v[214:217], v[2:5]
	s_setprio 0
	s_setprio 1
	v_mfma_f32_16x16x32_bf16 v[54:57], v[146:149], v[178:181], v[54:57]
	v_mfma_f32_16x16x32_bf16 v[50:53], v[146:149], v[194:197], v[50:53]
	v_mfma_f32_16x16x32_bf16 v[30:33], v[146:149], v[202:205], v[30:33]
	v_mfma_f32_16x16x32_bf16 v[14:17], v[146:149], v[210:213], v[14:17]
	v_mfma_f32_16x16x32_bf16 v[46:49], v[166:169], v[178:181], v[46:49]
	v_mfma_f32_16x16x32_bf16 v[42:45], v[166:169], v[194:197], v[42:45]
	v_mfma_f32_16x16x32_bf16 v[26:29], v[166:169], v[202:205], v[26:29]
	v_mfma_f32_16x16x32_bf16 v[10:13], v[166:169], v[210:213], v[10:13]
	v_mfma_f32_16x16x32_bf16 v[54:57], v[150:153], v[184:187], v[54:57]
	v_mfma_f32_16x16x32_bf16 v[50:53], v[150:153], v[198:201], v[50:53]
	v_mfma_f32_16x16x32_bf16 v[30:33], v[150:153], v[206:209], v[30:33]
	v_mfma_f32_16x16x32_bf16 v[14:17], v[150:153], v[214:217], v[14:17]
	v_mfma_f32_16x16x32_bf16 v[46:49], v[170:173], v[184:187], v[46:49]
	v_mfma_f32_16x16x32_bf16 v[42:45], v[170:173], v[198:201], v[42:45]
	v_mfma_f32_16x16x32_bf16 v[26:29], v[170:173], v[206:209], v[26:29]
	v_mfma_f32_16x16x32_bf16 v[10:13], v[170:173], v[214:217], v[10:13]
	s_setprio 0
	s_barrier
	s_add_u32 s60, s60, 0x100
	s_addc_u32 s61, s61, 0
	s_addk_i32 s64, 0x1000
	s_cmp_gt_u32 s65, 13
	s_mov_b32 s44, s65
	s_cbranch_scc0 .LBB0_709
	s_and_b64 vcc, exec, s[20:21]
	s_cbranch_vccz .LBB0_712
	s_barrier

; #define PG8_WAIT_V(n) asm volatile("s_waitcnt vmcnt(" #n ")" ::: "memory")
; #define PG8_BAR __builtin_amdgcn_s_barrier()
; template <class Epi, bool ALIGN_EPI, bool SPLITA>
; __device__ __forceinline__ void gemm_phase(LAS unsigned char* lds, const Gemm g, const StaticOrder& S, const Epi& E) {
;     ...
;         const bool has_next = S.next(ui + 1, nxt);
;         const char* nA = has_next ? baseA1(nxt) : cA;
;         const char* nB = has_next ? baseB(nxt) : cB;
;         const bool mirN = has_next ? mirrored(nxt) : mirC;
;         for (int t = 0; t < nt; t += 2) {
;             const bool last = (t == nt - 2);
;             if constexpr (Epi::MIDK) { if (t == g.ksplit) E.mid(acc, cur, wr, wc, fr, fq); }
;             const char *a1, *a2;
;             if constexpr (SPLITA) {
;                 a1 = (t + 1 < g.ksplit) ? cA + (size_t)(t + 1) * kstep : cA2 + (size_t)(t + 1 - g.ksplit) * 2048;
;                 a2 = last ? nA : ((t + 2 < g.ksplit) ? cA + (size_t)(t + 2) * kstep : cA2 + (size_t)(t + 2 - g.ksplit) * 2048);
;             } else { a1 = cA + kofs(t + 1); a2 = last ? nA : cA + kofs(t + 2); }
;             const char* b2 = last ? nB : cB + (size_t)(t + 2) * kstepB;
;             const bool s2a = SPLITA && (t + 1 >= g.ksplit), s2b = SPLITA && !last && (t + 2 >= g.ksplit);
;             const char* a3 = a2 + ((Epi::KSUB || s2b) ? (size_t)2048 : kstep); const char* b3 = b2 + kstepB;
;             const bool m1 = SPLITA && mirC && (t + 1 < g.ksplit), m2 = SPLITA && (last ? mirN : (mirC && (t + 2 < g.ksplit)));
;             const unsigned vo1[2] = {s2a ? voffA2[0] : m1 ? voffAm[0] : voffA[0], s2a ? voffA2[1] : m1 ? voffAm[1] : voffA[1]}, vo2[2] = {s2b ? voffA2[0] : m2 ? voffAm[0] : voffA[0], s2b ? voffA2[1] : m2 ? voffAm[1] : voffA[1]};
;             const char* a1h = m1 ? a1 - hstepA : a1 + hstepA; const char* a2h = m2 ? a2 - hstepA : a2 + hstepA;
;             PG8_LDB(B0, 0, 0); PG8_LDB(B1, 0, 1); PG8_SCHED; PG8_LDA(At, 0, 0); PG8_STAGE(PG8_SA(1, 1), a1h, vo1);
;             PG8_WAIT_V(8); PG8_WAIT_L(0); PG8_BAR; PG8_MMA(0, 0, At, B0); PG8_MMA(0, 1, At, B1); PG8_BAR; PG8_SCHED;
;             PG8_LDA(At, 0, 1); PG8_STAGE(PG8_SB(0, 0), b2, voffB); PG8_STAGE(PG8_SB(0, 1), b2 + hstepB, voffB); PG8_STAGE(PG8_SA(0, 0), a2, vo2);
;             PG8_WAIT_V(8); PG8_WAIT_L(0); PG8_BAR; PG8_MMA(1, 0, At, B0); PG8_MMA(1, 1, At, B1); PG8_BAR; PG8_SCHED;
.LBB0_795:
	s_ashr_i32 s19, s18, 31
	s_lshl_b64 s[12:13], s[18:19], 19
	s_add_u32 s22, s34, s12
	s_addc_u32 s23, s35, s13
	s_and_b64 s[12:13], s[2:3], exec
	s_cselect_b32 s19, s23, s39
	s_cselect_b32 s29, s22, s38
	s_ashr_i32 s21, s20, 31
	s_lshl_b64 s[12:13], s[20:21], 19
	s_add_u32 s24, s26, s12
	s_addc_u32 s25, s27, s13
	s_and_b64 s[12:13], s[2:3], exec
	s_cselect_b32 s21, s25, s37
	s_cselect_b32 s31, s24, s36
	s_add_u32 s55, s36, 0x1000
	s_addc_u32 s56, s37, 0
	s_add_u32 s36, s38, 0x40080
	s_addc_u32 s37, s39, 0
	s_mov_b32 s57, -2
	ds_read_b128 v[150:153], v155
	ds_read_b128 v[160:163], v155 offset:1024
	ds_read_b128 v[164:167], v155 offset:2048
	ds_read_b128 v[168:171], v155 offset:3072
	ds_read_b128 v[172:175], v156
	ds_read_b128 v[176:179], v156 offset:1024
	ds_read_b128 v[180:183], v156 offset:2048
	ds_read_b128 v[184:187], v156 offset:3072
	s_add_u32 s12, s36, 0xfffc0080
	s_addc_u32 s13, s37, -1
	s_cmp_eq_u32 s57, 12
	s_cselect_b32 s41, s19, s13
	s_cselect_b32 s40, s29, s12
	s_cselect_b32 s39, s21, s56
	s_cselect_b32 s38, s31, s55
	s_add_i32 m0, s42, 0xc000
	ds_read_b128 v[188:191], v157
	ds_read_b128 v[192:195], v157 offset:1024
	ds_read_b128 v[196:199], v157 offset:2048
	ds_read_b128 v[200:203], v157 offset:3072
	ds_read_b128 v[204:207], v157 offset:4096
	ds_read_b128 v[208:211], v157 offset:5120
	ds_read_b128 v[212:215], v157 offset:6144
	ds_read_b128 v[216:219], v157 offset:7168
	global_load_lds_dwordx4 v140, s[36:37]
	s_add_i32 m0, s42, 0xe000
	s_nop 0
	global_load_lds_dwordx4 v142, s[36:37]
	s_waitcnt vmcnt(8)
	s_waitcnt lgkmcnt(0)
	s_barrier
	s_setprio 1
	s_waitcnt lgkmcnt(0)
	v_mfma_f32_16x16x32_bf16 v[126:129], v[150:153], v[188:191], 0
	v_mfma_f32_16x16x32_bf16 v[110:113], v[150:153], v[196:199], 0
	v_mfma_f32_16x16x32_bf16 v[94:97], v[150:153], v[204:207], 0
	v_mfma_f32_16x16x32_bf16 v[78:81], v[150:153], v[212:215], 0
	v_mfma_f32_16x16x32_bf16 v[122:125], v[164:167], v[188:191], 0
	v_mfma_f32_16x16x32_bf16 v[106:109], v[164:167], v[196:199], 0
	v_mfma_f32_16x16x32_bf16 v[90:93], v[164:167], v[204:207], 0
	v_mfma_f32_16x16x32_bf16 v[74:77], v[164:167], v[212:215], 0
	v_mfma_f32_16x16x32_bf16 v[126:129], v[160:163], v[192:195], v[126:129]
	v_mfma_f32_16x16x32_bf16 v[110:113], v[160:163], v[200:203], v[110:113]
	v_mfma_f32_16x16x32_bf16 v[94:97], v[160:163], v[208:211], v[94:97]
	v_mfma_f32_16x16x32_bf16 v[78:81], v[160:163], v[216:219], v[78:81]
	v_mfma_f32_16x16x32_bf16 v[122:125], v[168:171], v[192:195], v[122:125]
	v_mfma_f32_16x16x32_bf16 v[106:109], v[168:171], v[200:203], v[106:109]
	v_mfma_f32_16x16x32_bf16 v[90:93], v[168:171], v[208:211], v[90:93]
	v_mfma_f32_16x16x32_bf16 v[74:77], v[168:171], v[216:219], v[74:77]
	s_setprio 0
	s_setprio 1
	v_mfma_f32_16x16x32_bf16 v[118:121], v[172:175], v[188:191], 0
	v_mfma_f32_16x16x32_bf16 v[102:105], v[172:175], v[196:199], 0
	v_mfma_f32_16x16x32_bf16 v[86:89], v[172:175], v[204:207], 0
	v_mfma_f32_16x16x32_bf16 v[70:73], v[172:175], v[212:215], 0
	v_mfma_f32_16x16x32_bf16 v[114:117], v[180:183], v[188:191], 0
	v_mfma_f32_16x16x32_bf16 v[98:101], v[180:183], v[196:199], 0
	v_mfma_f32_16x16x32_bf16 v[82:85], v[180:183], v[204:207], 0
	v_mfma_f32_16x16x32_bf16 v[66:69], v[180:183], v[212:215], 0
	v_mfma_f32_16x16x32_bf16 v[118:121], v[176:179], v[192:195], v[118:121]
	v_mfma_f32_16x16x32_bf16 v[102:105], v[176:179], v[200:203], v[102:105]
	v_mfma_f32_16x16x32_bf16 v[86:89], v[176:179], v[208:211], v[86:89]
	v_mfma_f32_16x16x32_bf16 v[70:73], v[176:179], v[216:219], v[70:73]
	v_mfma_f32_16x16x32_bf16 v[114:117], v[184:187], v[192:195], v[114:117]
	v_mfma_f32_16x16x32_bf16 v[98:101], v[184:187], v[200:203], v[98:101]
	v_mfma_f32_16x16x32_bf16 v[82:85], v[184:187], v[208:211], v[82:85]
	v_mfma_f32_16x16x32_bf16 v[66:69], v[184:187], v[216:219], v[66:69]
	s_setprio 0
	s_barrier
	s_add_u32 s98, s38, s8
	s_addc_u32 s99, s39, s9
	s_add_u32 s100, s40, s10
	s_addc_u32 s101, s41, s11
	s_add_i32 s12, s51, s6
	s_mov_b32 m0, s12
	ds_read_b128 v[188:191], v157 offset:16384
	ds_read_b128 v[192:195], v157 offset:17408
	ds_read_b128 v[196:199], v157 offset:18432
	ds_read_b128 v[200:203], v157 offset:19456
	ds_read_b128 v[204:207], v157 offset:20480
	ds_read_b128 v[208:211], v157 offset:21504
	ds_read_b128 v[212:215], v157 offset:22528
	ds_read_b128 v[216:219], v157 offset:23552
	global_load_lds_dwordx4 v134, s[38:39]
	s_add_i32 m0, s12, 0x2000
	s_add_u32 s12, s38, 0x40000
	s_addc_u32 s13, s39, 0
	s_add_i32 s60, s52, s6
	global_load_lds_dwordx4 v130, s[38:39]
	s_mov_b32 m0, s60
	s_nop 0
	global_load_lds_dwordx4 v134, s[12:13]
	s_add_i32 m0, s60, 0x2000
	s_nop 0
	global_load_lds_dwordx4 v130, s[12:13]
	s_mov_b32 m0, s42
	s_nop 0
	global_load_lds_dwordx4 v136, s[40:41]
	s_mov_b32 m0, s43
	s_nop 0
	global_load_lds_dwordx4 v132, s[40:41]
	s_waitcnt vmcnt(8)
	s_waitcnt lgkmcnt(0)
	s_barrier
; #define PG8_STAGE(bufoff, gbase, voff) do { _Pragma("unroll") for (int _i = 0; _i < 2; ++_i) \
;         __builtin_amdgcn_global_load_lds((const unsigned*)((const char*)(gbase) + (voff)[_i]), (LAS unsigned*)(lds + (bufoff) + ldsw + _i * 8192), 16, 0, 0); } while (0)
; #define PG8_LDA(dst, b, h) do { _Pragma("unroll") for (int m = 0; m < 4; ++m) _Pragma("unroll") for (int k = 0; k < 2; ++k) dst[m][k] = *(const LAS bf16x8*)(lds + PG8_SA(b, h) + aoff + m * 2048 + k * 1024); } while (0)
; #define PG8_LDB(dst, b, h) do { _Pragma("unroll") for (int n = 0; n < 2; ++n) _Pragma("unroll") for (int k = 0; k < 2; ++k) dst[n][k] = *(const LAS bf16x8*)(lds + PG8_SB(b, h) + boff + n * 2048 + k * 1024); } while (0)
; #define PG8_MMA(ai, bj, At, Bt) do { __builtin_amdgcn_s_setprio(1); _Pragma("unroll") for (int m = 0; m < 4; ++m) _Pragma("unroll") for (int n = 0; n < 2; ++n) _Pragma("unroll") for (int k = 0; k < 2; ++k) \
;         acc[ai][bj][m][n] = __builtin_amdgcn_mfma_f32_16x16x32_bf16(Bt[n][k], At[m][k], acc[ai][bj][m][n], 0, 0, 0); __builtin_amdgcn_s_setprio(0); } while (0)
; #define PG8_WAIT_V(n) asm volatile("s_waitcnt vmcnt(" #n ")" ::: "memory")
; #define PG8_WAIT_L(n) asm volatile("s_waitcnt lgkmcnt(" #n ")" ::: "memory")
; #define PG8_BAR __builtin_amdgcn_s_barrier()
; #define PG8_SCHED __builtin_amdgcn_sched_barrier(0)
; template <class Epi, bool ALIGN_EPI, bool SPLITA>
; __device__ __forceinline__ void gemm_phase(LAS unsigned char* lds, const Gemm g, const StaticOrder& S, const Epi& E) {
;     ...
;             PG8_WAIT_V(8); PG8_WAIT_L(0); PG8_BAR; PG8_MMA(1, 0, At, B0); PG8_MMA(1, 1, At, B1); PG8_BAR; PG8_SCHED;
;             PG8_LDB(B0, 1, 0); PG8_LDB(B1, 1, 1); PG8_SCHED; PG8_LDA(At, 1, 0); PG8_STAGE(PG8_SA(0, 1), a2h, vo2);
;             PG8_WAIT_V(8); PG8_WAIT_L(0); PG8_BAR; PG8_MMA(0, 0, At, B0); PG8_MMA(0, 1, At, B1); PG8_BAR; PG8_SCHED;
	s_setprio 1
	s_waitcnt lgkmcnt(0)
	v_mfma_f32_16x16x32_bf16 v[62:65], v[150:153], v[188:191], 0
	v_mfma_f32_16x16x32_bf16 v[38:41], v[150:153], v[196:199], 0
	v_mfma_f32_16x16x32_bf16 v[22:25], v[150:153], v[204:207], 0
	v_mfma_f32_16x16x32_bf16 v[6:9], v[150:153], v[212:215], 0
	v_mfma_f32_16x16x32_bf16 v[58:61], v[164:167], v[188:191], 0
	v_mfma_f32_16x16x32_bf16 v[34:37], v[164:167], v[196:199], 0
	v_mfma_f32_16x16x32_bf16 v[18:21], v[164:167], v[204:207], 0
	v_mfma_f32_16x16x32_bf16 v[2:5], v[164:167], v[212:215], 0
	v_mfma_f32_16x16x32_bf16 v[62:65], v[160:163], v[192:195], v[62:65]
	v_mfma_f32_16x16x32_bf16 v[38:41], v[160:163], v[200:203], v[38:41]
	v_mfma_f32_16x16x32_bf16 v[22:25], v[160:163], v[208:211], v[22:25]
	v_mfma_f32_16x16x32_bf16 v[6:9], v[160:163], v[216:219], v[6:9]
	v_mfma_f32_16x16x32_bf16 v[58:61], v[168:171], v[192:195], v[58:61]
	v_mfma_f32_16x16x32_bf16 v[34:37], v[168:171], v[200:203], v[34:37]
	v_mfma_f32_16x16x32_bf16 v[18:21], v[168:171], v[208:211], v[18:21]
	v_mfma_f32_16x16x32_bf16 v[2:5], v[168:171], v[216:219], v[2:5]
	s_setprio 0
	s_setprio 1
	v_mfma_f32_16x16x32_bf16 v[54:57], v[172:175], v[188:191], 0
	v_mfma_f32_16x16x32_bf16 v[42:45], v[172:175], v[196:199], 0
	v_mfma_f32_16x16x32_bf16 v[26:29], v[172:175], v[204:207], 0
	v_mfma_f32_16x16x32_bf16 v[10:13], v[172:175], v[212:215], 0
	v_mfma_f32_16x16x32_bf16 v[50:53], v[180:183], v[188:191], 0
	v_mfma_f32_16x16x32_bf16 v[46:49], v[180:183], v[196:199], 0
	v_mfma_f32_16x16x32_bf16 v[30:33], v[180:183], v[204:207], 0
	v_mfma_f32_16x16x32_bf16 v[14:17], v[180:183], v[212:215], 0
	v_mfma_f32_16x16x32_bf16 v[54:57], v[176:179], v[192:195], v[54:57]
	v_mfma_f32_16x16x32_bf16 v[42:45], v[176:179], v[200:203], v[42:45]
	v_mfma_f32_16x16x32_bf16 v[26:29], v[176:179], v[208:211], v[26:29]
	v_mfma_f32_16x16x32_bf16 v[10:13], v[176:179], v[216:219], v[10:13]
	v_mfma_f32_16x16x32_bf16 v[50:53], v[184:187], v[192:195], v[50:53]
	v_mfma_f32_16x16x32_bf16 v[46:49], v[184:187], v[200:203], v[46:49]
	v_mfma_f32_16x16x32_bf16 v[30:33], v[184:187], v[208:211], v[30:33]
	v_mfma_f32_16x16x32_bf16 v[14:17], v[184:187], v[216:219], v[14:17]
	s_setprio 0
	s_barrier
	s_add_i32 s60, 0, 0x18000
	v_add_u32_e32 v149, s60, v154
	s_add_i32 s61, 0, 0x1c000
	ds_read_b128 v[150:153], v149
	ds_read_b128 v[160:163], v149 offset:1024
	ds_read_b128 v[164:167], v149 offset:2048
	ds_read_b128 v[168:171], v149 offset:3072
	v_add_u32_e32 v149, s61, v154
	ds_read_b128 v[172:175], v149
	ds_read_b128 v[176:179], v149 offset:1024
	ds_read_b128 v[180:183], v149 offset:2048
	ds_read_b128 v[184:187], v149 offset:3072
	s_add_u32 s12, s40, 0x40000
	s_addc_u32 s13, s41, 0
	s_mov_b32 m0, s44
	ds_read_b128 v[188:191], v157 offset:32768
	ds_read_b128 v[192:195], v157 offset:33792
	ds_read_b128 v[196:199], v157 offset:34816
	ds_read_b128 v[200:203], v157 offset:35840
	ds_read_b128 v[204:207], v157 offset:36864
	ds_read_b128 v[208:211], v157 offset:37888
	ds_read_b128 v[212:215], v157 offset:38912
	ds_read_b128 v[216:219], v157 offset:39936
	global_load_lds_dwordx4 v136, s[12:13]
	s_mov_b32 m0, s45
	s_nop 0
	global_load_lds_dwordx4 v132, s[12:13]
	s_waitcnt vmcnt(8)
	s_waitcnt lgkmcnt(0)
	s_barrier
	s_setprio 1
	s_waitcnt lgkmcnt(0)
	v_mfma_f32_16x16x32_bf16 v[126:129], v[150:153], v[188:191], v[126:129]
	v_mfma_f32_16x16x32_bf16 v[110:113], v[150:153], v[196:199], v[110:113]
	v_mfma_f32_16x16x32_bf16 v[94:97], v[150:153], v[204:207], v[94:97]
	v_mfma_f32_16x16x32_bf16 v[78:81], v[150:153], v[212:215], v[78:81]
	v_mfma_f32_16x16x32_bf16 v[122:125], v[164:167], v[188:191], v[122:125]
	v_mfma_f32_16x16x32_bf16 v[106:109], v[164:167], v[196:199], v[106:109]
	v_mfma_f32_16x16x32_bf16 v[90:93], v[164:167], v[204:207], v[90:93]
	v_mfma_f32_16x16x32_bf16 v[74:77], v[164:167], v[212:215], v[74:77]
	v_mfma_f32_16x16x32_bf16 v[126:129], v[160:163], v[192:195], v[126:129]
	v_mfma_f32_16x16x32_bf16 v[110:113], v[160:163], v[200:203], v[110:113]
	v_mfma_f32_16x16x32_bf16 v[94:97], v[160:163], v[208:211], v[94:97]
	v_mfma_f32_16x16x32_bf16 v[78:81], v[160:163], v[216:219], v[78:81]
	v_mfma_f32_16x16x32_bf16 v[122:125], v[168:171], v[192:195], v[122:125]
	v_mfma_f32_16x16x32_bf16 v[106:109], v[168:171], v[200:203], v[106:109]
	v_mfma_f32_16x16x32_bf16 v[90:93], v[168:171], v[208:211], v[90:93]
	v_mfma_f32_16x16x32_bf16 v[74:77], v[168:171], v[216:219], v[74:77]
	s_setprio 0
	s_setprio 1
	v_mfma_f32_16x16x32_bf16 v[118:121], v[172:175], v[188:191], v[118:121]
	v_mfma_f32_16x16x32_bf16 v[102:105], v[172:175], v[196:199], v[102:105]
	v_mfma_f32_16x16x32_bf16 v[86:89], v[172:175], v[204:207], v[86:89]
	v_mfma_f32_16x16x32_bf16 v[70:73], v[172:175], v[212:215], v[70:73]
	v_mfma_f32_16x16x32_bf16 v[114:117], v[180:183], v[188:191], v[114:117]
	v_mfma_f32_16x16x32_bf16 v[98:101], v[180:183], v[196:199], v[98:101]
	v_mfma_f32_16x16x32_bf16 v[82:85], v[180:183], v[204:207], v[82:85]
	v_mfma_f32_16x16x32_bf16 v[66:69], v[180:183], v[212:215], v[66:69]
	v_mfma_f32_16x16x32_bf16 v[118:121], v[176:179], v[192:195], v[118:121]
	v_mfma_f32_16x16x32_bf16 v[102:105], v[176:179], v[200:203], v[102:105]
	v_mfma_f32_16x16x32_bf16 v[86:89], v[176:179], v[208:211], v[86:89]
	v_mfma_f32_16x16x32_bf16 v[70:73], v[176:179], v[216:219], v[70:73]
	v_mfma_f32_16x16x32_bf16 v[114:117], v[184:187], v[192:195], v[114:117]
	v_mfma_f32_16x16x32_bf16 v[98:101], v[184:187], v[200:203], v[98:101]
	v_mfma_f32_16x16x32_bf16 v[82:85], v[184:187], v[208:211], v[82:85]
	v_mfma_f32_16x16x32_bf16 v[66:69], v[184:187], v[216:219], v[66:69]
	s_setprio 0
	s_barrier
; #define PG8_STAGE(bufoff, gbase, voff) do { _Pragma("unroll") for (int _i = 0; _i < 2; ++_i) \
;         __builtin_amdgcn_global_load_lds((const unsigned*)((const char*)(gbase) + (voff)[_i]), (LAS unsigned*)(lds + (bufoff) + ldsw + _i * 8192), 16, 0, 0); } while (0)
; #define PG8_WAIT_V(n) asm volatile("s_waitcnt vmcnt(" #n ")" ::: "memory")
; template <class Epi, bool ALIGN_EPI, bool SPLITA>
; __device__ __forceinline__ void gemm_phase(LAS unsigned char* lds, const Gemm g, const StaticOrder& S, const Epi& E) {
;     ...
;         for (int t = 0; t < nt; t += 2) {
;             const bool last = (t == nt - 2);
;             if constexpr (Epi::MIDK) { if (t == g.ksplit) E.mid(acc, cur, wr, wc, fr, fq); }
;             const char *a1, *a2;
;             if constexpr (SPLITA) {
;                 a1 = (t + 1 < g.ksplit) ? cA + (size_t)(t + 1) * kstep : cA2 + (size_t)(t + 1 - g.ksplit) * 2048;
;                 a2 = last ? nA : ((t + 2 < g.ksplit) ? cA + (size_t)(t + 2) * kstep : cA2 + (size_t)(t + 2 - g.ksplit) * 2048);
;             } else { a1 = cA + kofs(t + 1); a2 = last ? nA : cA + kofs(t + 2); }
;             const char* b2 = last ? nB : cB + (size_t)(t + 2) * kstepB;
;             const bool s2a = SPLITA && (t + 1 >= g.ksplit), s2b = SPLITA && !last && (t + 2 >= g.ksplit);
;             const char* a3 = a2 + ((Epi::KSUB || s2b) ? (size_t)2048 : kstep); const char* b3 = b2 + kstepB;
;             const bool m1 = SPLITA && mirC && (t + 1 < g.ksplit), m2 = SPLITA && (last ? mirN : (mirC && (t + 2 < g.ksplit)));
;             const unsigned vo1[2] = {s2a ? voffA2[0] : m1 ? voffAm[0] : voffA[0], s2a ? voffA2[1] : m1 ? voffAm[1] : voffA[1]}, vo2[2] = {s2b ? voffA2[0] : m2 ? voffAm[0] : voffA[0], s2b ? voffA2[1] : m2 ? voffAm[1] : voffA[1]};
;             const char* a1h = m1 ? a1 - hstepA : a1 + hstepA; const char* a2h = m2 ? a2 - hstepA : a2 + hstepA;
;             PG8_LDB(B0, 0, 0); PG8_LDB(B1, 0, 1); PG8_SCHED; PG8_LDA(At, 0, 0); PG8_STAGE(PG8_SA(1, 1), a1h, vo1);
;             PG8_WAIT_V(8); PG8_WAIT_L(0); PG8_BAR; PG8_MMA(0, 0, At, B0); PG8_MMA(0, 1, At, B1); PG8_BAR; PG8_SCHED;
;     ...
;             PG8_LDA(At, 1, 1); PG8_STAGE(PG8_SB(1, 0), b3, voffB); PG8_STAGE(PG8_SB(1, 1), b3 + hstepB, voffB); PG8_STAGE(PG8_SA(1, 0), a3, vo2);
;             PG8_WAIT_V(8); PG8_WAIT_L(0); PG8_BAR; PG8_MMA(1, 0, At, B0); PG8_MMA(1, 1, At, B1); PG8_BAR; PG8_SCHED;
	s_add_i32 s12, s60, s6
	s_mov_b32 m0, s12
	ds_read_b128 v[188:191], v157 offset:49152
	ds_read_b128 v[192:195], v157 offset:50176
	ds_read_b128 v[196:199], v157 offset:51200
	ds_read_b128 v[200:203], v157 offset:52224
	ds_read_b128 v[204:207], v157 offset:53248
	ds_read_b128 v[208:211], v157 offset:54272
	ds_read_b128 v[212:215], v157 offset:55296
	ds_read_b128 v[216:219], v157 offset:56320
	global_load_lds_dwordx4 v134, s[98:99]
	s_add_i32 m0, s12, 0x2000
	s_add_u32 s12, s38, 0x40800
	s_addc_u32 s13, s39, 0
	s_add_i32 s38, s61, s6
	global_load_lds_dwordx4 v130, s[98:99]
	s_mov_b32 m0, s38
	s_nop 0
	global_load_lds_dwordx4 v134, s[12:13]
	s_add_i32 m0, s38, 0x2000
	s_nop 0
	global_load_lds_dwordx4 v130, s[12:13]
	s_mov_b32 m0, s49
	s_nop 0
	global_load_lds_dwordx4 v136, s[100:101]
	s_mov_b32 m0, s50
	s_nop 0
	global_load_lds_dwordx4 v132, s[100:101]
	s_waitcnt vmcnt(8)
	s_waitcnt lgkmcnt(0)
	s_barrier
	s_setprio 1
	s_waitcnt lgkmcnt(0)
	v_mfma_f32_16x16x32_bf16 v[62:65], v[150:153], v[188:191], v[62:65]
	v_mfma_f32_16x16x32_bf16 v[38:41], v[150:153], v[196:199], v[38:41]
	v_mfma_f32_16x16x32_bf16 v[22:25], v[150:153], v[204:207], v[22:25]
	v_mfma_f32_16x16x32_bf16 v[6:9], v[150:153], v[212:215], v[6:9]
	v_mfma_f32_16x16x32_bf16 v[58:61], v[164:167], v[188:191], v[58:61]
	v_mfma_f32_16x16x32_bf16 v[34:37], v[164:167], v[196:199], v[34:37]
	v_mfma_f32_16x16x32_bf16 v[18:21], v[164:167], v[204:207], v[18:21]
	v_mfma_f32_16x16x32_bf16 v[2:5], v[164:167], v[212:215], v[2:5]
	v_mfma_f32_16x16x32_bf16 v[62:65], v[160:163], v[192:195], v[62:65]
	v_mfma_f32_16x16x32_bf16 v[38:41], v[160:163], v[200:203], v[38:41]
	v_mfma_f32_16x16x32_bf16 v[22:25], v[160:163], v[208:211], v[22:25]
	v_mfma_f32_16x16x32_bf16 v[6:9], v[160:163], v[216:219], v[6:9]
	v_mfma_f32_16x16x32_bf16 v[58:61], v[168:171], v[192:195], v[58:61]
	v_mfma_f32_16x16x32_bf16 v[34:37], v[168:171], v[200:203], v[34:37]
	v_mfma_f32_16x16x32_bf16 v[18:21], v[168:171], v[208:211], v[18:21]
	v_mfma_f32_16x16x32_bf16 v[2:5], v[168:171], v[216:219], v[2:5]
	s_setprio 0
	s_setprio 1
	v_mfma_f32_16x16x32_bf16 v[54:57], v[172:175], v[188:191], v[54:57]
	v_mfma_f32_16x16x32_bf16 v[42:45], v[172:175], v[196:199], v[42:45]
	v_mfma_f32_16x16x32_bf16 v[26:29], v[172:175], v[204:207], v[26:29]
	v_mfma_f32_16x16x32_bf16 v[10:13], v[172:175], v[212:215], v[10:13]
	v_mfma_f32_16x16x32_bf16 v[50:53], v[180:183], v[188:191], v[50:53]
	v_mfma_f32_16x16x32_bf16 v[46:49], v[180:183], v[196:199], v[46:49]
	v_mfma_f32_16x16x32_bf16 v[30:33], v[180:183], v[204:207], v[30:33]
	v_mfma_f32_16x16x32_bf16 v[14:17], v[180:183], v[212:215], v[14:17]
	v_mfma_f32_16x16x32_bf16 v[54:57], v[176:179], v[192:195], v[54:57]
	v_mfma_f32_16x16x32_bf16 v[42:45], v[176:179], v[200:203], v[42:45]
	v_mfma_f32_16x16x32_bf16 v[26:29], v[176:179], v[208:211], v[26:29]
	v_mfma_f32_16x16x32_bf16 v[10:13], v[176:179], v[216:219], v[10:13]
	v_mfma_f32_16x16x32_bf16 v[50:53], v[184:187], v[192:195], v[50:53]
	v_mfma_f32_16x16x32_bf16 v[46:49], v[184:187], v[200:203], v[46:49]
	v_mfma_f32_16x16x32_bf16 v[30:33], v[184:187], v[208:211], v[30:33]
	v_mfma_f32_16x16x32_bf16 v[14:17], v[184:187], v[216:219], v[14:17]
	s_setprio 0
	s_barrier
	s_add_i32 s57, s57, 2
	s_add_u32 s55, s55, 0x1000
	s_addc_u32 s56, s56, 0
	s_add_u32 s36, s36, 0x100
	s_addc_u32 s37, s37, 0
.LBB0_796:
	ds_read_b128 v[150:153], v155
	ds_read_b128 v[160:163], v155 offset:1024
	ds_read_b128 v[164:167], v155 offset:2048
	ds_read_b128 v[168:171], v155 offset:3072
	ds_read_b128 v[172:175], v156
	ds_read_b128 v[176:179], v156 offset:1024
	ds_read_b128 v[180:183], v156 offset:2048
	ds_read_b128 v[184:187], v156 offset:3072
	s_add_u32 s12, s36, 0xfffc0080
	s_addc_u32 s13, s37, -1
	s_cmp_eq_u32 s57, 12
	s_cselect_b32 s41, s19, s13
	s_cselect_b32 s40, s29, s12
	s_cselect_b32 s39, s21, s56
	s_cselect_b32 s38, s31, s55
	s_add_i32 m0, s42, 0xc000
	ds_read_b128 v[188:191], v157
	ds_read_b128 v[192:195], v157 offset:1024
	ds_read_b128 v[196:199], v157 offset:2048
	ds_read_b128 v[200:203], v157 offset:3072
	ds_read_b128 v[204:207], v157 offset:4096
	ds_read_b128 v[208:211], v157 offset:5120
	ds_read_b128 v[212:215], v157 offset:6144
	ds_read_b128 v[216:219], v157 offset:7168
	global_load_lds_dwordx4 v140, s[36:37]
	s_add_i32 m0, s42, 0xe000
	s_nop 0
	global_load_lds_dwordx4 v142, s[36:37]
	s_waitcnt vmcnt(8)
	s_waitcnt lgkmcnt(0)
	s_barrier
	s_setprio 1
	s_waitcnt lgkmcnt(0)
	v_mfma_f32_16x16x32_bf16 v[126:129], v[150:153], v[188:191], v[126:129]
	v_mfma_f32_16x16x32_bf16 v[110:113], v[150:153], v[196:199], v[110:113]
	v_mfma_f32_16x16x32_bf16 v[94:97], v[150:153], v[204:207], v[94:97]
	v_mfma_f32_16x16x32_bf16 v[78:81], v[150:153], v[212:215], v[78:81]
	v_mfma_f32_16x16x32_bf16 v[122:125], v[164:167], v[188:191], v[122:125]
	v_mfma_f32_16x16x32_bf16 v[106:109], v[164:167], v[196:199], v[106:109]
	v_mfma_f32_16x16x32_bf16 v[90:93], v[164:167], v[204:207], v[90:93]
	v_mfma_f32_16x16x32_bf16 v[74:77], v[164:167], v[212:215], v[74:77]
	v_mfma_f32_16x16x32_bf16 v[126:129], v[160:163], v[192:195], v[126:129]
	v_mfma_f32_16x16x32_bf16 v[110:113], v[160:163], v[200:203], v[110:113]
	v_mfma_f32_16x16x32_bf16 v[94:97], v[160:163], v[208:211], v[94:97]
	v_mfma_f32_16x16x32_bf16 v[78:81], v[160:163], v[216:219], v[78:81]
	v_mfma_f32_16x16x32_bf16 v[122:125], v[168:171], v[192:195], v[122:125]
	v_mfma_f32_16x16x32_bf16 v[106:109], v[168:171], v[200:203], v[106:109]
	v_mfma_f32_16x16x32_bf16 v[90:93], v[168:171], v[208:211], v[90:93]
	v_mfma_f32_16x16x32_bf16 v[74:77], v[168:171], v[216:219], v[74:77]
	s_setprio 0
	s_setprio 1
	v_mfma_f32_16x16x32_bf16 v[118:121], v[172:175], v[188:191], v[118:121]
	v_mfma_f32_16x16x32_bf16 v[102:105], v[172:175], v[196:199], v[102:105]
	v_mfma_f32_16x16x32_bf16 v[86:89], v[172:175], v[204:207], v[86:89]
	v_mfma_f32_16x16x32_bf16 v[70:73], v[172:175], v[212:215], v[70:73]
	v_mfma_f32_16x16x32_bf16 v[114:117], v[180:183], v[188:191], v[114:117]
	v_mfma_f32_16x16x32_bf16 v[98:101], v[180:183], v[196:199], v[98:101]
	v_mfma_f32_16x16x32_bf16 v[82:85], v[180:183], v[204:207], v[82:85]
	v_mfma_f32_16x16x32_bf16 v[66:69], v[180:183], v[212:215], v[66:69]
	v_mfma_f32_16x16x32_bf16 v[118:121], v[176:179], v[192:195], v[118:121]
	v_mfma_f32_16x16x32_bf16 v[102:105], v[176:179], v[200:203], v[102:105]
	v_mfma_f32_16x16x32_bf16 v[86:89], v[176:179], v[208:211], v[86:89]
	v_mfma_f32_16x16x32_bf16 v[70:73], v[176:179], v[216:219], v[70:73]
	v_mfma_f32_16x16x32_bf16 v[114:117], v[184:187], v[192:195], v[114:117]
	v_mfma_f32_16x16x32_bf16 v[98:101], v[184:187], v[200:203], v[98:101]
	v_mfma_f32_16x16x32_bf16 v[82:85], v[184:187], v[208:211], v[82:85]
	v_mfma_f32_16x16x32_bf16 v[66:69], v[184:187], v[216:219], v[66:69]
	s_setprio 0
	s_barrier
; #define PG8_STAGE(bufoff, gbase, voff) do { _Pragma("unroll") for (int _i = 0; _i < 2; ++_i) \
;         __builtin_amdgcn_global_load_lds((const unsigned*)((const char*)(gbase) + (voff)[_i]), (LAS unsigned*)(lds + (bufoff) + ldsw + _i * 8192), 16, 0, 0); } while (0)
; #define PG8_LDA(dst, b, h) do { _Pragma("unroll") for (int m = 0; m < 4; ++m) _Pragma("unroll") for (int k = 0; k < 2; ++k) dst[m][k] = *(const LAS bf16x8*)(lds + PG8_SA(b, h) + aoff + m * 2048 + k * 1024); } while (0)
; #define PG8_LDB(dst, b, h) do { _Pragma("unroll") for (int n = 0; n < 2; ++n) _Pragma("unroll") for (int k = 0; k < 2; ++k) dst[n][k] = *(const LAS bf16x8*)(lds + PG8_SB(b, h) + boff + n * 2048 + k * 1024); } while (0)
; #define PG8_MMA(ai, bj, At, Bt) do { __builtin_amdgcn_s_setprio(1); _Pragma("unroll") for (int m = 0; m < 4; ++m) _Pragma("unroll") for (int n = 0; n < 2; ++n) _Pragma("unroll") for (int k = 0; k < 2; ++k) \
;         acc[ai][bj][m][n] = __builtin_amdgcn_mfma_f32_16x16x32_bf16(Bt[n][k], At[m][k], acc[ai][bj][m][n], 0, 0, 0); __builtin_amdgcn_s_setprio(0); } while (0)
; #define PG8_WAIT_V(n) asm volatile("s_waitcnt vmcnt(" #n ")" ::: "memory")
; #define PG8_WAIT_L(n) asm volatile("s_waitcnt lgkmcnt(" #n ")" ::: "memory")
; #define PG8_BAR __builtin_amdgcn_s_barrier()
; #define PG8_SCHED __builtin_amdgcn_sched_barrier(0)
; template <class Epi, bool ALIGN_EPI, bool SPLITA>
; __device__ __forceinline__ void gemm_phase(LAS unsigned char* lds, const Gemm g, const StaticOrder& S, const Epi& E) {
;     ...
;             PG8_LDA(At, 0, 1); PG8_STAGE(PG8_SB(0, 0), b2, voffB); PG8_STAGE(PG8_SB(0, 1), b2 + hstepB, voffB); PG8_STAGE(PG8_SA(0, 0), a2, vo2);
;             PG8_WAIT_V(8); PG8_WAIT_L(0); PG8_BAR; PG8_MMA(1, 0, At, B0); PG8_MMA(1, 1, At, B1); PG8_BAR; PG8_SCHED;
;             PG8_LDB(B0, 1, 0); PG8_LDB(B1, 1, 1); PG8_SCHED; PG8_LDA(At, 1, 0); PG8_STAGE(PG8_SA(0, 1), a2h, vo2);
;             PG8_WAIT_V(8); PG8_WAIT_L(0); PG8_BAR; PG8_MMA(0, 0, At, B0); PG8_MMA(0, 1, At, B1); PG8_BAR; PG8_SCHED;
	s_add_u32 s98, s38, s8
	s_addc_u32 s99, s39, s9
	s_add_u32 s100, s40, s10
	s_addc_u32 s101, s41, s11
	s_add_i32 s12, s51, s6
	s_mov_b32 m0, s12
	ds_read_b128 v[188:191], v157 offset:16384
	ds_read_b128 v[192:195], v157 offset:17408
	ds_read_b128 v[196:199], v157 offset:18432
	ds_read_b128 v[200:203], v157 offset:19456
	ds_read_b128 v[204:207], v157 offset:20480
	ds_read_b128 v[208:211], v157 offset:21504
	ds_read_b128 v[212:215], v157 offset:22528
	ds_read_b128 v[216:219], v157 offset:23552
	global_load_lds_dwordx4 v134, s[38:39]
	s_add_i32 m0, s12, 0x2000
	s_add_u32 s12, s38, 0x40000
	s_addc_u32 s13, s39, 0
	s_add_i32 s60, s52, s6
	global_load_lds_dwordx4 v130, s[38:39]
	s_mov_b32 m0, s60
	s_nop 0
	global_load_lds_dwordx4 v134, s[12:13]
	s_add_i32 m0, s60, 0x2000
	s_nop 0
	global_load_lds_dwordx4 v130, s[12:13]
	s_mov_b32 m0, s42
	s_nop 0
	global_load_lds_dwordx4 v136, s[40:41]
	s_mov_b32 m0, s43
	s_nop 0
	global_load_lds_dwordx4 v132, s[40:41]
	s_waitcnt vmcnt(8)
	s_waitcnt lgkmcnt(0)
	s_barrier
	s_setprio 1
	s_waitcnt lgkmcnt(0)
	v_mfma_f32_16x16x32_bf16 v[62:65], v[150:153], v[188:191], v[62:65]
	v_mfma_f32_16x16x32_bf16 v[38:41], v[150:153], v[196:199], v[38:41]
	v_mfma_f32_16x16x32_bf16 v[22:25], v[150:153], v[204:207], v[22:25]
	v_mfma_f32_16x16x32_bf16 v[6:9], v[150:153], v[212:215], v[6:9]
	v_mfma_f32_16x16x32_bf16 v[58:61], v[164:167], v[188:191], v[58:61]
	v_mfma_f32_16x16x32_bf16 v[34:37], v[164:167], v[196:199], v[34:37]
	v_mfma_f32_16x16x32_bf16 v[18:21], v[164:167], v[204:207], v[18:21]
	v_mfma_f32_16x16x32_bf16 v[2:5], v[164:167], v[212:215], v[2:5]
	v_mfma_f32_16x16x32_bf16 v[62:65], v[160:163], v[192:195], v[62:65]
	v_mfma_f32_16x16x32_bf16 v[38:41], v[160:163], v[200:203], v[38:41]
	v_mfma_f32_16x16x32_bf16 v[22:25], v[160:163], v[208:211], v[22:25]
	v_mfma_f32_16x16x32_bf16 v[6:9], v[160:163], v[216:219], v[6:9]
	v_mfma_f32_16x16x32_bf16 v[58:61], v[168:171], v[192:195], v[58:61]
	v_mfma_f32_16x16x32_bf16 v[34:37], v[168:171], v[200:203], v[34:37]
	v_mfma_f32_16x16x32_bf16 v[18:21], v[168:171], v[208:211], v[18:21]
	v_mfma_f32_16x16x32_bf16 v[2:5], v[168:171], v[216:219], v[2:5]
	s_setprio 0
	s_setprio 1
	v_mfma_f32_16x16x32_bf16 v[54:57], v[172:175], v[188:191], v[54:57]
	v_mfma_f32_16x16x32_bf16 v[42:45], v[172:175], v[196:199], v[42:45]
	v_mfma_f32_16x16x32_bf16 v[26:29], v[172:175], v[204:207], v[26:29]
	v_mfma_f32_16x16x32_bf16 v[10:13], v[172:175], v[212:215], v[10:13]
	v_mfma_f32_16x16x32_bf16 v[50:53], v[180:183], v[188:191], v[50:53]
	v_mfma_f32_16x16x32_bf16 v[46:49], v[180:183], v[196:199], v[46:49]
	v_mfma_f32_16x16x32_bf16 v[30:33], v[180:183], v[204:207], v[30:33]
	v_mfma_f32_16x16x32_bf16 v[14:17], v[180:183], v[212:215], v[14:17]
	v_mfma_f32_16x16x32_bf16 v[54:57], v[176:179], v[192:195], v[54:57]
	v_mfma_f32_16x16x32_bf16 v[42:45], v[176:179], v[200:203], v[42:45]
	v_mfma_f32_16x16x32_bf16 v[26:29], v[176:179], v[208:211], v[26:29]
	v_mfma_f32_16x16x32_bf16 v[10:13], v[176:179], v[216:219], v[10:13]
	v_mfma_f32_16x16x32_bf16 v[50:53], v[184:187], v[192:195], v[50:53]
	v_mfma_f32_16x16x32_bf16 v[46:49], v[184:187], v[200:203], v[46:49]
	v_mfma_f32_16x16x32_bf16 v[30:33], v[184:187], v[208:211], v[30:33]
	v_mfma_f32_16x16x32_bf16 v[14:17], v[184:187], v[216:219], v[14:17]
	s_setprio 0
	s_barrier
	s_add_i32 s60, 0, 0x18000
	v_add_u32_e32 v149, s60, v154
	s_add_i32 s61, 0, 0x1c000
	ds_read_b128 v[150:153], v149
	ds_read_b128 v[160:163], v149 offset:1024
	ds_read_b128 v[164:167], v149 offset:2048
	ds_read_b128 v[168:171], v149 offset:3072
	v_add_u32_e32 v149, s61, v154
	ds_read_b128 v[172:175], v149
	ds_read_b128 v[176:179], v149 offset:1024
	ds_read_b128 v[180:183], v149 offset:2048
	ds_read_b128 v[184:187], v149 offset:3072
	s_add_u32 s12, s40, 0x40000
	s_addc_u32 s13, s41, 0
	s_mov_b32 m0, s44
	ds_read_b128 v[188:191], v157 offset:32768
	ds_read_b128 v[192:195], v157 offset:33792
	ds_read_b128 v[196:199], v157 offset:34816
	ds_read_b128 v[200:203], v157 offset:35840
	ds_read_b128 v[204:207], v157 offset:36864
	ds_read_b128 v[208:211], v157 offset:37888
	ds_read_b128 v[212:215], v157 offset:38912
	ds_read_b128 v[216:219], v157 offset:39936
	global_load_lds_dwordx4 v136, s[12:13]
	s_mov_b32 m0, s45
	s_nop 0
	global_load_lds_dwordx4 v132, s[12:13]
	s_waitcnt vmcnt(8)
	s_waitcnt lgkmcnt(0)
	s_barrier
; #define PG8_STAGE(bufoff, gbase, voff) do { _Pragma("unroll") for (int _i = 0; _i < 2; ++_i) \
;         __builtin_amdgcn_global_load_lds((const unsigned*)((const char*)(gbase) + (voff)[_i]), (LAS unsigned*)(lds + (bufoff) + ldsw + _i * 8192), 16, 0, 0); } while (0)
; #define PG8_LDA(dst, b, h) do { _Pragma("unroll") for (int m = 0; m < 4; ++m) _Pragma("unroll") for (int k = 0; k < 2; ++k) dst[m][k] = *(const LAS bf16x8*)(lds + PG8_SA(b, h) + aoff + m * 2048 + k * 1024); } while (0)
; #define PG8_LDB(dst, b, h) do { _Pragma("unroll") for (int n = 0; n < 2; ++n) _Pragma("unroll") for (int k = 0; k < 2; ++k) dst[n][k] = *(const LAS bf16x8*)(lds + PG8_SB(b, h) + boff + n * 2048 + k * 1024); } while (0)
; #define PG8_MMA(ai, bj, At, Bt) do { __builtin_amdgcn_s_setprio(1); _Pragma("unroll") for (int m = 0; m < 4; ++m) _Pragma("unroll") for (int n = 0; n < 2; ++n) _Pragma("unroll") for (int k = 0; k < 2; ++k) \
;         acc[ai][bj][m][n] = __builtin_amdgcn_mfma_f32_16x16x32_bf16(Bt[n][k], At[m][k], acc[ai][bj][m][n], 0, 0, 0); __builtin_amdgcn_s_setprio(0); } while (0)
; #define PG8_WAIT_V(n) asm volatile("s_waitcnt vmcnt(" #n ")" ::: "memory")
; #define PG8_WAIT_L(n) asm volatile("s_waitcnt lgkmcnt(" #n ")" ::: "memory")
; #define PG8_BAR __builtin_amdgcn_s_barrier()
; #define PG8_SCHED __builtin_amdgcn_sched_barrier(0)
; template <class Epi, bool ALIGN_EPI, bool SPLITA>
; __device__ __forceinline__ void gemm_phase(LAS unsigned char* lds, const Gemm g, const StaticOrder& S, const Epi& E) {
;     ...
;         for (int t = 0; t < nt; t += 2) {
;     ...
;             PG8_LDB(B0, 1, 0); PG8_LDB(B1, 1, 1); PG8_SCHED; PG8_LDA(At, 1, 0); PG8_STAGE(PG8_SA(0, 1), a2h, vo2);
;             PG8_WAIT_V(8); PG8_WAIT_L(0); PG8_BAR; PG8_MMA(0, 0, At, B0); PG8_MMA(0, 1, At, B1); PG8_BAR; PG8_SCHED;
;             PG8_LDA(At, 1, 1); PG8_STAGE(PG8_SB(1, 0), b3, voffB); PG8_STAGE(PG8_SB(1, 1), b3 + hstepB, voffB); PG8_STAGE(PG8_SA(1, 0), a3, vo2);
;             PG8_WAIT_V(8); PG8_WAIT_L(0); PG8_BAR; PG8_MMA(1, 0, At, B0); PG8_MMA(1, 1, At, B1); PG8_BAR; PG8_SCHED;
	s_setprio 1
	s_waitcnt lgkmcnt(0)
	v_mfma_f32_16x16x32_bf16 v[126:129], v[150:153], v[188:191], v[126:129]
	v_mfma_f32_16x16x32_bf16 v[110:113], v[150:153], v[196:199], v[110:113]
	v_mfma_f32_16x16x32_bf16 v[94:97], v[150:153], v[204:207], v[94:97]
	v_mfma_f32_16x16x32_bf16 v[78:81], v[150:153], v[212:215], v[78:81]
	v_mfma_f32_16x16x32_bf16 v[122:125], v[164:167], v[188:191], v[122:125]
	v_mfma_f32_16x16x32_bf16 v[106:109], v[164:167], v[196:199], v[106:109]
	v_mfma_f32_16x16x32_bf16 v[90:93], v[164:167], v[204:207], v[90:93]
	v_mfma_f32_16x16x32_bf16 v[74:77], v[164:167], v[212:215], v[74:77]
	v_mfma_f32_16x16x32_bf16 v[126:129], v[160:163], v[192:195], v[126:129]
	v_mfma_f32_16x16x32_bf16 v[110:113], v[160:163], v[200:203], v[110:113]
	v_mfma_f32_16x16x32_bf16 v[94:97], v[160:163], v[208:211], v[94:97]
	v_mfma_f32_16x16x32_bf16 v[78:81], v[160:163], v[216:219], v[78:81]
	v_mfma_f32_16x16x32_bf16 v[122:125], v[168:171], v[192:195], v[122:125]
	v_mfma_f32_16x16x32_bf16 v[106:109], v[168:171], v[200:203], v[106:109]
	v_mfma_f32_16x16x32_bf16 v[90:93], v[168:171], v[208:211], v[90:93]
	v_mfma_f32_16x16x32_bf16 v[74:77], v[168:171], v[216:219], v[74:77]
	s_setprio 0
	s_setprio 1
	v_mfma_f32_16x16x32_bf16 v[118:121], v[172:175], v[188:191], v[118:121]
	v_mfma_f32_16x16x32_bf16 v[102:105], v[172:175], v[196:199], v[102:105]
	v_mfma_f32_16x16x32_bf16 v[86:89], v[172:175], v[204:207], v[86:89]
	v_mfma_f32_16x16x32_bf16 v[70:73], v[172:175], v[212:215], v[70:73]
	v_mfma_f32_16x16x32_bf16 v[114:117], v[180:183], v[188:191], v[114:117]
	v_mfma_f32_16x16x32_bf16 v[98:101], v[180:183], v[196:199], v[98:101]
	v_mfma_f32_16x16x32_bf16 v[82:85], v[180:183], v[204:207], v[82:85]
	v_mfma_f32_16x16x32_bf16 v[66:69], v[180:183], v[212:215], v[66:69]
	v_mfma_f32_16x16x32_bf16 v[118:121], v[176:179], v[192:195], v[118:121]
	v_mfma_f32_16x16x32_bf16 v[102:105], v[176:179], v[200:203], v[102:105]
	v_mfma_f32_16x16x32_bf16 v[86:89], v[176:179], v[208:211], v[86:89]
	v_mfma_f32_16x16x32_bf16 v[70:73], v[176:179], v[216:219], v[70:73]
	v_mfma_f32_16x16x32_bf16 v[114:117], v[184:187], v[192:195], v[114:117]
	v_mfma_f32_16x16x32_bf16 v[98:101], v[184:187], v[200:203], v[98:101]
	v_mfma_f32_16x16x32_bf16 v[82:85], v[184:187], v[208:211], v[82:85]
	v_mfma_f32_16x16x32_bf16 v[66:69], v[184:187], v[216:219], v[66:69]
	s_setprio 0
	s_barrier
	s_add_i32 s12, s60, s6
	s_mov_b32 m0, s12
	ds_read_b128 v[188:191], v157 offset:49152
	ds_read_b128 v[192:195], v157 offset:50176
	ds_read_b128 v[196:199], v157 offset:51200
	ds_read_b128 v[200:203], v157 offset:52224
	ds_read_b128 v[204:207], v157 offset:53248
	ds_read_b128 v[208:211], v157 offset:54272
	ds_read_b128 v[212:215], v157 offset:55296
	ds_read_b128 v[216:219], v157 offset:56320
	global_load_lds_dwordx4 v134, s[98:99]
	s_add_i32 m0, s12, 0x2000
	s_add_u32 s12, s38, 0x40800
	s_addc_u32 s13, s39, 0
	s_add_i32 s38, s61, s6
	global_load_lds_dwordx4 v130, s[98:99]
	s_mov_b32 m0, s38
	s_nop 0
	global_load_lds_dwordx4 v134, s[12:13]
	s_add_i32 m0, s38, 0x2000
	s_nop 0
	global_load_lds_dwordx4 v130, s[12:13]
	s_mov_b32 m0, s49
	s_nop 0
	global_load_lds_dwordx4 v136, s[100:101]
	s_mov_b32 m0, s50
	s_nop 0
	global_load_lds_dwordx4 v132, s[100:101]
	s_waitcnt vmcnt(8)
	s_waitcnt lgkmcnt(0)
	s_barrier
	s_setprio 1
	s_waitcnt lgkmcnt(0)
	v_mfma_f32_16x16x32_bf16 v[62:65], v[150:153], v[188:191], v[62:65]
	v_mfma_f32_16x16x32_bf16 v[38:41], v[150:153], v[196:199], v[38:41]
	v_mfma_f32_16x16x32_bf16 v[22:25], v[150:153], v[204:207], v[22:25]
	v_mfma_f32_16x16x32_bf16 v[6:9], v[150:153], v[212:215], v[6:9]
	v_mfma_f32_16x16x32_bf16 v[58:61], v[164:167], v[188:191], v[58:61]
	v_mfma_f32_16x16x32_bf16 v[34:37], v[164:167], v[196:199], v[34:37]
	v_mfma_f32_16x16x32_bf16 v[18:21], v[164:167], v[204:207], v[18:21]
	v_mfma_f32_16x16x32_bf16 v[2:5], v[164:167], v[212:215], v[2:5]
	v_mfma_f32_16x16x32_bf16 v[62:65], v[160:163], v[192:195], v[62:65]
	v_mfma_f32_16x16x32_bf16 v[38:41], v[160:163], v[200:203], v[38:41]
	v_mfma_f32_16x16x32_bf16 v[22:25], v[160:163], v[208:211], v[22:25]
	v_mfma_f32_16x16x32_bf16 v[6:9], v[160:163], v[216:219], v[6:9]
	v_mfma_f32_16x16x32_bf16 v[58:61], v[168:171], v[192:195], v[58:61]
	v_mfma_f32_16x16x32_bf16 v[34:37], v[168:171], v[200:203], v[34:37]
	v_mfma_f32_16x16x32_bf16 v[18:21], v[168:171], v[208:211], v[18:21]
	v_mfma_f32_16x16x32_bf16 v[2:5], v[168:171], v[216:219], v[2:5]
	s_setprio 0
	s_setprio 1
	v_mfma_f32_16x16x32_bf16 v[54:57], v[172:175], v[188:191], v[54:57]
	v_mfma_f32_16x16x32_bf16 v[42:45], v[172:175], v[196:199], v[42:45]
	v_mfma_f32_16x16x32_bf16 v[26:29], v[172:175], v[204:207], v[26:29]
	v_mfma_f32_16x16x32_bf16 v[10:13], v[172:175], v[212:215], v[10:13]
	v_mfma_f32_16x16x32_bf16 v[50:53], v[180:183], v[188:191], v[50:53]
	v_mfma_f32_16x16x32_bf16 v[46:49], v[180:183], v[196:199], v[46:49]
	v_mfma_f32_16x16x32_bf16 v[30:33], v[180:183], v[204:207], v[30:33]
	v_mfma_f32_16x16x32_bf16 v[14:17], v[180:183], v[212:215], v[14:17]
	v_mfma_f32_16x16x32_bf16 v[54:57], v[176:179], v[192:195], v[54:57]
	v_mfma_f32_16x16x32_bf16 v[42:45], v[176:179], v[200:203], v[42:45]
	v_mfma_f32_16x16x32_bf16 v[26:29], v[176:179], v[208:211], v[26:29]
	v_mfma_f32_16x16x32_bf16 v[10:13], v[176:179], v[216:219], v[10:13]
	v_mfma_f32_16x16x32_bf16 v[50:53], v[184:187], v[192:195], v[50:53]
	v_mfma_f32_16x16x32_bf16 v[46:49], v[184:187], v[200:203], v[46:49]
	v_mfma_f32_16x16x32_bf16 v[30:33], v[184:187], v[208:211], v[30:33]
	v_mfma_f32_16x16x32_bf16 v[14:17], v[184:187], v[216:219], v[14:17]
	s_setprio 0
	s_barrier
	s_add_i32 s57, s57, 2
	s_add_u32 s55, s55, 0x1000
	s_addc_u32 s56, s56, 0
	s_add_u32 s36, s36, 0x100
	s_addc_u32 s37, s37, 0
	s_cmp_gt_u32 s57, 13
	s_cbranch_scc0 .LBB0_796
	s_and_b64 vcc, exec, s[16:17]
	s_cbranch_vccz .LBB0_799
	s_barrier

; #define PG8_WAIT_V(n) asm volatile("s_waitcnt vmcnt(" #n ")" ::: "memory")
; #define PG8_BAR __builtin_amdgcn_s_barrier()
; template <class Epi, bool ALIGN_EPI, bool SPLITA>
; __device__ __forceinline__ void gemm_phase(LAS unsigned char* lds, const Gemm g, const StaticOrder& S, const Epi& E) {
;     ...
;         const bool has_next = S.next(ui + 1, nxt);
;         const char* nA = has_next ? baseA1(nxt) : cA;
;         const char* nB = has_next ? baseB(nxt) : cB;
;         const bool mirN = has_next ? mirrored(nxt) : mirC;
;         for (int t = 0; t < nt; t += 2) {
;             const bool last = (t == nt - 2);
;             if constexpr (Epi::MIDK) { if (t == g.ksplit) E.mid(acc, cur, wr, wc, fr, fq); }
;             const char *a1, *a2;
;             if constexpr (SPLITA) {
;                 a1 = (t + 1 < g.ksplit) ? cA + (size_t)(t + 1) * kstep : cA2 + (size_t)(t + 1 - g.ksplit) * 2048;
;                 a2 = last ? nA : ((t + 2 < g.ksplit) ? cA + (size_t)(t + 2) * kstep : cA2 + (size_t)(t + 2 - g.ksplit) * 2048);
;             } else { a1 = cA + kofs(t + 1); a2 = last ? nA : cA + kofs(t + 2); }
;             const char* b2 = last ? nB : cB + (size_t)(t + 2) * kstepB;
;             const bool s2a = SPLITA && (t + 1 >= g.ksplit), s2b = SPLITA && !last && (t + 2 >= g.ksplit);
;             const char* a3 = a2 + ((Epi::KSUB || s2b) ? (size_t)2048 : kstep); const char* b3 = b2 + kstepB;
;             const bool m1 = SPLITA && mirC && (t + 1 < g.ksplit), m2 = SPLITA && (last ? mirN : (mirC && (t + 2 < g.ksplit)));
;             const unsigned vo1[2] = {s2a ? voffA2[0] : m1 ? voffAm[0] : voffA[0], s2a ? voffA2[1] : m1 ? voffAm[1] : voffA[1]}, vo2[2] = {s2b ? voffA2[0] : m2 ? voffAm[0] : voffA[0], s2b ? voffA2[1] : m2 ? voffAm[1] : voffA[1]};
;             const char* a1h = m1 ? a1 - hstepA : a1 + hstepA; const char* a2h = m2 ? a2 - hstepA : a2 + hstepA;
;             PG8_LDB(B0, 0, 0); PG8_LDB(B1, 0, 1); PG8_SCHED; PG8_LDA(At, 0, 0); PG8_STAGE(PG8_SA(1, 1), a1h, vo1);
;             PG8_WAIT_V(8); PG8_WAIT_L(0); PG8_BAR; PG8_MMA(0, 0, At, B0); PG8_MMA(0, 1, At, B1); PG8_BAR; PG8_SCHED;
;             PG8_LDA(At, 0, 1); PG8_STAGE(PG8_SB(0, 0), b2, voffB); PG8_STAGE(PG8_SB(0, 1), b2 + hstepB, voffB); PG8_STAGE(PG8_SA(0, 0), a2, vo2);
;             PG8_WAIT_V(8); PG8_WAIT_L(0); PG8_BAR; PG8_MMA(1, 0, At, B0); PG8_MMA(1, 1, At, B1); PG8_BAR; PG8_SCHED;
.LBB0_866:
	s_ashr_i32 s17, s16, 31
	s_lshl_b64 s[12:13], s[16:17], 21
	s_add_u32 s20, s82, s12
	s_addc_u32 s21, s83, s13
	s_and_b64 s[12:13], s[0:1], exec
	s_cselect_b32 s17, s21, s27
	s_cselect_b32 s48, s20, s26
	s_ashr_i32 s19, s18, 31
	s_lshl_b64 s[12:13], s[18:19], 21
	s_add_u32 s22, s78, s12
	s_addc_u32 s23, s79, s13
	s_and_b64 s[12:13], s[0:1], exec
	s_cselect_b32 s19, s23, s29
	s_cselect_b32 s49, s22, s28
	s_add_u32 s50, s28, 0x100
	s_addc_u32 s51, s29, 0
	s_mov_b32 s28, -2
	s_movk_i32 s52, 0x1000
	s_add_i32 s53, s28, 2
	s_lshr_b32 s2, s53, 2
	s_lshl_b64 s[12:13], s[2:3], 17
	s_add_i32 s2, s52, 0xfffff000
	s_and_b32 s2, s2, 0x1000
	s_add_u32 s12, s26, s12
	s_addc_u32 s13, s27, s13
	s_add_u32 s29, s12, s2
	s_addc_u32 s30, s13, 0
	s_add_i32 s2, s28, 4
	ds_read_b128 v[140:143], v151
	ds_read_b128 v[144:147], v151 offset:1024
	ds_read_b128 v[154:157], v151 offset:2048
	ds_read_b128 v[158:161], v151 offset:3072
	ds_read_b128 v[162:165], v152
	ds_read_b128 v[166:169], v152 offset:1024
	ds_read_b128 v[170:173], v152 offset:2048
	ds_read_b128 v[174:177], v152 offset:3072
	s_lshr_b32 s2, s2, 2
	s_lshl_b64 s[12:13], s[2:3], 17
	s_and_b32 s2, s52, 0x1000
	s_add_u32 s12, s26, s12
	s_addc_u32 s13, s27, s13
	s_add_u32 s2, s12, s2
	s_addc_u32 s31, s13, 0
	s_add_u32 s12, s29, 0x10800
	s_addc_u32 s13, s30, 0
	s_cmp_eq_u32 s28, 60
	s_cselect_b32 s28, s49, s50
	s_cselect_b32 s31, s17, s31
	s_cselect_b32 s30, s48, s2
	s_cselect_b32 s29, s19, s51
	s_add_i32 m0, s25, 0xc000
	ds_read_b128 v[178:181], v153
	ds_read_b128 v[182:185], v153 offset:1024
	ds_read_b128 v[186:189], v153 offset:2048
	ds_read_b128 v[190:193], v153 offset:3072
	ds_read_b128 v[194:197], v153 offset:4096
	ds_read_b128 v[198:201], v153 offset:5120
	ds_read_b128 v[202:205], v153 offset:6144
	ds_read_b128 v[206:209], v153 offset:7168
	global_load_lds_dwordx4 v134, s[12:13]
	s_add_i32 m0, s25, 0xe000
	s_nop 0
	global_load_lds_dwordx4 v130, s[12:13]
	s_waitcnt vmcnt(8)
	s_waitcnt lgkmcnt(0)
	s_barrier
	s_setprio 1
	s_waitcnt lgkmcnt(0)
	v_mfma_f32_16x16x32_bf16 v[124:127], v[140:143], v[178:181], 0
	v_mfma_f32_16x16x32_bf16 v[108:111], v[140:143], v[186:189], 0
	v_mfma_f32_16x16x32_bf16 v[96:99], v[140:143], v[194:197], 0
	v_mfma_f32_16x16x32_bf16 v[80:83], v[140:143], v[202:205], 0
	v_mfma_f32_16x16x32_bf16 v[120:123], v[154:157], v[178:181], 0
	v_mfma_f32_16x16x32_bf16 v[104:107], v[154:157], v[186:189], 0
	v_mfma_f32_16x16x32_bf16 v[88:91], v[154:157], v[194:197], 0
	v_mfma_f32_16x16x32_bf16 v[72:75], v[154:157], v[202:205], 0
	v_mfma_f32_16x16x32_bf16 v[124:127], v[144:147], v[182:185], v[124:127]
	v_mfma_f32_16x16x32_bf16 v[108:111], v[144:147], v[190:193], v[108:111]
	v_mfma_f32_16x16x32_bf16 v[96:99], v[144:147], v[198:201], v[96:99]
	v_mfma_f32_16x16x32_bf16 v[80:83], v[144:147], v[206:209], v[80:83]
	v_mfma_f32_16x16x32_bf16 v[120:123], v[158:161], v[182:185], v[120:123]
	v_mfma_f32_16x16x32_bf16 v[104:107], v[158:161], v[190:193], v[104:107]
	v_mfma_f32_16x16x32_bf16 v[88:91], v[158:161], v[198:201], v[88:91]
	v_mfma_f32_16x16x32_bf16 v[72:75], v[158:161], v[206:209], v[72:75]
	s_setprio 0
	s_setprio 1
	v_mfma_f32_16x16x32_bf16 v[116:119], v[162:165], v[178:181], 0
	v_mfma_f32_16x16x32_bf16 v[100:103], v[162:165], v[186:189], 0
	v_mfma_f32_16x16x32_bf16 v[84:87], v[162:165], v[194:197], 0
	v_mfma_f32_16x16x32_bf16 v[68:71], v[162:165], v[202:205], 0
	v_mfma_f32_16x16x32_bf16 v[112:115], v[170:173], v[178:181], 0
	v_mfma_f32_16x16x32_bf16 v[92:95], v[170:173], v[186:189], 0
	v_mfma_f32_16x16x32_bf16 v[76:79], v[170:173], v[194:197], 0
	v_mfma_f32_16x16x32_bf16 v[64:67], v[170:173], v[202:205], 0
	v_mfma_f32_16x16x32_bf16 v[116:119], v[166:169], v[182:185], v[116:119]
	v_mfma_f32_16x16x32_bf16 v[100:103], v[166:169], v[190:193], v[100:103]
	v_mfma_f32_16x16x32_bf16 v[84:87], v[166:169], v[198:201], v[84:87]
	v_mfma_f32_16x16x32_bf16 v[68:71], v[166:169], v[206:209], v[68:71]
	v_mfma_f32_16x16x32_bf16 v[112:115], v[174:177], v[182:185], v[112:115]
	v_mfma_f32_16x16x32_bf16 v[92:95], v[174:177], v[190:193], v[92:95]
	v_mfma_f32_16x16x32_bf16 v[76:79], v[174:177], v[198:201], v[76:79]
	v_mfma_f32_16x16x32_bf16 v[64:67], v[174:177], v[206:209], v[64:67]
	s_setprio 0
	s_barrier
	s_add_u32 s98, s28, s6
	s_addc_u32 s99, s29, s7
	s_add_u32 s100, s30, s8
	s_addc_u32 s101, s31, s9
	s_add_i32 s2, s44, s33
	s_mov_b32 m0, s2
	ds_read_b128 v[178:181], v153 offset:16384
	ds_read_b128 v[182:185], v153 offset:17408
	ds_read_b128 v[186:189], v153 offset:18432
	ds_read_b128 v[190:193], v153 offset:19456
	ds_read_b128 v[194:197], v153 offset:20480
	ds_read_b128 v[198:201], v153 offset:21504
	ds_read_b128 v[202:205], v153 offset:22528
	ds_read_b128 v[206:209], v153 offset:23552
	global_load_lds_dwordx4 v132, s[28:29]
	s_add_i32 m0, s2, 0x2000
	s_add_u32 s12, s28, 0x100000
	s_addc_u32 s13, s29, 0
	s_add_i32 s2, s45, s33
	global_load_lds_dwordx4 v128, s[28:29]
	s_mov_b32 m0, s2
	s_nop 0
	global_load_lds_dwordx4 v132, s[12:13]
	s_add_i32 m0, s2, 0x2000
	s_nop 0
	global_load_lds_dwordx4 v128, s[12:13]
	s_mov_b32 m0, s25
	s_nop 0
	global_load_lds_dwordx4 v134, s[30:31]
	s_mov_b32 m0, s38
	s_nop 0
	global_load_lds_dwordx4 v130, s[30:31]
	s_waitcnt vmcnt(8)
	s_waitcnt lgkmcnt(0)
	s_barrier
; #define PG8_STAGE(bufoff, gbase, voff) do { _Pragma("unroll") for (int _i = 0; _i < 2; ++_i) \
;         __builtin_amdgcn_global_load_lds((const unsigned*)((const char*)(gbase) + (voff)[_i]), (LAS unsigned*)(lds + (bufoff) + ldsw + _i * 8192), 16, 0, 0); } while (0)
; #define PG8_LDA(dst, b, h) do { _Pragma("unroll") for (int m = 0; m < 4; ++m) _Pragma("unroll") for (int k = 0; k < 2; ++k) dst[m][k] = *(const LAS bf16x8*)(lds + PG8_SA(b, h) + aoff + m * 2048 + k * 1024); } while (0)
; #define PG8_LDB(dst, b, h) do { _Pragma("unroll") for (int n = 0; n < 2; ++n) _Pragma("unroll") for (int k = 0; k < 2; ++k) dst[n][k] = *(const LAS bf16x8*)(lds + PG8_SB(b, h) + boff + n * 2048 + k * 1024); } while (0)
; #define PG8_MMA(ai, bj, At, Bt) do { __builtin_amdgcn_s_setprio(1); _Pragma("unroll") for (int m = 0; m < 4; ++m) _Pragma("unroll") for (int n = 0; n < 2; ++n) _Pragma("unroll") for (int k = 0; k < 2; ++k) \
;         acc[ai][bj][m][n] = __builtin_amdgcn_mfma_f32_16x16x32_bf16(Bt[n][k], At[m][k], acc[ai][bj][m][n], 0, 0, 0); __builtin_amdgcn_s_setprio(0); } while (0)
; #define PG8_WAIT_V(n) asm volatile("s_waitcnt vmcnt(" #n ")" ::: "memory")
; #define PG8_WAIT_L(n) asm volatile("s_waitcnt lgkmcnt(" #n ")" ::: "memory")
; #define PG8_BAR __builtin_amdgcn_s_barrier()
; #define PG8_SCHED __builtin_amdgcn_sched_barrier(0)
; template <class Epi, bool ALIGN_EPI, bool SPLITA>
; __device__ __forceinline__ void gemm_phase(LAS unsigned char* lds, const Gemm g, const StaticOrder& S, const Epi& E) {
;     ...
;             PG8_WAIT_V(8); PG8_WAIT_L(0); PG8_BAR; PG8_MMA(1, 0, At, B0); PG8_MMA(1, 1, At, B1); PG8_BAR; PG8_SCHED;
;             PG8_LDB(B0, 1, 0); PG8_LDB(B1, 1, 1); PG8_SCHED; PG8_LDA(At, 1, 0); PG8_STAGE(PG8_SA(0, 1), a2h, vo2);
;             PG8_WAIT_V(8); PG8_WAIT_L(0); PG8_BAR; PG8_MMA(0, 0, At, B0); PG8_MMA(0, 1, At, B1); PG8_BAR; PG8_SCHED;
	s_setprio 1
	s_waitcnt lgkmcnt(0)
	v_mfma_f32_16x16x32_bf16 v[60:63], v[140:143], v[178:181], 0
	v_mfma_f32_16x16x32_bf16 v[40:43], v[140:143], v[186:189], 0
	v_mfma_f32_16x16x32_bf16 v[20:23], v[140:143], v[194:197], 0
	v_mfma_f32_16x16x32_bf16 v[4:7], v[140:143], v[202:205], 0
	v_mfma_f32_16x16x32_bf16 v[56:59], v[154:157], v[178:181], 0
	v_mfma_f32_16x16x32_bf16 v[32:35], v[154:157], v[186:189], 0
	v_mfma_f32_16x16x32_bf16 v[8:11], v[154:157], v[194:197], 0
	v_mfma_f32_16x16x32_bf16 v[0:3], v[154:157], v[202:205], 0
	v_mfma_f32_16x16x32_bf16 v[60:63], v[144:147], v[182:185], v[60:63]
	v_mfma_f32_16x16x32_bf16 v[40:43], v[144:147], v[190:193], v[40:43]
	v_mfma_f32_16x16x32_bf16 v[20:23], v[144:147], v[198:201], v[20:23]
	v_mfma_f32_16x16x32_bf16 v[4:7], v[144:147], v[206:209], v[4:7]
	v_mfma_f32_16x16x32_bf16 v[56:59], v[158:161], v[182:185], v[56:59]
	v_mfma_f32_16x16x32_bf16 v[32:35], v[158:161], v[190:193], v[32:35]
	v_mfma_f32_16x16x32_bf16 v[8:11], v[158:161], v[198:201], v[8:11]
	v_mfma_f32_16x16x32_bf16 v[0:3], v[158:161], v[206:209], v[0:3]
	s_setprio 0
	s_setprio 1
	v_mfma_f32_16x16x32_bf16 v[44:47], v[162:165], v[178:181], 0
	v_mfma_f32_16x16x32_bf16 v[52:55], v[162:165], v[186:189], 0
	v_mfma_f32_16x16x32_bf16 v[28:31], v[162:165], v[194:197], 0
	v_mfma_f32_16x16x32_bf16 v[16:19], v[162:165], v[202:205], 0
	v_mfma_f32_16x16x32_bf16 v[36:39], v[170:173], v[178:181], 0
	v_mfma_f32_16x16x32_bf16 v[48:51], v[170:173], v[186:189], 0
	v_mfma_f32_16x16x32_bf16 v[24:27], v[170:173], v[194:197], 0
	v_mfma_f32_16x16x32_bf16 v[12:15], v[170:173], v[202:205], 0
	v_mfma_f32_16x16x32_bf16 v[44:47], v[166:169], v[182:185], v[44:47]
	v_mfma_f32_16x16x32_bf16 v[52:55], v[166:169], v[190:193], v[52:55]
	v_mfma_f32_16x16x32_bf16 v[28:31], v[166:169], v[198:201], v[28:31]
	v_mfma_f32_16x16x32_bf16 v[16:19], v[166:169], v[206:209], v[16:19]
	v_mfma_f32_16x16x32_bf16 v[36:39], v[174:177], v[182:185], v[36:39]
	v_mfma_f32_16x16x32_bf16 v[48:51], v[174:177], v[190:193], v[48:51]
	v_mfma_f32_16x16x32_bf16 v[24:27], v[174:177], v[198:201], v[24:27]
	v_mfma_f32_16x16x32_bf16 v[12:15], v[174:177], v[206:209], v[12:15]
	s_setprio 0
	s_barrier
	s_add_i32 s2, 0, 0x18000
	s_add_i32 s54, 0, 0x1c000
	v_add_u32_e32 v158, s2, v149
	v_add_u32_e32 v174, s54, v149
	ds_read_b128 v[140:143], v158
	ds_read_b128 v[144:147], v158 offset:1024
	ds_read_b128 v[154:157], v158 offset:2048
	ds_read_b128 v[158:161], v158 offset:3072
	ds_read_b128 v[162:165], v174
	ds_read_b128 v[166:169], v174 offset:1024
	ds_read_b128 v[170:173], v174 offset:2048
	ds_read_b128 v[174:177], v174 offset:3072
	s_add_u32 s12, s30, 0x10000
	s_addc_u32 s13, s31, 0
	s_mov_b32 m0, s39
	ds_read_b128 v[178:181], v153 offset:32768
	ds_read_b128 v[182:185], v153 offset:33792
	ds_read_b128 v[186:189], v153 offset:34816
	ds_read_b128 v[190:193], v153 offset:35840
	ds_read_b128 v[194:197], v153 offset:36864
	ds_read_b128 v[198:201], v153 offset:37888
	ds_read_b128 v[202:205], v153 offset:38912
	ds_read_b128 v[206:209], v153 offset:39936
	global_load_lds_dwordx4 v134, s[12:13]
	s_mov_b32 m0, s40
	s_nop 0
	global_load_lds_dwordx4 v130, s[12:13]
	s_waitcnt vmcnt(8)
	s_waitcnt lgkmcnt(0)
	s_barrier
	s_setprio 1
	s_waitcnt lgkmcnt(0)
	v_mfma_f32_16x16x32_bf16 v[124:127], v[140:143], v[178:181], v[124:127]
	v_mfma_f32_16x16x32_bf16 v[108:111], v[140:143], v[186:189], v[108:111]
	v_mfma_f32_16x16x32_bf16 v[96:99], v[140:143], v[194:197], v[96:99]
	v_mfma_f32_16x16x32_bf16 v[80:83], v[140:143], v[202:205], v[80:83]
	v_mfma_f32_16x16x32_bf16 v[120:123], v[154:157], v[178:181], v[120:123]
	v_mfma_f32_16x16x32_bf16 v[104:107], v[154:157], v[186:189], v[104:107]
	v_mfma_f32_16x16x32_bf16 v[88:91], v[154:157], v[194:197], v[88:91]
	v_mfma_f32_16x16x32_bf16 v[72:75], v[154:157], v[202:205], v[72:75]
	v_mfma_f32_16x16x32_bf16 v[124:127], v[144:147], v[182:185], v[124:127]
	v_mfma_f32_16x16x32_bf16 v[108:111], v[144:147], v[190:193], v[108:111]
	v_mfma_f32_16x16x32_bf16 v[96:99], v[144:147], v[198:201], v[96:99]
	v_mfma_f32_16x16x32_bf16 v[80:83], v[144:147], v[206:209], v[80:83]
	v_mfma_f32_16x16x32_bf16 v[120:123], v[158:161], v[182:185], v[120:123]
	v_mfma_f32_16x16x32_bf16 v[104:107], v[158:161], v[190:193], v[104:107]
	v_mfma_f32_16x16x32_bf16 v[88:91], v[158:161], v[198:201], v[88:91]
	v_mfma_f32_16x16x32_bf16 v[72:75], v[158:161], v[206:209], v[72:75]
	s_setprio 0
	s_setprio 1
	v_mfma_f32_16x16x32_bf16 v[116:119], v[162:165], v[178:181], v[116:119]
	v_mfma_f32_16x16x32_bf16 v[100:103], v[162:165], v[186:189], v[100:103]
	v_mfma_f32_16x16x32_bf16 v[84:87], v[162:165], v[194:197], v[84:87]
	v_mfma_f32_16x16x32_bf16 v[68:71], v[162:165], v[202:205], v[68:71]
	v_mfma_f32_16x16x32_bf16 v[112:115], v[170:173], v[178:181], v[112:115]
	v_mfma_f32_16x16x32_bf16 v[92:95], v[170:173], v[186:189], v[92:95]
	v_mfma_f32_16x16x32_bf16 v[76:79], v[170:173], v[194:197], v[76:79]
	v_mfma_f32_16x16x32_bf16 v[64:67], v[170:173], v[202:205], v[64:67]
	v_mfma_f32_16x16x32_bf16 v[116:119], v[166:169], v[182:185], v[116:119]
	v_mfma_f32_16x16x32_bf16 v[100:103], v[166:169], v[190:193], v[100:103]
	v_mfma_f32_16x16x32_bf16 v[84:87], v[166:169], v[198:201], v[84:87]
	v_mfma_f32_16x16x32_bf16 v[68:71], v[166:169], v[206:209], v[68:71]
	v_mfma_f32_16x16x32_bf16 v[112:115], v[174:177], v[182:185], v[112:115]
	v_mfma_f32_16x16x32_bf16 v[92:95], v[174:177], v[190:193], v[92:95]
	v_mfma_f32_16x16x32_bf16 v[76:79], v[174:177], v[198:201], v[76:79]
	v_mfma_f32_16x16x32_bf16 v[64:67], v[174:177], v[206:209], v[64:67]
	s_setprio 0
	s_barrier
; #define PG8_STAGE(bufoff, gbase, voff) do { _Pragma("unroll") for (int _i = 0; _i < 2; ++_i) \
;         __builtin_amdgcn_global_load_lds((const unsigned*)((const char*)(gbase) + (voff)[_i]), (LAS unsigned*)(lds + (bufoff) + ldsw + _i * 8192), 16, 0, 0); } while (0)
; #define PG8_WAIT_V(n) asm volatile("s_waitcnt vmcnt(" #n ")" ::: "memory")
; template <class Epi, bool ALIGN_EPI, bool SPLITA>
; __device__ __forceinline__ void gemm_phase(LAS unsigned char* lds, const Gemm g, const StaticOrder& S, const Epi& E) {
;     ...
;         for (int t = 0; t < nt; t += 2) {
;             const bool last = (t == nt - 2);
;             if constexpr (Epi::MIDK) { if (t == g.ksplit) E.mid(acc, cur, wr, wc, fr, fq); }
;             const char *a1, *a2;
;             if constexpr (SPLITA) {
;                 a1 = (t + 1 < g.ksplit) ? cA + (size_t)(t + 1) * kstep : cA2 + (size_t)(t + 1 - g.ksplit) * 2048;
;                 a2 = last ? nA : ((t + 2 < g.ksplit) ? cA + (size_t)(t + 2) * kstep : cA2 + (size_t)(t + 2 - g.ksplit) * 2048);
;             } else { a1 = cA + kofs(t + 1); a2 = last ? nA : cA + kofs(t + 2); }
;             const char* b2 = last ? nB : cB + (size_t)(t + 2) * kstepB;
;             const bool s2a = SPLITA && (t + 1 >= g.ksplit), s2b = SPLITA && !last && (t + 2 >= g.ksplit);
;             const char* a3 = a2 + ((Epi::KSUB || s2b) ? (size_t)2048 : kstep); const char* b3 = b2 + kstepB;
;             const bool m1 = SPLITA && mirC && (t + 1 < g.ksplit), m2 = SPLITA && (last ? mirN : (mirC && (t + 2 < g.ksplit)));
;             const unsigned vo1[2] = {s2a ? voffA2[0] : m1 ? voffAm[0] : voffA[0], s2a ? voffA2[1] : m1 ? voffAm[1] : voffA[1]}, vo2[2] = {s2b ? voffA2[0] : m2 ? voffAm[0] : voffA[0], s2b ? voffA2[1] : m2 ? voffAm[1] : voffA[1]};
;             const char* a1h = m1 ? a1 - hstepA : a1 + hstepA; const char* a2h = m2 ? a2 - hstepA : a2 + hstepA;
;             PG8_LDB(B0, 0, 0); PG8_LDB(B1, 0, 1); PG8_SCHED; PG8_LDA(At, 0, 0); PG8_STAGE(PG8_SA(1, 1), a1h, vo1);
;             PG8_WAIT_V(8); PG8_WAIT_L(0); PG8_BAR; PG8_MMA(0, 0, At, B0); PG8_MMA(0, 1, At, B1); PG8_BAR; PG8_SCHED;
;     ...
;             PG8_LDA(At, 1, 1); PG8_STAGE(PG8_SB(1, 0), b3, voffB); PG8_STAGE(PG8_SB(1, 1), b3 + hstepB, voffB); PG8_STAGE(PG8_SA(1, 0), a3, vo2);
;             PG8_WAIT_V(8); PG8_WAIT_L(0); PG8_BAR; PG8_MMA(1, 0, At, B0); PG8_MMA(1, 1, At, B1); PG8_BAR; PG8_SCHED;
	s_add_i32 s2, s2, s33
	s_mov_b32 m0, s2
	ds_read_b128 v[178:181], v153 offset:49152
	ds_read_b128 v[182:185], v153 offset:50176
	ds_read_b128 v[186:189], v153 offset:51200
	ds_read_b128 v[190:193], v153 offset:52224
	ds_read_b128 v[194:197], v153 offset:53248
	ds_read_b128 v[198:201], v153 offset:54272
	ds_read_b128 v[202:205], v153 offset:55296
	ds_read_b128 v[206:209], v153 offset:56320
	global_load_lds_dwordx4 v132, s[98:99]
	s_add_i32 m0, s2, 0x2000
	s_add_u32 s12, s28, 0x100080
	s_addc_u32 s13, s29, 0
	s_add_i32 s2, s54, s33
	global_load_lds_dwordx4 v128, s[98:99]
	s_mov_b32 m0, s2
	s_nop 0
	global_load_lds_dwordx4 v132, s[12:13]
	s_add_i32 m0, s2, 0x2000
	s_nop 0
	global_load_lds_dwordx4 v128, s[12:13]
	s_mov_b32 m0, s41
	s_nop 0
	global_load_lds_dwordx4 v134, s[100:101]
	s_mov_b32 m0, s42
	s_nop 0
	global_load_lds_dwordx4 v130, s[100:101]
	s_waitcnt vmcnt(8)
	s_waitcnt lgkmcnt(0)
	s_barrier
	s_setprio 1
	s_waitcnt lgkmcnt(0)
	v_mfma_f32_16x16x32_bf16 v[60:63], v[140:143], v[178:181], v[60:63]
	v_mfma_f32_16x16x32_bf16 v[40:43], v[140:143], v[186:189], v[40:43]
	v_mfma_f32_16x16x32_bf16 v[20:23], v[140:143], v[194:197], v[20:23]
	v_mfma_f32_16x16x32_bf16 v[4:7], v[140:143], v[202:205], v[4:7]
	v_mfma_f32_16x16x32_bf16 v[56:59], v[154:157], v[178:181], v[56:59]
	v_mfma_f32_16x16x32_bf16 v[32:35], v[154:157], v[186:189], v[32:35]
	v_mfma_f32_16x16x32_bf16 v[8:11], v[154:157], v[194:197], v[8:11]
	v_mfma_f32_16x16x32_bf16 v[0:3], v[154:157], v[202:205], v[0:3]
	v_mfma_f32_16x16x32_bf16 v[60:63], v[144:147], v[182:185], v[60:63]
	v_mfma_f32_16x16x32_bf16 v[40:43], v[144:147], v[190:193], v[40:43]
	v_mfma_f32_16x16x32_bf16 v[20:23], v[144:147], v[198:201], v[20:23]
	v_mfma_f32_16x16x32_bf16 v[4:7], v[144:147], v[206:209], v[4:7]
	v_mfma_f32_16x16x32_bf16 v[56:59], v[158:161], v[182:185], v[56:59]
	v_mfma_f32_16x16x32_bf16 v[32:35], v[158:161], v[190:193], v[32:35]
	v_mfma_f32_16x16x32_bf16 v[8:11], v[158:161], v[198:201], v[8:11]
	v_mfma_f32_16x16x32_bf16 v[0:3], v[158:161], v[206:209], v[0:3]
	s_setprio 0
	s_setprio 1
	v_mfma_f32_16x16x32_bf16 v[44:47], v[162:165], v[178:181], v[44:47]
	v_mfma_f32_16x16x32_bf16 v[52:55], v[162:165], v[186:189], v[52:55]
	v_mfma_f32_16x16x32_bf16 v[28:31], v[162:165], v[194:197], v[28:31]
	v_mfma_f32_16x16x32_bf16 v[16:19], v[162:165], v[202:205], v[16:19]
	v_mfma_f32_16x16x32_bf16 v[36:39], v[170:173], v[178:181], v[36:39]
	v_mfma_f32_16x16x32_bf16 v[48:51], v[170:173], v[186:189], v[48:51]
	v_mfma_f32_16x16x32_bf16 v[24:27], v[170:173], v[194:197], v[24:27]
	v_mfma_f32_16x16x32_bf16 v[12:15], v[170:173], v[202:205], v[12:15]
	v_mfma_f32_16x16x32_bf16 v[44:47], v[166:169], v[182:185], v[44:47]
	v_mfma_f32_16x16x32_bf16 v[52:55], v[166:169], v[190:193], v[52:55]
	v_mfma_f32_16x16x32_bf16 v[28:31], v[166:169], v[198:201], v[28:31]
	v_mfma_f32_16x16x32_bf16 v[16:19], v[166:169], v[206:209], v[16:19]
	v_mfma_f32_16x16x32_bf16 v[36:39], v[174:177], v[182:185], v[36:39]
	v_mfma_f32_16x16x32_bf16 v[48:51], v[174:177], v[190:193], v[48:51]
	v_mfma_f32_16x16x32_bf16 v[24:27], v[174:177], v[198:201], v[24:27]
	v_mfma_f32_16x16x32_bf16 v[12:15], v[174:177], v[206:209], v[12:15]
	s_setprio 0
	s_barrier
	s_add_u32 s50, s50, 0x100
	s_addc_u32 s51, s51, 0
	s_addk_i32 s52, 0x1000
	s_mov_b32 s28, s53
.LBB0_867:
	s_add_i32 s53, s28, 2
	s_lshr_b32 s2, s53, 2
	s_lshl_b64 s[12:13], s[2:3], 17
	s_add_i32 s2, s52, 0xfffff000
	s_and_b32 s2, s2, 0x1000
	s_add_u32 s12, s26, s12
	s_addc_u32 s13, s27, s13
	s_add_u32 s29, s12, s2
	s_addc_u32 s30, s13, 0
	s_add_i32 s2, s28, 4
	ds_read_b128 v[140:143], v151
	ds_read_b128 v[144:147], v151 offset:1024
	ds_read_b128 v[154:157], v151 offset:2048
	ds_read_b128 v[158:161], v151 offset:3072
	ds_read_b128 v[162:165], v152
	ds_read_b128 v[166:169], v152 offset:1024
	ds_read_b128 v[170:173], v152 offset:2048
	ds_read_b128 v[174:177], v152 offset:3072
	s_lshr_b32 s2, s2, 2
	s_lshl_b64 s[12:13], s[2:3], 17
	s_and_b32 s2, s52, 0x1000
	s_add_u32 s12, s26, s12
	s_addc_u32 s13, s27, s13
	s_add_u32 s2, s12, s2
	s_addc_u32 s31, s13, 0
	s_add_u32 s12, s29, 0x10800
	s_addc_u32 s13, s30, 0
	s_cmp_eq_u32 s28, 60
	s_cselect_b32 s28, s49, s50
	s_cselect_b32 s31, s17, s31
	s_cselect_b32 s30, s48, s2
	s_cselect_b32 s29, s19, s51
	s_add_i32 m0, s25, 0xc000
	ds_read_b128 v[178:181], v153
	ds_read_b128 v[182:185], v153 offset:1024
	ds_read_b128 v[186:189], v153 offset:2048
	ds_read_b128 v[190:193], v153 offset:3072
	ds_read_b128 v[194:197], v153 offset:4096
	ds_read_b128 v[198:201], v153 offset:5120
	ds_read_b128 v[202:205], v153 offset:6144
	ds_read_b128 v[206:209], v153 offset:7168
	global_load_lds_dwordx4 v134, s[12:13]
	s_add_i32 m0, s25, 0xe000
	s_nop 0
	global_load_lds_dwordx4 v130, s[12:13]
	s_waitcnt vmcnt(8)
	s_waitcnt lgkmcnt(0)
	s_barrier
; #define PG8_STAGE(bufoff, gbase, voff) do { _Pragma("unroll") for (int _i = 0; _i < 2; ++_i) \
;         __builtin_amdgcn_global_load_lds((const unsigned*)((const char*)(gbase) + (voff)[_i]), (LAS unsigned*)(lds + (bufoff) + ldsw + _i * 8192), 16, 0, 0); } while (0)
; #define PG8_LDA(dst, b, h) do { _Pragma("unroll") for (int m = 0; m < 4; ++m) _Pragma("unroll") for (int k = 0; k < 2; ++k) dst[m][k] = *(const LAS bf16x8*)(lds + PG8_SA(b, h) + aoff + m * 2048 + k * 1024); } while (0)
; #define PG8_LDB(dst, b, h) do { _Pragma("unroll") for (int n = 0; n < 2; ++n) _Pragma("unroll") for (int k = 0; k < 2; ++k) dst[n][k] = *(const LAS bf16x8*)(lds + PG8_SB(b, h) + boff + n * 2048 + k * 1024); } while (0)
; #define PG8_MMA(ai, bj, At, Bt) do { __builtin_amdgcn_s_setprio(1); _Pragma("unroll") for (int m = 0; m < 4; ++m) _Pragma("unroll") for (int n = 0; n < 2; ++n) _Pragma("unroll") for (int k = 0; k < 2; ++k) \
;         acc[ai][bj][m][n] = __builtin_amdgcn_mfma_f32_16x16x32_bf16(Bt[n][k], At[m][k], acc[ai][bj][m][n], 0, 0, 0); __builtin_amdgcn_s_setprio(0); } while (0)
; #define PG8_WAIT_V(n) asm volatile("s_waitcnt vmcnt(" #n ")" ::: "memory")
; #define PG8_WAIT_L(n) asm volatile("s_waitcnt lgkmcnt(" #n ")" ::: "memory")
; #define PG8_BAR __builtin_amdgcn_s_barrier()
; #define PG8_SCHED __builtin_amdgcn_sched_barrier(0)
; template <class Epi, bool ALIGN_EPI, bool SPLITA>
; __device__ __forceinline__ void gemm_phase(LAS unsigned char* lds, const Gemm g, const StaticOrder& S, const Epi& E) {
;     ...
;             PG8_WAIT_V(8); PG8_WAIT_L(0); PG8_BAR; PG8_MMA(0, 0, At, B0); PG8_MMA(0, 1, At, B1); PG8_BAR; PG8_SCHED;
;             PG8_LDA(At, 0, 1); PG8_STAGE(PG8_SB(0, 0), b2, voffB); PG8_STAGE(PG8_SB(0, 1), b2 + hstepB, voffB); PG8_STAGE(PG8_SA(0, 0), a2, vo2);
;             PG8_WAIT_V(8); PG8_WAIT_L(0); PG8_BAR; PG8_MMA(1, 0, At, B0); PG8_MMA(1, 1, At, B1); PG8_BAR; PG8_SCHED;
;             PG8_LDB(B0, 1, 0); PG8_LDB(B1, 1, 1); PG8_SCHED; PG8_LDA(At, 1, 0); PG8_STAGE(PG8_SA(0, 1), a2h, vo2);
;             PG8_WAIT_V(8); PG8_WAIT_L(0); PG8_BAR; PG8_MMA(0, 0, At, B0); PG8_MMA(0, 1, At, B1); PG8_BAR; PG8_SCHED;
	s_setprio 1
	s_waitcnt lgkmcnt(0)
	v_mfma_f32_16x16x32_bf16 v[124:127], v[140:143], v[178:181], v[124:127]
	v_mfma_f32_16x16x32_bf16 v[108:111], v[140:143], v[186:189], v[108:111]
	v_mfma_f32_16x16x32_bf16 v[96:99], v[140:143], v[194:197], v[96:99]
	v_mfma_f32_16x16x32_bf16 v[80:83], v[140:143], v[202:205], v[80:83]
	v_mfma_f32_16x16x32_bf16 v[120:123], v[154:157], v[178:181], v[120:123]
	v_mfma_f32_16x16x32_bf16 v[104:107], v[154:157], v[186:189], v[104:107]
	v_mfma_f32_16x16x32_bf16 v[88:91], v[154:157], v[194:197], v[88:91]
	v_mfma_f32_16x16x32_bf16 v[72:75], v[154:157], v[202:205], v[72:75]
	v_mfma_f32_16x16x32_bf16 v[124:127], v[144:147], v[182:185], v[124:127]
	v_mfma_f32_16x16x32_bf16 v[108:111], v[144:147], v[190:193], v[108:111]
	v_mfma_f32_16x16x32_bf16 v[96:99], v[144:147], v[198:201], v[96:99]
	v_mfma_f32_16x16x32_bf16 v[80:83], v[144:147], v[206:209], v[80:83]
	v_mfma_f32_16x16x32_bf16 v[120:123], v[158:161], v[182:185], v[120:123]
	v_mfma_f32_16x16x32_bf16 v[104:107], v[158:161], v[190:193], v[104:107]
	v_mfma_f32_16x16x32_bf16 v[88:91], v[158:161], v[198:201], v[88:91]
	v_mfma_f32_16x16x32_bf16 v[72:75], v[158:161], v[206:209], v[72:75]
	s_setprio 0
	s_setprio 1
	v_mfma_f32_16x16x32_bf16 v[116:119], v[162:165], v[178:181], v[116:119]
	v_mfma_f32_16x16x32_bf16 v[100:103], v[162:165], v[186:189], v[100:103]
	v_mfma_f32_16x16x32_bf16 v[84:87], v[162:165], v[194:197], v[84:87]
	v_mfma_f32_16x16x32_bf16 v[68:71], v[162:165], v[202:205], v[68:71]
	v_mfma_f32_16x16x32_bf16 v[112:115], v[170:173], v[178:181], v[112:115]
	v_mfma_f32_16x16x32_bf16 v[92:95], v[170:173], v[186:189], v[92:95]
	v_mfma_f32_16x16x32_bf16 v[76:79], v[170:173], v[194:197], v[76:79]
	v_mfma_f32_16x16x32_bf16 v[64:67], v[170:173], v[202:205], v[64:67]
	v_mfma_f32_16x16x32_bf16 v[116:119], v[166:169], v[182:185], v[116:119]
	v_mfma_f32_16x16x32_bf16 v[100:103], v[166:169], v[190:193], v[100:103]
	v_mfma_f32_16x16x32_bf16 v[84:87], v[166:169], v[198:201], v[84:87]
	v_mfma_f32_16x16x32_bf16 v[68:71], v[166:169], v[206:209], v[68:71]
	v_mfma_f32_16x16x32_bf16 v[112:115], v[174:177], v[182:185], v[112:115]
	v_mfma_f32_16x16x32_bf16 v[92:95], v[174:177], v[190:193], v[92:95]
	v_mfma_f32_16x16x32_bf16 v[76:79], v[174:177], v[198:201], v[76:79]
	v_mfma_f32_16x16x32_bf16 v[64:67], v[174:177], v[206:209], v[64:67]
	s_setprio 0
	s_barrier
	s_add_u32 s98, s28, s6
	s_addc_u32 s99, s29, s7
	s_add_u32 s100, s30, s8
	s_addc_u32 s101, s31, s9
	s_add_i32 s2, s44, s33
	s_mov_b32 m0, s2
	ds_read_b128 v[178:181], v153 offset:16384
	ds_read_b128 v[182:185], v153 offset:17408
	ds_read_b128 v[186:189], v153 offset:18432
	ds_read_b128 v[190:193], v153 offset:19456
	ds_read_b128 v[194:197], v153 offset:20480
	ds_read_b128 v[198:201], v153 offset:21504
	ds_read_b128 v[202:205], v153 offset:22528
	ds_read_b128 v[206:209], v153 offset:23552
	global_load_lds_dwordx4 v132, s[28:29]
	s_add_i32 m0, s2, 0x2000
	s_add_u32 s12, s28, 0x100000
	s_addc_u32 s13, s29, 0
	s_add_i32 s2, s45, s33
	global_load_lds_dwordx4 v128, s[28:29]
	s_mov_b32 m0, s2
	s_nop 0
	global_load_lds_dwordx4 v132, s[12:13]
	s_add_i32 m0, s2, 0x2000
	s_nop 0
	global_load_lds_dwordx4 v128, s[12:13]
	s_mov_b32 m0, s25
	s_nop 0
	global_load_lds_dwordx4 v134, s[30:31]
	s_mov_b32 m0, s38
	s_nop 0
	global_load_lds_dwordx4 v130, s[30:31]
	s_waitcnt vmcnt(8)
	s_waitcnt lgkmcnt(0)
	s_barrier
	s_setprio 1
	s_waitcnt lgkmcnt(0)
	v_mfma_f32_16x16x32_bf16 v[60:63], v[140:143], v[178:181], v[60:63]
	v_mfma_f32_16x16x32_bf16 v[40:43], v[140:143], v[186:189], v[40:43]
	v_mfma_f32_16x16x32_bf16 v[20:23], v[140:143], v[194:197], v[20:23]
	v_mfma_f32_16x16x32_bf16 v[4:7], v[140:143], v[202:205], v[4:7]
	v_mfma_f32_16x16x32_bf16 v[56:59], v[154:157], v[178:181], v[56:59]
	v_mfma_f32_16x16x32_bf16 v[32:35], v[154:157], v[186:189], v[32:35]
	v_mfma_f32_16x16x32_bf16 v[8:11], v[154:157], v[194:197], v[8:11]
	v_mfma_f32_16x16x32_bf16 v[0:3], v[154:157], v[202:205], v[0:3]
	v_mfma_f32_16x16x32_bf16 v[60:63], v[144:147], v[182:185], v[60:63]
	v_mfma_f32_16x16x32_bf16 v[40:43], v[144:147], v[190:193], v[40:43]
	v_mfma_f32_16x16x32_bf16 v[20:23], v[144:147], v[198:201], v[20:23]
	v_mfma_f32_16x16x32_bf16 v[4:7], v[144:147], v[206:209], v[4:7]
	v_mfma_f32_16x16x32_bf16 v[56:59], v[158:161], v[182:185], v[56:59]
	v_mfma_f32_16x16x32_bf16 v[32:35], v[158:161], v[190:193], v[32:35]
	v_mfma_f32_16x16x32_bf16 v[8:11], v[158:161], v[198:201], v[8:11]
	v_mfma_f32_16x16x32_bf16 v[0:3], v[158:161], v[206:209], v[0:3]
	s_setprio 0
	s_setprio 1
	v_mfma_f32_16x16x32_bf16 v[44:47], v[162:165], v[178:181], v[44:47]
	v_mfma_f32_16x16x32_bf16 v[52:55], v[162:165], v[186:189], v[52:55]
	v_mfma_f32_16x16x32_bf16 v[28:31], v[162:165], v[194:197], v[28:31]
	v_mfma_f32_16x16x32_bf16 v[16:19], v[162:165], v[202:205], v[16:19]
	v_mfma_f32_16x16x32_bf16 v[36:39], v[170:173], v[178:181], v[36:39]
	v_mfma_f32_16x16x32_bf16 v[48:51], v[170:173], v[186:189], v[48:51]
	v_mfma_f32_16x16x32_bf16 v[24:27], v[170:173], v[194:197], v[24:27]
	v_mfma_f32_16x16x32_bf16 v[12:15], v[170:173], v[202:205], v[12:15]
	v_mfma_f32_16x16x32_bf16 v[44:47], v[166:169], v[182:185], v[44:47]
	v_mfma_f32_16x16x32_bf16 v[52:55], v[166:169], v[190:193], v[52:55]
	v_mfma_f32_16x16x32_bf16 v[28:31], v[166:169], v[198:201], v[28:31]
	v_mfma_f32_16x16x32_bf16 v[16:19], v[166:169], v[206:209], v[16:19]
	v_mfma_f32_16x16x32_bf16 v[36:39], v[174:177], v[182:185], v[36:39]
	v_mfma_f32_16x16x32_bf16 v[48:51], v[174:177], v[190:193], v[48:51]
	v_mfma_f32_16x16x32_bf16 v[24:27], v[174:177], v[198:201], v[24:27]
	v_mfma_f32_16x16x32_bf16 v[12:15], v[174:177], v[206:209], v[12:15]
	s_setprio 0
	s_barrier
; #define PG8_STAGE(bufoff, gbase, voff) do { _Pragma("unroll") for (int _i = 0; _i < 2; ++_i) \
;         __builtin_amdgcn_global_load_lds((const unsigned*)((const char*)(gbase) + (voff)[_i]), (LAS unsigned*)(lds + (bufoff) + ldsw + _i * 8192), 16, 0, 0); } while (0)
; #define PG8_LDA(dst, b, h) do { _Pragma("unroll") for (int m = 0; m < 4; ++m) _Pragma("unroll") for (int k = 0; k < 2; ++k) dst[m][k] = *(const LAS bf16x8*)(lds + PG8_SA(b, h) + aoff + m * 2048 + k * 1024); } while (0)
; #define PG8_LDB(dst, b, h) do { _Pragma("unroll") for (int n = 0; n < 2; ++n) _Pragma("unroll") for (int k = 0; k < 2; ++k) dst[n][k] = *(const LAS bf16x8*)(lds + PG8_SB(b, h) + boff + n * 2048 + k * 1024); } while (0)
; #define PG8_MMA(ai, bj, At, Bt) do { __builtin_amdgcn_s_setprio(1); _Pragma("unroll") for (int m = 0; m < 4; ++m) _Pragma("unroll") for (int n = 0; n < 2; ++n) _Pragma("unroll") for (int k = 0; k < 2; ++k) \
;         acc[ai][bj][m][n] = __builtin_amdgcn_mfma_f32_16x16x32_bf16(Bt[n][k], At[m][k], acc[ai][bj][m][n], 0, 0, 0); __builtin_amdgcn_s_setprio(0); } while (0)
; #define PG8_WAIT_V(n) asm volatile("s_waitcnt vmcnt(" #n ")" ::: "memory")
; #define PG8_WAIT_L(n) asm volatile("s_waitcnt lgkmcnt(" #n ")" ::: "memory")
; #define PG8_BAR __builtin_amdgcn_s_barrier()
; #define PG8_SCHED __builtin_amdgcn_sched_barrier(0)
; template <class Epi, bool ALIGN_EPI, bool SPLITA>
; __device__ __forceinline__ void gemm_phase(LAS unsigned char* lds, const Gemm g, const StaticOrder& S, const Epi& E) {
;     ...
;         for (int t = 0; t < nt; t += 2) {
;     ...
;             PG8_LDB(B0, 1, 0); PG8_LDB(B1, 1, 1); PG8_SCHED; PG8_LDA(At, 1, 0); PG8_STAGE(PG8_SA(0, 1), a2h, vo2);
;             PG8_WAIT_V(8); PG8_WAIT_L(0); PG8_BAR; PG8_MMA(0, 0, At, B0); PG8_MMA(0, 1, At, B1); PG8_BAR; PG8_SCHED;
;             PG8_LDA(At, 1, 1); PG8_STAGE(PG8_SB(1, 0), b3, voffB); PG8_STAGE(PG8_SB(1, 1), b3 + hstepB, voffB); PG8_STAGE(PG8_SA(1, 0), a3, vo2);
;             PG8_WAIT_V(8); PG8_WAIT_L(0); PG8_BAR; PG8_MMA(1, 0, At, B0); PG8_MMA(1, 1, At, B1); PG8_BAR; PG8_SCHED;
	s_add_i32 s2, 0, 0x18000
	s_add_i32 s54, 0, 0x1c000
	v_add_u32_e32 v158, s2, v149
	v_add_u32_e32 v174, s54, v149
	ds_read_b128 v[140:143], v158
	ds_read_b128 v[144:147], v158 offset:1024
	ds_read_b128 v[154:157], v158 offset:2048
	ds_read_b128 v[158:161], v158 offset:3072
	ds_read_b128 v[162:165], v174
	ds_read_b128 v[166:169], v174 offset:1024
	ds_read_b128 v[170:173], v174 offset:2048
	ds_read_b128 v[174:177], v174 offset:3072
	s_add_u32 s12, s30, 0x10000
	s_addc_u32 s13, s31, 0
	s_mov_b32 m0, s39
	ds_read_b128 v[178:181], v153 offset:32768
	ds_read_b128 v[182:185], v153 offset:33792
	ds_read_b128 v[186:189], v153 offset:34816
	ds_read_b128 v[190:193], v153 offset:35840
	ds_read_b128 v[194:197], v153 offset:36864
	ds_read_b128 v[198:201], v153 offset:37888
	ds_read_b128 v[202:205], v153 offset:38912
	ds_read_b128 v[206:209], v153 offset:39936
	global_load_lds_dwordx4 v134, s[12:13]
	s_mov_b32 m0, s40
	s_nop 0
	global_load_lds_dwordx4 v130, s[12:13]
	s_waitcnt vmcnt(8)
	s_waitcnt lgkmcnt(0)
	s_barrier
	s_setprio 1
	s_waitcnt lgkmcnt(0)
	v_mfma_f32_16x16x32_bf16 v[124:127], v[140:143], v[178:181], v[124:127]
	v_mfma_f32_16x16x32_bf16 v[108:111], v[140:143], v[186:189], v[108:111]
	v_mfma_f32_16x16x32_bf16 v[96:99], v[140:143], v[194:197], v[96:99]
	v_mfma_f32_16x16x32_bf16 v[80:83], v[140:143], v[202:205], v[80:83]
	v_mfma_f32_16x16x32_bf16 v[120:123], v[154:157], v[178:181], v[120:123]
	v_mfma_f32_16x16x32_bf16 v[104:107], v[154:157], v[186:189], v[104:107]
	v_mfma_f32_16x16x32_bf16 v[88:91], v[154:157], v[194:197], v[88:91]
	v_mfma_f32_16x16x32_bf16 v[72:75], v[154:157], v[202:205], v[72:75]
	v_mfma_f32_16x16x32_bf16 v[124:127], v[144:147], v[182:185], v[124:127]
	v_mfma_f32_16x16x32_bf16 v[108:111], v[144:147], v[190:193], v[108:111]
	v_mfma_f32_16x16x32_bf16 v[96:99], v[144:147], v[198:201], v[96:99]
	v_mfma_f32_16x16x32_bf16 v[80:83], v[144:147], v[206:209], v[80:83]
	v_mfma_f32_16x16x32_bf16 v[120:123], v[158:161], v[182:185], v[120:123]
	v_mfma_f32_16x16x32_bf16 v[104:107], v[158:161], v[190:193], v[104:107]
	v_mfma_f32_16x16x32_bf16 v[88:91], v[158:161], v[198:201], v[88:91]
	v_mfma_f32_16x16x32_bf16 v[72:75], v[158:161], v[206:209], v[72:75]
	s_setprio 0
	s_setprio 1
	v_mfma_f32_16x16x32_bf16 v[116:119], v[162:165], v[178:181], v[116:119]
	v_mfma_f32_16x16x32_bf16 v[100:103], v[162:165], v[186:189], v[100:103]
	v_mfma_f32_16x16x32_bf16 v[84:87], v[162:165], v[194:197], v[84:87]
	v_mfma_f32_16x16x32_bf16 v[68:71], v[162:165], v[202:205], v[68:71]
	v_mfma_f32_16x16x32_bf16 v[112:115], v[170:173], v[178:181], v[112:115]
	v_mfma_f32_16x16x32_bf16 v[92:95], v[170:173], v[186:189], v[92:95]
	v_mfma_f32_16x16x32_bf16 v[76:79], v[170:173], v[194:197], v[76:79]
	v_mfma_f32_16x16x32_bf16 v[64:67], v[170:173], v[202:205], v[64:67]
	v_mfma_f32_16x16x32_bf16 v[116:119], v[166:169], v[182:185], v[116:119]
	v_mfma_f32_16x16x32_bf16 v[100:103], v[166:169], v[190:193], v[100:103]
	v_mfma_f32_16x16x32_bf16 v[84:87], v[166:169], v[198:201], v[84:87]
	v_mfma_f32_16x16x32_bf16 v[68:71], v[166:169], v[206:209], v[68:71]
	v_mfma_f32_16x16x32_bf16 v[112:115], v[174:177], v[182:185], v[112:115]
	v_mfma_f32_16x16x32_bf16 v[92:95], v[174:177], v[190:193], v[92:95]
	v_mfma_f32_16x16x32_bf16 v[76:79], v[174:177], v[198:201], v[76:79]
	v_mfma_f32_16x16x32_bf16 v[64:67], v[174:177], v[206:209], v[64:67]
	s_setprio 0
	s_barrier
	s_add_i32 s2, s2, s33
	s_mov_b32 m0, s2
	ds_read_b128 v[178:181], v153 offset:49152
	ds_read_b128 v[182:185], v153 offset:50176
	ds_read_b128 v[186:189], v153 offset:51200
	ds_read_b128 v[190:193], v153 offset:52224
	ds_read_b128 v[194:197], v153 offset:53248
	ds_read_b128 v[198:201], v153 offset:54272
	ds_read_b128 v[202:205], v153 offset:55296
	ds_read_b128 v[206:209], v153 offset:56320
	global_load_lds_dwordx4 v132, s[98:99]
	s_add_i32 m0, s2, 0x2000
	s_add_u32 s12, s28, 0x100080
	s_addc_u32 s13, s29, 0
	s_add_i32 s2, s54, s33
	global_load_lds_dwordx4 v128, s[98:99]
	s_mov_b32 m0, s2
	s_nop 0
	global_load_lds_dwordx4 v132, s[12:13]
	s_add_i32 m0, s2, 0x2000
	s_nop 0
	global_load_lds_dwordx4 v128, s[12:13]
	s_mov_b32 m0, s41
	s_nop 0
	global_load_lds_dwordx4 v134, s[100:101]
	s_mov_b32 m0, s42
	s_nop 0
	global_load_lds_dwordx4 v130, s[100:101]
	s_waitcnt vmcnt(8)
	s_waitcnt lgkmcnt(0)
	s_barrier
	s_setprio 1
	s_waitcnt lgkmcnt(0)
	v_mfma_f32_16x16x32_bf16 v[60:63], v[140:143], v[178:181], v[60:63]
	v_mfma_f32_16x16x32_bf16 v[40:43], v[140:143], v[186:189], v[40:43]
	v_mfma_f32_16x16x32_bf16 v[20:23], v[140:143], v[194:197], v[20:23]
	v_mfma_f32_16x16x32_bf16 v[4:7], v[140:143], v[202:205], v[4:7]
	v_mfma_f32_16x16x32_bf16 v[56:59], v[154:157], v[178:181], v[56:59]
	v_mfma_f32_16x16x32_bf16 v[32:35], v[154:157], v[186:189], v[32:35]
	v_mfma_f32_16x16x32_bf16 v[8:11], v[154:157], v[194:197], v[8:11]
	v_mfma_f32_16x16x32_bf16 v[0:3], v[154:157], v[202:205], v[0:3]
	v_mfma_f32_16x16x32_bf16 v[60:63], v[144:147], v[182:185], v[60:63]
	v_mfma_f32_16x16x32_bf16 v[40:43], v[144:147], v[190:193], v[40:43]
	v_mfma_f32_16x16x32_bf16 v[20:23], v[144:147], v[198:201], v[20:23]
	v_mfma_f32_16x16x32_bf16 v[4:7], v[144:147], v[206:209], v[4:7]
	v_mfma_f32_16x16x32_bf16 v[56:59], v[158:161], v[182:185], v[56:59]
	v_mfma_f32_16x16x32_bf16 v[32:35], v[158:161], v[190:193], v[32:35]
	v_mfma_f32_16x16x32_bf16 v[8:11], v[158:161], v[198:201], v[8:11]
	v_mfma_f32_16x16x32_bf16 v[0:3], v[158:161], v[206:209], v[0:3]
	s_setprio 0
	s_setprio 1
	v_mfma_f32_16x16x32_bf16 v[44:47], v[162:165], v[178:181], v[44:47]
	v_mfma_f32_16x16x32_bf16 v[52:55], v[162:165], v[186:189], v[52:55]
	v_mfma_f32_16x16x32_bf16 v[28:31], v[162:165], v[194:197], v[28:31]
	v_mfma_f32_16x16x32_bf16 v[16:19], v[162:165], v[202:205], v[16:19]
	v_mfma_f32_16x16x32_bf16 v[36:39], v[170:173], v[178:181], v[36:39]
	v_mfma_f32_16x16x32_bf16 v[48:51], v[170:173], v[186:189], v[48:51]
	v_mfma_f32_16x16x32_bf16 v[24:27], v[170:173], v[194:197], v[24:27]
	v_mfma_f32_16x16x32_bf16 v[12:15], v[170:173], v[202:205], v[12:15]
	v_mfma_f32_16x16x32_bf16 v[44:47], v[166:169], v[182:185], v[44:47]
	v_mfma_f32_16x16x32_bf16 v[52:55], v[166:169], v[190:193], v[52:55]
	v_mfma_f32_16x16x32_bf16 v[28:31], v[166:169], v[198:201], v[28:31]
	v_mfma_f32_16x16x32_bf16 v[16:19], v[166:169], v[206:209], v[16:19]
	v_mfma_f32_16x16x32_bf16 v[36:39], v[174:177], v[182:185], v[36:39]
	v_mfma_f32_16x16x32_bf16 v[48:51], v[174:177], v[190:193], v[48:51]
	v_mfma_f32_16x16x32_bf16 v[24:27], v[174:177], v[198:201], v[24:27]
	v_mfma_f32_16x16x32_bf16 v[12:15], v[174:177], v[206:209], v[12:15]
	s_setprio 0
	s_barrier
	s_add_u32 s50, s50, 0x100
	s_addc_u32 s51, s51, 0
	s_addk_i32 s52, 0x1000
	s_cmp_gt_u32 s53, 61
	s_mov_b32 s28, s53
	s_cbranch_scc0 .LBB0_867
	s_and_b64 vcc, exec, s[10:11]
	s_cbranch_vccz .LBB0_870
	s_barrier
